# PEER rewrite + expert tables in line-aligned A/B blocks per XCD slice + L1-bypass (sc1) row loads
# speedup vs baseline: 1.0969x; 1.0044x over previous
.LBB0_100:
	s_or_b64 exec, exec, s[8:9]
	s_movk_i32 s0, 0x4000
	v_cmp_gt_i32_e64 s[8:9], s0, v174
	v_mul_u32_u24_e32 v130, 24, v236
	s_mul_hi_i32 s13, s80, 0x600
	s_mul_i32 s12, s80, 0x600
	s_and_saveexec_b64 s[14:15], s[8:9]
	s_cbranch_execz .LBB0_361
	v_mbcnt_hi_u32_b32 v0, -1, v152
	v_and_b32_e32 v2, 64, v0
	v_xor_b32_e32 v1, 32, v0
	v_add_u32_e32 v2, 64, v2
	v_cmp_lt_i32_e32 vcc, v1, v2
	s_load_dwordx2 s[0:1], s[76:77], 0x50
	s_load_dwordx2 s[6:7], s[76:77], 0x98
	s_load_dwordx2 s[16:17], s[76:77], 0xa8
	v_cndmask_b32_e32 v1, v0, v1, vcc
	v_lshlrev_b32_e32 v39, 2, v1
	v_xor_b32_e32 v1, 16, v0
	v_cmp_lt_i32_e32 vcc, v1, v2
	v_mov_b32_e32 v131, 0
	s_ashr_i32 s81, s80, 31
	v_cndmask_b32_e32 v1, v0, v1, vcc
	v_lshlrev_b32_e32 v40, 2, v1
	v_xor_b32_e32 v1, 8, v0
	v_cmp_lt_i32_e32 vcc, v1, v2
	v_cmp_eq_u32_e64 s[10:11], 0, v236
	s_waitcnt lgkmcnt(0)
	v_lshl_add_u64 v[32:33], v[174:175], 2, s[16:17]
	v_cndmask_b32_e32 v1, v0, v1, vcc
	v_lshlrev_b32_e32 v41, 2, v1
	v_xor_b32_e32 v1, 4, v0
	v_cmp_lt_i32_e32 vcc, v1, v2
	s_lshl_b64 s[16:17], s[80:81], 2
	s_lshl_b64 s[18:19], s[80:81], 13
	v_cndmask_b32_e32 v1, v0, v1, vcc
	v_lshlrev_b32_e32 v42, 2, v1
	v_xor_b32_e32 v1, 2, v0
	v_cmp_lt_i32_e32 vcc, v1, v2
	s_mov_b64 s[20:21], 0
	s_mov_b32 s3, 0x40f00000
	v_cndmask_b32_e32 v1, v0, v1, vcc
	v_lshlrev_b32_e32 v43, 2, v1
	v_xor_b32_e32 v1, 1, v0
	v_cmp_lt_i32_e32 vcc, v1, v2
	v_mov_b32_e32 v45, v174
	s_nop 0
	v_cndmask_b32_e32 v0, v0, v1, vcc
	v_lshlrev_b32_e32 v44, 2, v0
	v_lshlrev_b64 v[0:1], 13, v[174:175]
	v_lshl_or_b32 v0, v236, 4, v0
	v_lshl_add_u64 v[0:1], s[0:1], 0, v[0:1]
	s_mov_b64 s[0:1], 0x1000
	v_lshl_add_u64 v[34:35], v[0:1], 0, s[0:1]
	s_movk_i32 s0, 0x80
	v_lshrrev_b32_e32 v46, 3, v236
	v_and_b32_e32 v47, 7, v236
	v_mul_u32_u24_e32 v46, 0x300000, v46
	v_lshl_add_u32 v46, v47, 4, v46
	v_lshlrev_b32_e32 v48, 3, v47
	v_lshl_add_u32 v48, v174, 6, v48
	v_sub_u32_e32 v130, 0x200000, v48
	v_mov_b32_e32 v47, 0
	s_lshl_b32 s98, s80, 7
	s_mov_b32 s99, 0
	s_lshl_b32 s100, s80, 6
	v_mad_i64_i32 v[0:1], s[0:1], v174, s0, v[46:47]
	v_lshl_add_u64 v[0:1], s[6:7], 0, v[0:1]
	v_lshl_add_u64 v[36:37], v[0:1], 0, 8
	s_mov_b32 s6, 0x41000000
	s_movk_i32 s7, 0x3fff
	s_branch .LBB0_103
.LBB0_102:
	s_or_b64 exec, exec, s[22:23]
	v_add_u32_e32 v45, s80, v45
	v_cmp_lt_i32_e32 vcc, s7, v45
	v_lshl_add_u64 v[32:33], v[32:33], 0, s[16:17]
	v_lshl_add_u64 v[34:35], v[34:35], 0, s[18:19]
	s_or_b64 s[20:21], vcc, s[20:21]
	v_lshl_add_u64 v[36:37], v[36:37], 0, s[98:99]
	v_subrev_u32_e32 v130, s100, v130
	s_andn2_b64 exec, exec, s[20:21]
	s_cbranch_execz .LBB0_361

.LBB0_357:
	s_andn2_saveexec_b64 s[22:23], s[22:23]
	v_mul_f32_e64 v1, |v0|, s6
	v_rndne_f32_e32 v1, v1
	s_or_b64 exec, exec, s[22:23]
	v_max_f32_e32 v3, v80, v80
	v_min_f32_e32 v3, 0x41f80000, v3
	v_max_f32_e32 v51, v79, v79
	v_cvt_u32_f32_e32 v3, v3
	v_min_f32_e32 v51, 0x41f80000, v51
	v_cvt_u32_f32_e32 v51, v51
	v_cmp_gt_f32_e32 vcc, 0, v2
	v_max_f32_e32 v75, v75, v75
	v_min_f32_e32 v75, 0x41f80000, v75
	v_cndmask_b32_e64 v2, 0, 32, vcc
	v_cmp_gt_f32_e32 vcc, 0, v78
	v_or_b32_e32 v79, v2, v3
	v_cvt_u32_f32_e32 v75, v75
	v_cndmask_b32_e64 v2, 0, 32, vcc
	v_or_b32_e32 v51, v2, v51
	v_max_f32_e32 v2, v77, v77
	v_min_f32_e32 v2, 0x41f80000, v2
	v_cvt_u32_f32_e32 v2, v2
	v_cmp_gt_f32_e32 vcc, 0, v76
	v_max_f32_e32 v48, v48, v48
	v_max_f32_e32 v50, v50, v50
	v_cndmask_b32_e64 v3, 0, 32, vcc
	v_cmp_gt_f32_e32 vcc, 0, v7
	v_or_b32_e32 v76, v3, v2
	v_max_f32_e32 v3, v73, v73
	v_cndmask_b32_e64 v2, 0, 32, vcc
	v_or_b32_e32 v7, v2, v75
	v_max_f32_e32 v2, v74, v74
	v_min_f32_e32 v2, 0x41f80000, v2
	v_cvt_u32_f32_e32 v74, v2
	v_min_f32_e32 v3, 0x41f80000, v3
	v_cvt_u32_f32_e32 v3, v3
	v_cmp_gt_f32_e32 vcc, 0, v6
	v_max_f32_e32 v49, v49, v49
	v_min_f32_e32 v48, 0x41f80000, v48
	v_cndmask_b32_e64 v2, 0, 32, vcc
	v_cmp_gt_f32_e32 vcc, 0, v5
	v_or_b32_e32 v6, v2, v74
	v_max_f32_e32 v1, v1, v1
	v_cndmask_b32_e64 v2, 0, 32, vcc
	v_or_b32_e32 v5, v2, v3
	v_max_f32_e32 v2, v72, v72
	v_min_f32_e32 v2, 0x41f80000, v2
	v_cmp_gt_f32_e32 vcc, 0, v4
	v_max_f32_e32 v4, v71, v71
	v_cvt_u32_f32_e32 v2, v2
	v_min_f32_e32 v4, 0x41f80000, v4
	v_cvt_u32_f32_e32 v4, v4
	v_cndmask_b32_e64 v3, 0, 32, vcc
	v_cmp_gt_f32_e32 vcc, 0, v11
	v_or_b32_sdwa v71, v3, v2 dst_sel:WORD_1 dst_unused:UNUSED_PAD src0_sel:DWORD src1_sel:DWORD
	v_min_f32_e32 v50, 0x41f80000, v50
	v_cndmask_b32_e64 v2, 0, 32, vcc
	v_or_b32_e32 v4, v2, v4
	v_max_f32_e32 v2, v70, v70
	v_min_f32_e32 v2, 0x41f80000, v2
	v_cmp_gt_f32_e32 vcc, 0, v10
	v_max_f32_e32 v10, v69, v69
	v_cvt_u32_f32_e32 v2, v2
	v_min_f32_e32 v10, 0x41f80000, v10
	v_cvt_u32_f32_e32 v10, v10
	v_cndmask_b32_e64 v3, 0, 32, vcc
	v_cmp_gt_f32_e32 vcc, 0, v9
	v_or_b32_e32 v11, v3, v2
	v_min_f32_e32 v49, 0x41f80000, v49
	v_cndmask_b32_e64 v2, 0, 32, vcc
	v_or_b32_e32 v9, v2, v10
	v_max_f32_e32 v2, v68, v68
	v_min_f32_e32 v2, 0x41f80000, v2
	v_cmp_gt_f32_e32 vcc, 0, v8
	v_max_f32_e32 v8, v67, v67
	v_cvt_u32_f32_e32 v2, v2
	v_min_f32_e32 v8, 0x41f80000, v8
	v_cvt_u32_f32_e32 v8, v8
	v_cndmask_b32_e64 v3, 0, 32, vcc
	v_cmp_gt_f32_e32 vcc, 0, v15
	v_or_b32_sdwa v3, v3, v2 dst_sel:BYTE_3 dst_unused:UNUSED_PAD src0_sel:DWORD src1_sel:DWORD
	v_max_f32_e32 v15, v65, v65
	v_cndmask_b32_e64 v2, 0, 32, vcc
	v_or_b32_e32 v8, v2, v8
	v_max_f32_e32 v2, v66, v66
	v_min_f32_e32 v2, 0x41f80000, v2
	v_cvt_u32_f32_e32 v2, v2
	v_min_f32_e32 v15, 0x41f80000, v15
	v_cvt_u32_f32_e32 v15, v15
	v_cmp_gt_f32_e32 vcc, 0, v14
	v_cvt_u32_f32_e32 v48, v48
	v_max_f32_e32 v47, v47, v47
	v_cndmask_b32_e64 v14, 0, 32, vcc
	v_cmp_gt_f32_e32 vcc, 0, v13
	v_or_b32_e32 v14, v14, v2
	v_min_f32_e32 v1, 0x41f80000, v1
	v_cndmask_b32_e64 v2, 0, 32, vcc
	v_or_b32_e32 v13, v2, v15
	v_max_f32_e32 v2, v64, v64
	v_min_f32_e32 v2, 0x41f80000, v2
	v_cvt_u32_f32_e32 v15, v2
	v_max_f32_e32 v2, v63, v63
	v_min_f32_e32 v2, 0x41f80000, v2
	v_cvt_u32_f32_e32 v2, v2
	v_cmp_gt_f32_e32 vcc, 0, v12
	v_max_f32_e32 v53, v53, v53
	v_max_f32_e32 v52, v52, v52
	v_cndmask_b32_e64 v12, 0, 32, vcc
	v_cmp_gt_f32_e32 vcc, 0, v19
	v_cvt_u32_f32_e32 v50, v50
	v_cvt_u32_f32_e32 v49, v49
	v_cndmask_b32_e64 v19, 0, 32, vcc
	v_or_b32_e32 v2, v19, v2
	v_max_f32_e32 v19, v62, v62
	v_min_f32_e32 v19, 0x41f80000, v19
	v_cvt_u32_f32_e32 v19, v19
	v_cmp_gt_f32_e32 vcc, 0, v18
	v_min_f32_e32 v47, 0x41f80000, v47
	v_cvt_u32_f32_e32 v1, v1
	v_cndmask_b32_e64 v18, 0, 32, vcc
	v_or_b32_e32 v18, v18, v19
	v_max_f32_e32 v19, v60, v60
	v_min_f32_e32 v19, 0x41f80000, v19
	v_cvt_u32_f32_e32 v19, v19
	v_cmp_gt_f32_e32 vcc, 0, v17
	v_max_f32_e32 v55, v55, v55
	v_max_f32_e32 v54, v54, v54
	v_cndmask_b32_e64 v17, 0, 32, vcc
	v_cmp_gt_f32_e32 vcc, 0, v16
	v_min_f32_e32 v53, 0x41f80000, v53
	v_min_f32_e32 v52, 0x41f80000, v52
	v_cndmask_b32_e64 v16, 0, 32, vcc
	v_cmp_gt_f32_e32 vcc, 0, v23
	v_or_b32_e32 v16, v16, v19
	v_cvt_u32_f32_e32 v47, v47
	v_cndmask_b32_e64 v19, 0, 32, vcc
	v_cmp_gt_f32_e32 vcc, 0, v22
	v_max_f32_e32 v57, v57, v57
	v_max_f32_e32 v56, v56, v56
	v_cndmask_b32_e64 v22, 0, 32, vcc
	v_cmp_gt_f32_e32 vcc, 0, v21
	v_min_f32_e32 v55, 0x41f80000, v55
	v_min_f32_e32 v54, 0x41f80000, v54
	v_cndmask_b32_e64 v21, 0, 32, vcc
	v_cmp_gt_f32_e32 vcc, 0, v20
	v_cvt_u32_f32_e32 v53, v53
	v_cvt_u32_f32_e32 v52, v52
	v_cndmask_b32_e64 v20, 0, 32, vcc
	v_cmp_gt_f32_e32 vcc, 0, v27
	v_max_f32_e32 v23, v58, v58
	v_min_f32_e32 v57, 0x41f80000, v57
	v_cndmask_b32_e64 v27, 0, 32, vcc
	v_cmp_gt_f32_e32 vcc, 0, v26
	v_min_f32_e32 v56, 0x41f80000, v56
	v_cvt_u32_f32_e32 v55, v55
	v_cndmask_b32_e64 v26, 0, 32, vcc
	v_cmp_gt_f32_e32 vcc, 0, v25
	v_cvt_u32_f32_e32 v54, v54
	v_max_f32_e32 v61, v61, v61
	v_cndmask_b32_e64 v25, 0, 32, vcc
	v_cmp_gt_f32_e32 vcc, 0, v24
	v_max_f32_e32 v59, v59, v59
	v_min_f32_e32 v23, 0x41f80000, v23
	v_cndmask_b32_e64 v24, 0, 32, vcc
	v_cmp_gt_f32_e32 vcc, 0, v31
	v_cvt_u32_f32_e32 v57, v57
	v_cvt_u32_f32_e32 v56, v56
	v_cndmask_b32_e64 v31, 0, 32, vcc
	v_cmp_gt_f32_e32 vcc, 0, v30
	v_or_b32_e32 v31, v31, v50
	v_min_f32_e32 v61, 0x41f80000, v61
	v_cndmask_b32_e64 v30, 0, 32, vcc
	v_cmp_gt_f32_e32 vcc, 0, v29
	v_or_b32_e32 v30, v30, v49
	v_min_f32_e32 v59, 0x41f80000, v59
	v_cndmask_b32_e64 v29, 0, 32, vcc
	v_cmp_gt_f32_e32 vcc, 0, v28
	v_or_b32_e32 v29, v29, v48
	v_cvt_u32_f32_e32 v23, v23
	v_cndmask_b32_e64 v28, 0, 32, vcc
	v_cmp_gt_f32_e32 vcc, 0, v0
	v_lshlrev_b32_e32 v13, 6, v13
	v_cvt_u32_f32_e32 v61, v61
	v_cndmask_b32_e64 v0, 0, 32, vcc
	v_or_b32_e32 v48, v0, v1
	v_lshlrev_b32_e32 v0, 6, v29
	v_or3_b32 v0, v28, v47, v0
	v_lshlrev_b32_e32 v1, 12, v30
	v_lshlrev_b32_e32 v28, 18, v31
	v_cvt_u32_f32_e32 v59, v59
	v_or_b32_e32 v25, v25, v53
	v_or_b32_sdwa v24, v24, v52 dst_sel:BYTE_3 dst_unused:UNUSED_PAD src0_sel:DWORD src1_sel:DWORD
	v_or3_b32 v0, v0, v1, v28
	v_lshlrev_b32_e32 v1, 30, v53
	v_or3_b32 v12, v12, v15, v13
	v_lshlrev_b32_e32 v13, 12, v14
	v_lshlrev_b32_e32 v8, 18, v8
	v_or_b32_e32 v27, v27, v55
	v_or_b32_e32 v26, v26, v54
	v_or3_b32 v0, v0, v24, v1
	v_lshrrev_b32_e32 v1, 2, v25
	v_or3_b32 v8, v12, v13, v8
	v_lshlrev_b32_e32 v10, 30, v10
	v_or_b32_e32 v21, v21, v57
	v_or_b32_sdwa v20, v20, v56 dst_sel:WORD_1 dst_unused:UNUSED_PAD src0_sel:DWORD src1_sel:DWORD
	v_lshl_or_b32 v1, v26, 4, v1
	v_lshlrev_b32_e32 v24, 10, v27
	v_or3_b32 v3, v8, v3, v10
	v_lshrrev_b32_e32 v8, 2, v9
	v_or_b32_e32 v22, v22, v23
	v_or3_b32 v1, v1, v24, v20
	v_lshlrev_b32_e32 v20, 22, v21
	v_lshlrev_b32_e32 v21, 28, v23
	v_lshl_or_b32 v8, v11, 4, v8
	v_lshlrev_b32_e32 v4, 10, v4
	v_or_b32_e32 v17, v17, v61
	v_or_b32_e32 v19, v19, v59
	v_or3_b32 v1, v1, v20, v21
	v_lshrrev_b32_e32 v20, 4, v22
	v_or3_b32 v4, v8, v4, v71
	v_lshlrev_b32_e32 v5, 22, v5
	v_lshlrev_b32_e32 v8, 28, v74
	v_lshl_or_b32 v19, v19, 2, v20
	v_lshlrev_b32_e32 v16, 8, v16
	v_lshlrev_b32_e32 v17, 14, v17
	v_or3_b32 v4, v4, v5, v8
	v_lshrrev_b32_e32 v5, 4, v6
	v_or3_b32 v16, v19, v16, v17
	v_lshlrev_b32_e32 v17, 20, v18
	v_lshlrev_b32_e32 v2, 26, v2
	v_lshl_or_b32 v5, v7, 2, v5
	v_lshlrev_b32_e32 v6, 8, v76
	v_lshlrev_b32_e32 v7, 14, v51
	v_or3_b32 v2, v16, v17, v2
	v_or3_b32 v5, v5, v6, v7
	v_lshlrev_b32_e32 v6, 20, v79
	v_lshlrev_b32_e32 v7, 26, v48
	v_or3_b32 v5, v5, v6, v7
	global_store_dwordx4 v[36:37], v[0:3], off offset:-8
	v_lshl_add_u64 v[6:7], v[36:37], 0, v[130:131]
	global_store_dwordx2 v[6:7], v[4:5], off offset:-8
	s_and_saveexec_b64 s[22:23], s[10:11]
	s_cbranch_execz .LBB0_102
	v_mul_f32_e32 v0, 0x3e088889, v46
	global_store_dword v[32:33], v0, off
	s_branch .LBB0_102
.LBB0_361:
	s_or_b64 exec, exec, s[14:15]
	s_and_saveexec_b64 s[10:11], s[8:9]
	s_cbranch_execz .LBB0_622
	v_mbcnt_hi_u32_b32 v0, -1, v152
	v_and_b32_e32 v2, 64, v0
	v_xor_b32_e32 v1, 32, v0
	v_add_u32_e32 v2, 64, v2
	v_cmp_lt_i32_e32 vcc, v1, v2
	s_load_dwordx2 s[0:1], s[76:77], 0x58
	s_load_dwordx2 s[6:7], s[76:77], 0xa0
	s_load_dwordx2 s[14:15], s[76:77], 0xb0
	v_cndmask_b32_e32 v1, v0, v1, vcc
	v_lshlrev_b32_e32 v39, 2, v1
	v_xor_b32_e32 v1, 16, v0
	v_cmp_lt_i32_e32 vcc, v1, v2
	v_mov_b32_e32 v131, 0
	s_ashr_i32 s81, s80, 31
	v_cndmask_b32_e32 v1, v0, v1, vcc
	v_lshlrev_b32_e32 v40, 2, v1
	v_xor_b32_e32 v1, 8, v0
	v_cmp_lt_i32_e32 vcc, v1, v2
	v_cmp_eq_u32_e64 s[8:9], 0, v236
	s_waitcnt lgkmcnt(0)
	v_lshl_add_u64 v[32:33], v[174:175], 2, s[14:15]
	v_cndmask_b32_e32 v1, v0, v1, vcc
	v_lshlrev_b32_e32 v41, 2, v1
	v_xor_b32_e32 v1, 4, v0
	v_cmp_lt_i32_e32 vcc, v1, v2
	s_lshl_b64 s[14:15], s[80:81], 2
	s_lshl_b64 s[16:17], s[80:81], 13
	v_cndmask_b32_e32 v1, v0, v1, vcc
	v_lshlrev_b32_e32 v42, 2, v1
	v_xor_b32_e32 v1, 2, v0
	v_cmp_lt_i32_e32 vcc, v1, v2
	s_mov_b64 s[18:19], 0
	s_mov_b32 s3, 0x40f00000
	v_cndmask_b32_e32 v1, v0, v1, vcc
	v_lshlrev_b32_e32 v43, 2, v1
	v_xor_b32_e32 v1, 1, v0
	v_cmp_lt_i32_e32 vcc, v1, v2
	v_mov_b32_e32 v45, v174
	s_nop 0
	v_cndmask_b32_e32 v0, v0, v1, vcc
	v_lshlrev_b32_e32 v44, 2, v0
	v_lshlrev_b64 v[0:1], 13, v[174:175]
	v_lshl_or_b32 v0, v236, 4, v0
	v_lshl_add_u64 v[0:1], s[0:1], 0, v[0:1]
	s_mov_b64 s[0:1], 0x1000
	v_lshl_add_u64 v[34:35], v[0:1], 0, s[0:1]
	s_movk_i32 s0, 0x80
	v_lshrrev_b32_e32 v46, 3, v236
	v_and_b32_e32 v47, 7, v236
	v_mul_u32_u24_e32 v46, 0x300000, v46
	v_lshl_add_u32 v46, v47, 4, v46
	v_lshlrev_b32_e32 v48, 3, v47
	v_lshl_add_u32 v48, v174, 6, v48
	v_sub_u32_e32 v130, 0x200000, v48
	v_mov_b32_e32 v47, 0
	s_lshl_b32 s98, s80, 7
	s_mov_b32 s99, 0
	s_lshl_b32 s100, s80, 6
	v_mad_i64_i32 v[0:1], s[0:1], v174, s0, v[46:47]
	v_lshl_add_u64 v[0:1], s[6:7], 0, v[0:1]
	v_lshl_add_u64 v[36:37], v[0:1], 0, 8
	s_mov_b32 s6, 0x41000000
	s_movk_i32 s7, 0x3fff
	s_branch .LBB0_364
.LBB0_363:
	s_or_b64 exec, exec, s[20:21]
	v_add_u32_e32 v45, s80, v45
	v_cmp_lt_i32_e32 vcc, s7, v45
	v_lshl_add_u64 v[32:33], v[32:33], 0, s[14:15]
	v_lshl_add_u64 v[34:35], v[34:35], 0, s[16:17]
	s_or_b64 s[18:19], vcc, s[18:19]
	v_lshl_add_u64 v[36:37], v[36:37], 0, s[98:99]
	v_subrev_u32_e32 v130, s100, v130
	s_andn2_b64 exec, exec, s[18:19]
	s_cbranch_execz .LBB0_622

.LBB0_618:
	s_andn2_saveexec_b64 s[20:21], s[20:21]
	v_mul_f32_e64 v1, |v0|, s6
	v_rndne_f32_e32 v1, v1
	s_or_b64 exec, exec, s[20:21]
	v_max_f32_e32 v3, v80, v80
	v_min_f32_e32 v3, 0x41f80000, v3
	v_max_f32_e32 v51, v79, v79
	v_cvt_u32_f32_e32 v3, v3
	v_min_f32_e32 v51, 0x41f80000, v51
	v_cvt_u32_f32_e32 v51, v51
	v_cmp_gt_f32_e32 vcc, 0, v2
	v_max_f32_e32 v75, v75, v75
	v_min_f32_e32 v75, 0x41f80000, v75
	v_cndmask_b32_e64 v2, 0, 32, vcc
	v_cmp_gt_f32_e32 vcc, 0, v78
	v_or_b32_e32 v79, v2, v3
	v_cvt_u32_f32_e32 v75, v75
	v_cndmask_b32_e64 v2, 0, 32, vcc
	v_or_b32_e32 v51, v2, v51
	v_max_f32_e32 v2, v77, v77
	v_min_f32_e32 v2, 0x41f80000, v2
	v_cvt_u32_f32_e32 v2, v2
	v_cmp_gt_f32_e32 vcc, 0, v76
	v_max_f32_e32 v48, v48, v48
	v_max_f32_e32 v50, v50, v50
	v_cndmask_b32_e64 v3, 0, 32, vcc
	v_cmp_gt_f32_e32 vcc, 0, v7
	v_or_b32_e32 v76, v3, v2
	v_max_f32_e32 v3, v73, v73
	v_cndmask_b32_e64 v2, 0, 32, vcc
	v_or_b32_e32 v7, v2, v75
	v_max_f32_e32 v2, v74, v74
	v_min_f32_e32 v2, 0x41f80000, v2
	v_cvt_u32_f32_e32 v74, v2
	v_min_f32_e32 v3, 0x41f80000, v3
	v_cvt_u32_f32_e32 v3, v3
	v_cmp_gt_f32_e32 vcc, 0, v6
	v_max_f32_e32 v49, v49, v49
	v_min_f32_e32 v48, 0x41f80000, v48
	v_cndmask_b32_e64 v2, 0, 32, vcc
	v_cmp_gt_f32_e32 vcc, 0, v5
	v_or_b32_e32 v6, v2, v74
	v_max_f32_e32 v1, v1, v1
	v_cndmask_b32_e64 v2, 0, 32, vcc
	v_or_b32_e32 v5, v2, v3
	v_max_f32_e32 v2, v72, v72
	v_min_f32_e32 v2, 0x41f80000, v2
	v_cmp_gt_f32_e32 vcc, 0, v4
	v_max_f32_e32 v4, v71, v71
	v_cvt_u32_f32_e32 v2, v2
	v_min_f32_e32 v4, 0x41f80000, v4
	v_cvt_u32_f32_e32 v4, v4
	v_cndmask_b32_e64 v3, 0, 32, vcc
	v_cmp_gt_f32_e32 vcc, 0, v11
	v_or_b32_sdwa v71, v3, v2 dst_sel:WORD_1 dst_unused:UNUSED_PAD src0_sel:DWORD src1_sel:DWORD
	v_min_f32_e32 v50, 0x41f80000, v50
	v_cndmask_b32_e64 v2, 0, 32, vcc
	v_or_b32_e32 v4, v2, v4
	v_max_f32_e32 v2, v70, v70
	v_min_f32_e32 v2, 0x41f80000, v2
	v_cmp_gt_f32_e32 vcc, 0, v10
	v_max_f32_e32 v10, v69, v69
	v_cvt_u32_f32_e32 v2, v2
	v_min_f32_e32 v10, 0x41f80000, v10
	v_cvt_u32_f32_e32 v10, v10
	v_cndmask_b32_e64 v3, 0, 32, vcc
	v_cmp_gt_f32_e32 vcc, 0, v9
	v_or_b32_e32 v11, v3, v2
	v_min_f32_e32 v49, 0x41f80000, v49
	v_cndmask_b32_e64 v2, 0, 32, vcc
	v_or_b32_e32 v9, v2, v10
	v_max_f32_e32 v2, v68, v68
	v_min_f32_e32 v2, 0x41f80000, v2
	v_cmp_gt_f32_e32 vcc, 0, v8
	v_max_f32_e32 v8, v67, v67
	v_cvt_u32_f32_e32 v2, v2
	v_min_f32_e32 v8, 0x41f80000, v8
	v_cvt_u32_f32_e32 v8, v8
	v_cndmask_b32_e64 v3, 0, 32, vcc
	v_cmp_gt_f32_e32 vcc, 0, v15
	v_or_b32_sdwa v3, v3, v2 dst_sel:BYTE_3 dst_unused:UNUSED_PAD src0_sel:DWORD src1_sel:DWORD
	v_max_f32_e32 v15, v65, v65
	v_cndmask_b32_e64 v2, 0, 32, vcc
	v_or_b32_e32 v8, v2, v8
	v_max_f32_e32 v2, v66, v66
	v_min_f32_e32 v2, 0x41f80000, v2
	v_cvt_u32_f32_e32 v2, v2
	v_min_f32_e32 v15, 0x41f80000, v15
	v_cvt_u32_f32_e32 v15, v15
	v_cmp_gt_f32_e32 vcc, 0, v14
	v_cvt_u32_f32_e32 v48, v48
	v_max_f32_e32 v47, v47, v47
	v_cndmask_b32_e64 v14, 0, 32, vcc
	v_cmp_gt_f32_e32 vcc, 0, v13
	v_or_b32_e32 v14, v14, v2
	v_min_f32_e32 v1, 0x41f80000, v1
	v_cndmask_b32_e64 v2, 0, 32, vcc
	v_or_b32_e32 v13, v2, v15
	v_max_f32_e32 v2, v64, v64
	v_min_f32_e32 v2, 0x41f80000, v2
	v_cvt_u32_f32_e32 v15, v2
	v_max_f32_e32 v2, v63, v63
	v_min_f32_e32 v2, 0x41f80000, v2
	v_cvt_u32_f32_e32 v2, v2
	v_cmp_gt_f32_e32 vcc, 0, v12
	v_max_f32_e32 v53, v53, v53
	v_max_f32_e32 v52, v52, v52
	v_cndmask_b32_e64 v12, 0, 32, vcc
	v_cmp_gt_f32_e32 vcc, 0, v19
	v_cvt_u32_f32_e32 v50, v50
	v_cvt_u32_f32_e32 v49, v49
	v_cndmask_b32_e64 v19, 0, 32, vcc
	v_or_b32_e32 v2, v19, v2
	v_max_f32_e32 v19, v62, v62
	v_min_f32_e32 v19, 0x41f80000, v19
	v_cvt_u32_f32_e32 v19, v19
	v_cmp_gt_f32_e32 vcc, 0, v18
	v_min_f32_e32 v47, 0x41f80000, v47
	v_cvt_u32_f32_e32 v1, v1
	v_cndmask_b32_e64 v18, 0, 32, vcc
	v_or_b32_e32 v18, v18, v19
	v_max_f32_e32 v19, v60, v60
	v_min_f32_e32 v19, 0x41f80000, v19
	v_cvt_u32_f32_e32 v19, v19
	v_cmp_gt_f32_e32 vcc, 0, v17
	v_max_f32_e32 v55, v55, v55
	v_max_f32_e32 v54, v54, v54
	v_cndmask_b32_e64 v17, 0, 32, vcc
	v_cmp_gt_f32_e32 vcc, 0, v16
	v_min_f32_e32 v53, 0x41f80000, v53
	v_min_f32_e32 v52, 0x41f80000, v52
	v_cndmask_b32_e64 v16, 0, 32, vcc
	v_cmp_gt_f32_e32 vcc, 0, v23
	v_or_b32_e32 v16, v16, v19
	v_cvt_u32_f32_e32 v47, v47
	v_cndmask_b32_e64 v19, 0, 32, vcc
	v_cmp_gt_f32_e32 vcc, 0, v22
	v_max_f32_e32 v57, v57, v57
	v_max_f32_e32 v56, v56, v56
	v_cndmask_b32_e64 v22, 0, 32, vcc
	v_cmp_gt_f32_e32 vcc, 0, v21
	v_min_f32_e32 v55, 0x41f80000, v55
	v_min_f32_e32 v54, 0x41f80000, v54
	v_cndmask_b32_e64 v21, 0, 32, vcc
	v_cmp_gt_f32_e32 vcc, 0, v20
	v_cvt_u32_f32_e32 v53, v53
	v_cvt_u32_f32_e32 v52, v52
	v_cndmask_b32_e64 v20, 0, 32, vcc
	v_cmp_gt_f32_e32 vcc, 0, v27
	v_max_f32_e32 v23, v58, v58
	v_min_f32_e32 v57, 0x41f80000, v57
	v_cndmask_b32_e64 v27, 0, 32, vcc
	v_cmp_gt_f32_e32 vcc, 0, v26
	v_min_f32_e32 v56, 0x41f80000, v56
	v_cvt_u32_f32_e32 v55, v55
	v_cndmask_b32_e64 v26, 0, 32, vcc
	v_cmp_gt_f32_e32 vcc, 0, v25
	v_cvt_u32_f32_e32 v54, v54
	v_max_f32_e32 v61, v61, v61
	v_cndmask_b32_e64 v25, 0, 32, vcc
	v_cmp_gt_f32_e32 vcc, 0, v24
	v_max_f32_e32 v59, v59, v59
	v_min_f32_e32 v23, 0x41f80000, v23
	v_cndmask_b32_e64 v24, 0, 32, vcc
	v_cmp_gt_f32_e32 vcc, 0, v31
	v_cvt_u32_f32_e32 v57, v57
	v_cvt_u32_f32_e32 v56, v56
	v_cndmask_b32_e64 v31, 0, 32, vcc
	v_cmp_gt_f32_e32 vcc, 0, v30
	v_or_b32_e32 v31, v31, v50
	v_min_f32_e32 v61, 0x41f80000, v61
	v_cndmask_b32_e64 v30, 0, 32, vcc
	v_cmp_gt_f32_e32 vcc, 0, v29
	v_or_b32_e32 v30, v30, v49
	v_min_f32_e32 v59, 0x41f80000, v59
	v_cndmask_b32_e64 v29, 0, 32, vcc
	v_cmp_gt_f32_e32 vcc, 0, v28
	v_or_b32_e32 v29, v29, v48
	v_cvt_u32_f32_e32 v23, v23
	v_cndmask_b32_e64 v28, 0, 32, vcc
	v_cmp_gt_f32_e32 vcc, 0, v0
	v_lshlrev_b32_e32 v13, 6, v13
	v_cvt_u32_f32_e32 v61, v61
	v_cndmask_b32_e64 v0, 0, 32, vcc
	v_or_b32_e32 v48, v0, v1
	v_lshlrev_b32_e32 v0, 6, v29
	v_or3_b32 v0, v28, v47, v0
	v_lshlrev_b32_e32 v1, 12, v30
	v_lshlrev_b32_e32 v28, 18, v31
	v_cvt_u32_f32_e32 v59, v59
	v_or_b32_e32 v25, v25, v53
	v_or_b32_sdwa v24, v24, v52 dst_sel:BYTE_3 dst_unused:UNUSED_PAD src0_sel:DWORD src1_sel:DWORD
	v_or3_b32 v0, v0, v1, v28
	v_lshlrev_b32_e32 v1, 30, v53
	v_or3_b32 v12, v12, v15, v13
	v_lshlrev_b32_e32 v13, 12, v14
	v_lshlrev_b32_e32 v8, 18, v8
	v_or_b32_e32 v27, v27, v55
	v_or_b32_e32 v26, v26, v54
	v_or3_b32 v0, v0, v24, v1
	v_lshrrev_b32_e32 v1, 2, v25
	v_or3_b32 v8, v12, v13, v8
	v_lshlrev_b32_e32 v10, 30, v10
	v_or_b32_e32 v21, v21, v57
	v_or_b32_sdwa v20, v20, v56 dst_sel:WORD_1 dst_unused:UNUSED_PAD src0_sel:DWORD src1_sel:DWORD
	v_lshl_or_b32 v1, v26, 4, v1
	v_lshlrev_b32_e32 v24, 10, v27
	v_or3_b32 v3, v8, v3, v10
	v_lshrrev_b32_e32 v8, 2, v9
	v_or_b32_e32 v22, v22, v23
	v_or3_b32 v1, v1, v24, v20
	v_lshlrev_b32_e32 v20, 22, v21
	v_lshlrev_b32_e32 v21, 28, v23
	v_lshl_or_b32 v8, v11, 4, v8
	v_lshlrev_b32_e32 v4, 10, v4
	v_or_b32_e32 v17, v17, v61
	v_or_b32_e32 v19, v19, v59
	v_or3_b32 v1, v1, v20, v21
	v_lshrrev_b32_e32 v20, 4, v22
	v_or3_b32 v4, v8, v4, v71
	v_lshlrev_b32_e32 v5, 22, v5
	v_lshlrev_b32_e32 v8, 28, v74
	v_lshl_or_b32 v19, v19, 2, v20
	v_lshlrev_b32_e32 v16, 8, v16
	v_lshlrev_b32_e32 v17, 14, v17
	v_or3_b32 v4, v4, v5, v8
	v_lshrrev_b32_e32 v5, 4, v6
	v_or3_b32 v16, v19, v16, v17
	v_lshlrev_b32_e32 v17, 20, v18
	v_lshlrev_b32_e32 v2, 26, v2
	v_lshl_or_b32 v5, v7, 2, v5
	v_lshlrev_b32_e32 v6, 8, v76
	v_lshlrev_b32_e32 v7, 14, v51
	v_or3_b32 v2, v16, v17, v2
	v_or3_b32 v5, v5, v6, v7
	v_lshlrev_b32_e32 v6, 20, v79
	v_lshlrev_b32_e32 v7, 26, v48
	v_or3_b32 v5, v5, v6, v7
	global_store_dwordx4 v[36:37], v[0:3], off offset:-8
	v_lshl_add_u64 v[6:7], v[36:37], 0, v[130:131]
	global_store_dwordx2 v[6:7], v[4:5], off offset:-8
	s_and_saveexec_b64 s[20:21], s[8:9]
	s_cbranch_execz .LBB0_363
	v_mul_f32_e32 v0, 0x3e088889, v46
	global_store_dword v[32:33], v0, off
	s_branch .LBB0_363

.LBB0_1385:
	s_mov_b64 exec, -1
	s_nop 3
	v_readfirstlane_b32 s20, v174
	s_load_dwordx4 s[4:7], s[52:53], 0x120
	s_load_dwordx2 s[8:9], s[52:53], 0xa0
	s_load_dwordx2 s[10:11], s[52:53], 0x68
	s_load_dwordx2 s[12:13], s[52:53], 0x108
	s_load_dwordx2 s[14:15], s[52:53], 0x140
	s_load_dwordx2 s[16:17], s[52:53], 0x60
	s_load_dwordx2 s[48:49], s[52:53], 0x98
	s_load_dwordx2 s[78:79], s[52:53], 0x100
	s_load_dwordx2 s[54:55], s[52:53], 0x118
	s_load_dwordx2 s[56:57], s[52:53], 0x38
	s_load_dwordx2 s[58:59], s[52:53], 0xa8
	s_load_dwordx2 s[76:77], s[52:53], 0xb0
	s_and_b32 s21, s20, 3
	s_lshr_b32 s22, s20, 2
	s_and_b32 s23, s22, 7
	s_lshr_b32 s24, s22, 3
	s_lshl_b32 s24, s24, 2
	s_add_u32 s24, s24, s21
	s_lshr_b32 s25, s80, 2
	s_lshl_b32 s43, s23, 2
	s_movk_i32 s19, 0xc0
	v_mbcnt_lo_u32_b32 v0, -1, 0
	v_mbcnt_hi_u32_b32 v0, -1, v0
	v_and_b32_e32 v10, 7, v0
	v_lshrrev_b32_e32 v11, 3, v0
	v_lshlrev_b32_e32 v1, 4, v10
	v_lshlrev_b32_e32 v2, 6, v11
	v_mov_b32_e32 v3, 0
	s_mul_i32 s29, s21, 0x2400
	v_mul_u32_u24_e32 v4, 0x90, v0
	v_add_u32_e32 v4, s29, v4
	v_mul_u32_u24_e32 v5, 0x90, v10
	v_lshl_add_u32 v5, v11, 4, v5
	v_add_u32_e32 v5, s29, v5
	v_lshlrev_b32_e32 v6, 10, v11
	v_lshl_add_u32 v6, v10, 4, v6
	s_lshl_b32 s29, s23, 7
	v_add_u32_e32 v6, s29, v6
	v_cmp_eq_u32_e64 s[36:37], 63, v0
	s_waitcnt lgkmcnt(0)
	s_mul_i32 s29, s23, 0x300000
	s_add_u32 s26, s8, s29
	s_addc_u32 s27, s9, 0
	s_add_u32 s48, s48, s29
	s_addc_u32 s49, s49, 0
	s_lshl_b32 s29, s23, 9
	s_add_u32 s50, s78, s29
	s_addc_u32 s51, s79, 0
	v_cmp_eq_u32_e64 s[60:61], 0, v10
	v_cmp_eq_u32_e64 s[62:63], 1, v10
	v_cmp_eq_u32_e64 s[64:65], 2, v10
	v_cmp_eq_u32_e64 s[66:67], 3, v10
	v_cmp_eq_u32_e64 s[68:69], 4, v10
	v_cmp_eq_u32_e64 s[70:71], 5, v10
	v_cmp_eq_u32_e64 s[72:73], 6, v10
	v_cmp_eq_u32_e64 s[74:75], 7, v10
	v_lshlrev_b32_e32 v9, 2, v10
	v_lshl_add_u32 v9, v11, 6, v9
	s_lshl_b32 s29, s23, 7
	v_lshlrev_b32_e32 v13, 4, v10
	v_add_u32_e32 v13, s29, v13
	v_add_u32_e32 v14, 0x1000, v13
	v_lshl_add_u32 v15, v11, 10, v13
	global_load_dwordx4 v[112:115], v15, s[56:57]
	s_mul_i32 s29, s21, 0x2400
	v_mul_u32_u24_e32 v12, 0x90, v10
	v_add_u32_e32 v12, s29, v12
	v_lshl_add_u32 v15, v11, 4, v12
	s_waitcnt vmcnt(0)
	ds_write_b128 v15, v[112:115]
	s_waitcnt lgkmcnt(0)
	v_mov_b32_e32 v124, v12
	v_lshlrev_b32_e32 v125, 3, v10
	v_add_u32_e32 v125, 0x200000, v125
	s_mov_b32 s28, 0
	s_add_u32 s40, s28, 0
	s_min_u32 s40, s40, 127
	s_lshl_b32 s40, s40, 8
	s_add_u32 s40, s40, s24
	s_lshl_b32 s29, s40, 13
	s_add_u32 s34, s10, s29
	s_addc_u32 s35, s11, 0
	global_load_dwordx4 v[48:51], v13, s[34:35] offset:0
	global_load_dwordx4 v[52:55], v13, s[34:35] offset:1024
	global_load_dwordx4 v[56:59], v13, s[34:35] offset:2048
	global_load_dwordx4 v[60:63], v13, s[34:35] offset:3072
	global_load_dwordx4 v[64:67], v14, s[34:35] offset:0
	global_load_dwordx4 v[68:71], v14, s[34:35] offset:1024
	global_load_dwordx4 v[72:75], v14, s[34:35] offset:2048
	global_load_dwordx4 v[76:79], v14, s[34:35] offset:3072
	s_lshl_b32 s29, s40, 7
	s_add_u32 s38, s54, s29
	s_addc_u32 s39, s55, 0
	global_load_dwordx4 v[112:115], v1, s[38:39]
	s_add_u32 s40, s28, 0
	s_min_u32 s40, s40, 127
	s_lshl_b32 s40, s40, 8
	s_add_u32 s40, s40, s24
	s_lshl_b32 s29, s40, 9
	s_add_u32 s30, s4, s29
	s_addc_u32 s31, s5, 0
	global_load_dwordx4 v[16:19], v2, s[30:31] offset:0
	global_load_dwordx4 v[20:23], v2, s[30:31] offset:16
	global_load_dwordx4 v[24:27], v2, s[30:31] offset:32
	global_load_dwordx4 v[28:31], v2, s[30:31] offset:48
	s_add_u32 s40, s28, 1
	s_min_u32 s40, s40, 127
	s_lshl_b32 s40, s40, 8
	s_add_u32 s40, s40, s24
	s_lshl_b32 s29, s40, 9
	s_add_u32 s30, s4, s29
	s_addc_u32 s31, s5, 0
	global_load_dwordx4 v[32:35], v2, s[30:31] offset:0
	global_load_dwordx4 v[36:39], v2, s[30:31] offset:16
	global_load_dwordx4 v[40:43], v2, s[30:31] offset:32
	global_load_dwordx4 v[44:47], v2, s[30:31] offset:48
	s_waitcnt vmcnt(0)
	v_lshl_add_u32 v7, v16, 7, v1
	v_lshl_add_u32 v8, v16, 6, v125
	global_load_dwordx4 v[160:163], v7, s[48:49] sc1
	global_load_dwordx2 v[164:165], v8, s[48:49] sc1
	v_lshl_add_u32 v7, v17, 7, v1
	v_lshl_add_u32 v8, v17, 6, v125
	global_load_dwordx4 v[166:169], v7, s[48:49] sc1
	global_load_dwordx2 v[170:171], v8, s[48:49] sc1
	v_lshl_add_u32 v7, v18, 7, v1
	v_lshl_add_u32 v8, v18, 6, v125
	global_load_dwordx4 v[172:175], v7, s[48:49] sc1
	global_load_dwordx2 v[176:177], v8, s[48:49] sc1
	v_lshl_add_u32 v7, v19, 7, v1
	v_lshl_add_u32 v8, v19, 6, v125
	global_load_dwordx4 v[178:181], v7, s[48:49] sc1
	global_load_dwordx2 v[182:183], v8, s[48:49] sc1
	v_lshl_add_u32 v7, v20, 7, v1
	v_lshl_add_u32 v8, v20, 6, v125
	global_load_dwordx4 v[184:187], v7, s[48:49] sc1
	global_load_dwordx2 v[188:189], v8, s[48:49] sc1
	v_lshl_add_u32 v7, v21, 7, v1
	v_lshl_add_u32 v8, v21, 6, v125
	global_load_dwordx4 v[190:193], v7, s[48:49] sc1
	global_load_dwordx2 v[194:195], v8, s[48:49] sc1
	v_lshl_add_u32 v7, v22, 7, v1
	v_lshl_add_u32 v8, v22, 6, v125
	global_load_dwordx4 v[196:199], v7, s[48:49] sc1
	global_load_dwordx2 v[200:201], v8, s[48:49] sc1
	v_lshl_add_u32 v7, v23, 7, v1
	v_lshl_add_u32 v8, v23, 6, v125
	global_load_dwordx4 v[202:205], v7, s[48:49] sc1
	global_load_dwordx2 v[206:207], v8, s[48:49] sc1
	v_lshl_add_u32 v7, v24, 7, v1
	v_lshl_add_u32 v8, v24, 6, v125
	global_load_dwordx4 v[208:211], v7, s[48:49] sc1
	global_load_dwordx2 v[212:213], v8, s[48:49] sc1
	v_lshl_add_u32 v7, v25, 7, v1
	v_lshl_add_u32 v8, v25, 6, v125
	global_load_dwordx4 v[214:217], v7, s[48:49] sc1
	global_load_dwordx2 v[218:219], v8, s[48:49] sc1
	v_lshl_add_u32 v7, v26, 7, v1
	v_lshl_add_u32 v8, v26, 6, v125
	global_load_dwordx4 v[220:223], v7, s[48:49] sc1
	global_load_dwordx2 v[224:225], v8, s[48:49] sc1
	v_lshl_add_u32 v7, v27, 7, v1
	v_lshl_add_u32 v8, v27, 6, v125
	global_load_dwordx4 v[226:229], v7, s[48:49] sc1
	global_load_dwordx2 v[230:231], v8, s[48:49] sc1
	v_lshl_add_u32 v7, v28, 7, v1
	v_lshl_add_u32 v8, v28, 6, v125
	global_load_dwordx4 v[232:235], v7, s[48:49] sc1
	global_load_dwordx2 v[236:237], v8, s[48:49] sc1
	v_lshl_add_u32 v7, v29, 7, v1
	v_lshl_add_u32 v8, v29, 6, v125
	global_load_dwordx4 v[238:241], v7, s[48:49] sc1
	global_load_dwordx2 v[242:243], v8, s[48:49] sc1
	v_lshl_add_u32 v7, v30, 7, v1
	v_lshl_add_u32 v8, v30, 6, v125
	global_load_dwordx4 v[244:247], v7, s[48:49] sc1
	global_load_dwordx2 v[248:249], v8, s[48:49] sc1
	v_lshl_add_u32 v7, v31, 7, v1
	v_lshl_add_u32 v8, v31, 6, v125
	global_load_dwordx4 v[250:253], v7, s[48:49] sc1
	global_load_dwordx2 v[254:255], v8, s[48:49] sc1
	global_store_dword v3, v3, s[14:15] offset:480
	global_store_dword v3, v3, s[14:15] offset:484
.Lpa_tokloop:
	s_waitcnt vmcnt(34)
	ds_read_b128 v[128:131], v124 offset:0
	ds_read_b128 v[132:135], v124 offset:16
	ds_read_b128 v[136:139], v124 offset:32
	ds_read_b128 v[140:143], v124 offset:48
	ds_read_b128 v[144:147], v124 offset:64
	ds_read_b128 v[148:151], v124 offset:80
	ds_read_b128 v[152:155], v124 offset:96
	ds_read_b128 v[156:159], v124 offset:112
	v_add_f32_e32 v126, v112, v113
	v_add_f32_e32 v127, v114, v115
	v_add_f32_e32 v126, v126, v127
	s_nop 1
	v_add_f32_dpp v126, v126, v126 quad_perm:[1,0,3,2] row_mask:0xf bank_mask:0xf
	s_nop 1
	v_add_f32_dpp v126, v126, v126 quad_perm:[2,3,0,1] row_mask:0xf bank_mask:0xf
	s_nop 1
	v_add_f32_dpp v126, v126, v126 row_half_mirror row_mask:0xf bank_mask:0xf
	s_nop 1
	v_mov_b32_e32 v127, 0x358637bd
	v_fmac_f32_e32 v127, 0x3a000000, v126
	v_rsq_f32_e32 v127, v127
	s_waitcnt lgkmcnt(0)
	v_pk_mul_f32 v[80:81], v[48:49], v[128:129]
	v_pk_mul_f32 v[82:83], v[50:51], v[130:131]
	v_pk_mul_f32 v[84:85], v[52:53], v[132:133]
	v_pk_mul_f32 v[86:87], v[54:55], v[134:135]
	v_pk_mul_f32 v[88:89], v[56:57], v[136:137]
	v_pk_mul_f32 v[90:91], v[58:59], v[138:139]
	v_pk_mul_f32 v[92:93], v[60:61], v[140:141]
	v_pk_mul_f32 v[94:95], v[62:63], v[142:143]
	v_pk_mul_f32 v[96:97], v[64:65], v[144:145]
	v_pk_mul_f32 v[98:99], v[66:67], v[146:147]
	v_pk_mul_f32 v[100:101], v[68:69], v[148:149]
	v_pk_mul_f32 v[102:103], v[70:71], v[150:151]
	v_pk_mul_f32 v[104:105], v[72:73], v[152:153]
	v_pk_mul_f32 v[106:107], v[74:75], v[154:155]
	v_pk_mul_f32 v[108:109], v[76:77], v[156:157]
	v_pk_mul_f32 v[110:111], v[78:79], v[158:159]
	s_add_u32 s40, s28, 0
	s_min_u32 s40, s40, 127
	s_lshl_b32 s40, s40, 8
	s_add_u32 s40, s40, s24
	s_lshl_b32 s29, s40, 12
	s_add_u32 s44, s50, s29
	s_addc_u32 s45, s51, 0
	s_add_u32 s40, s28, 1
	s_min_u32 s40, s40, 127
	s_lshl_b32 s40, s40, 8
	s_add_u32 s40, s40, s24
	s_lshl_b32 s29, s40, 13
	s_add_u32 s34, s10, s29
	s_addc_u32 s35, s11, 0
	global_load_dwordx4 v[48:51], v13, s[34:35] offset:0
	global_load_dwordx4 v[52:55], v13, s[34:35] offset:1024
	global_load_dwordx4 v[56:59], v13, s[34:35] offset:2048
	global_load_dwordx4 v[60:63], v13, s[34:35] offset:3072
	global_load_dwordx4 v[64:67], v14, s[34:35] offset:0
	global_load_dwordx4 v[68:71], v14, s[34:35] offset:1024
	global_load_dwordx4 v[72:75], v14, s[34:35] offset:2048
	global_load_dwordx4 v[76:79], v14, s[34:35] offset:3072
	s_lshl_b32 s29, s40, 7
	s_add_u32 s38, s54, s29
	s_addc_u32 s39, s55, 0
	global_load_dwordx4 v[112:115], v1, s[38:39]
	s_add_u32 s40, s28, 2
	s_min_u32 s40, s40, 127
	s_lshl_b32 s40, s40, 8
	s_add_u32 s40, s40, s24
	s_lshl_b32 s29, s40, 9
	s_add_u32 s30, s4, s29
	s_addc_u32 s31, s5, 0
	global_load_dwordx4 v[16:19], v2, s[30:31] offset:0
	global_load_dwordx4 v[20:23], v2, s[30:31] offset:16
	global_load_dwordx4 v[24:27], v2, s[30:31] offset:32
	global_load_dwordx4 v[28:31], v2, s[30:31] offset:48
	s_waitcnt vmcnt(45)
	v_cvt_scalef32_pk32_f32_fp6 v[128:159], v[160:165], 1.0
	v_pk_mul_f32 v[116:117], v[128:129], v[80:81]
	v_pk_mul_f32 v[118:119], v[130:131], v[82:83]
	v_pk_mul_f32 v[120:121], v[132:133], v[84:85]
	v_pk_mul_f32 v[122:123], v[134:135], v[86:87]
	v_pk_fma_f32 v[116:117], v[136:137], v[88:89], v[116:117]
	v_pk_fma_f32 v[118:119], v[138:139], v[90:91], v[118:119]
	v_pk_fma_f32 v[120:121], v[140:141], v[92:93], v[120:121]
	v_pk_fma_f32 v[122:123], v[142:143], v[94:95], v[122:123]
	v_pk_fma_f32 v[116:117], v[144:145], v[96:97], v[116:117]
	v_pk_fma_f32 v[118:119], v[146:147], v[98:99], v[118:119]
	v_pk_fma_f32 v[120:121], v[148:149], v[100:101], v[120:121]
	v_pk_fma_f32 v[122:123], v[150:151], v[102:103], v[122:123]
	v_pk_fma_f32 v[116:117], v[152:153], v[104:105], v[116:117]
	v_pk_fma_f32 v[118:119], v[154:155], v[106:107], v[118:119]
	v_pk_fma_f32 v[120:121], v[156:157], v[108:109], v[120:121]
	v_pk_fma_f32 v[122:123], v[158:159], v[110:111], v[122:123]
	v_pk_add_f32 v[116:117], v[116:117], v[118:119]
	v_pk_add_f32 v[120:121], v[120:121], v[122:123]
	v_pk_add_f32 v[116:117], v[116:117], v[120:121]
	v_add_f32_e32 v126, v116, v117
	v_lshl_add_u32 v7, v32, 7, v1
	v_lshl_add_u32 v8, v32, 6, v125
	v_add_f32_dpp v126, v126, v126 quad_perm:[1,0,3,2] row_mask:0xf bank_mask:0xf
	global_load_dwordx4 v[160:163], v7, s[48:49] sc1
	s_nop 0
	v_add_f32_dpp v126, v126, v126 quad_perm:[2,3,0,1] row_mask:0xf bank_mask:0xf
	global_load_dwordx2 v[164:165], v8, s[48:49] sc1
	s_nop 0
	v_add_f32_dpp v126, v126, v126 row_half_mirror row_mask:0xf bank_mask:0xf
	v_cndmask_b32_e64 v12, v12, v126, s[60:61]
	s_waitcnt vmcnt(45)
	v_cvt_scalef32_pk32_f32_fp6 v[128:159], v[166:171], 1.0
	v_pk_mul_f32 v[116:117], v[128:129], v[80:81]
	v_pk_mul_f32 v[118:119], v[130:131], v[82:83]
	v_pk_mul_f32 v[120:121], v[132:133], v[84:85]
	v_pk_mul_f32 v[122:123], v[134:135], v[86:87]
	v_pk_fma_f32 v[116:117], v[136:137], v[88:89], v[116:117]
	v_pk_fma_f32 v[118:119], v[138:139], v[90:91], v[118:119]
	v_pk_fma_f32 v[120:121], v[140:141], v[92:93], v[120:121]
	v_pk_fma_f32 v[122:123], v[142:143], v[94:95], v[122:123]
	v_pk_fma_f32 v[116:117], v[144:145], v[96:97], v[116:117]
	v_pk_fma_f32 v[118:119], v[146:147], v[98:99], v[118:119]
	v_pk_fma_f32 v[120:121], v[148:149], v[100:101], v[120:121]
	v_pk_fma_f32 v[122:123], v[150:151], v[102:103], v[122:123]
	v_pk_fma_f32 v[116:117], v[152:153], v[104:105], v[116:117]
	v_pk_fma_f32 v[118:119], v[154:155], v[106:107], v[118:119]
	v_pk_fma_f32 v[120:121], v[156:157], v[108:109], v[120:121]
	v_pk_fma_f32 v[122:123], v[158:159], v[110:111], v[122:123]
	v_pk_add_f32 v[116:117], v[116:117], v[118:119]
	v_pk_add_f32 v[120:121], v[120:121], v[122:123]
	v_pk_add_f32 v[116:117], v[116:117], v[120:121]
	v_add_f32_e32 v126, v116, v117
	v_lshl_add_u32 v7, v33, 7, v1
	v_lshl_add_u32 v8, v33, 6, v125
	v_add_f32_dpp v126, v126, v126 quad_perm:[1,0,3,2] row_mask:0xf bank_mask:0xf
	global_load_dwordx4 v[166:169], v7, s[48:49] sc1
	s_nop 0
	v_add_f32_dpp v126, v126, v126 quad_perm:[2,3,0,1] row_mask:0xf bank_mask:0xf
	global_load_dwordx2 v[170:171], v8, s[48:49] sc1
	s_nop 0
	v_add_f32_dpp v126, v126, v126 row_half_mirror row_mask:0xf bank_mask:0xf
	v_cndmask_b32_e64 v12, v12, v126, s[62:63]
	s_waitcnt vmcnt(45)
	v_cvt_scalef32_pk32_f32_fp6 v[128:159], v[172:177], 1.0
	v_pk_mul_f32 v[116:117], v[128:129], v[80:81]
	v_pk_mul_f32 v[118:119], v[130:131], v[82:83]
	v_pk_mul_f32 v[120:121], v[132:133], v[84:85]
	v_pk_mul_f32 v[122:123], v[134:135], v[86:87]
	v_pk_fma_f32 v[116:117], v[136:137], v[88:89], v[116:117]
	v_pk_fma_f32 v[118:119], v[138:139], v[90:91], v[118:119]
	v_pk_fma_f32 v[120:121], v[140:141], v[92:93], v[120:121]
	v_pk_fma_f32 v[122:123], v[142:143], v[94:95], v[122:123]
	v_pk_fma_f32 v[116:117], v[144:145], v[96:97], v[116:117]
	v_pk_fma_f32 v[118:119], v[146:147], v[98:99], v[118:119]
	v_pk_fma_f32 v[120:121], v[148:149], v[100:101], v[120:121]
	v_pk_fma_f32 v[122:123], v[150:151], v[102:103], v[122:123]
	v_pk_fma_f32 v[116:117], v[152:153], v[104:105], v[116:117]
	v_pk_fma_f32 v[118:119], v[154:155], v[106:107], v[118:119]
	v_pk_fma_f32 v[120:121], v[156:157], v[108:109], v[120:121]
	v_pk_fma_f32 v[122:123], v[158:159], v[110:111], v[122:123]
	v_pk_add_f32 v[116:117], v[116:117], v[118:119]
	v_pk_add_f32 v[120:121], v[120:121], v[122:123]
	v_pk_add_f32 v[116:117], v[116:117], v[120:121]
	v_add_f32_e32 v126, v116, v117
	v_lshl_add_u32 v7, v34, 7, v1
	v_lshl_add_u32 v8, v34, 6, v125
	v_add_f32_dpp v126, v126, v126 quad_perm:[1,0,3,2] row_mask:0xf bank_mask:0xf
	global_load_dwordx4 v[172:175], v7, s[48:49] sc1
	s_nop 0
	v_add_f32_dpp v126, v126, v126 quad_perm:[2,3,0,1] row_mask:0xf bank_mask:0xf
	global_load_dwordx2 v[176:177], v8, s[48:49] sc1
	s_nop 0
	v_add_f32_dpp v126, v126, v126 row_half_mirror row_mask:0xf bank_mask:0xf
	v_cndmask_b32_e64 v12, v12, v126, s[64:65]
	s_waitcnt vmcnt(45)
	v_cvt_scalef32_pk32_f32_fp6 v[128:159], v[178:183], 1.0
	v_pk_mul_f32 v[116:117], v[128:129], v[80:81]
	v_pk_mul_f32 v[118:119], v[130:131], v[82:83]
	v_pk_mul_f32 v[120:121], v[132:133], v[84:85]
	v_pk_mul_f32 v[122:123], v[134:135], v[86:87]
	v_pk_fma_f32 v[116:117], v[136:137], v[88:89], v[116:117]
	v_pk_fma_f32 v[118:119], v[138:139], v[90:91], v[118:119]
	v_pk_fma_f32 v[120:121], v[140:141], v[92:93], v[120:121]
	v_pk_fma_f32 v[122:123], v[142:143], v[94:95], v[122:123]
	v_pk_fma_f32 v[116:117], v[144:145], v[96:97], v[116:117]
	v_pk_fma_f32 v[118:119], v[146:147], v[98:99], v[118:119]
	v_pk_fma_f32 v[120:121], v[148:149], v[100:101], v[120:121]
	v_pk_fma_f32 v[122:123], v[150:151], v[102:103], v[122:123]
	v_pk_fma_f32 v[116:117], v[152:153], v[104:105], v[116:117]
	v_pk_fma_f32 v[118:119], v[154:155], v[106:107], v[118:119]
	v_pk_fma_f32 v[120:121], v[156:157], v[108:109], v[120:121]
	v_pk_fma_f32 v[122:123], v[158:159], v[110:111], v[122:123]
	v_pk_add_f32 v[116:117], v[116:117], v[118:119]
	v_pk_add_f32 v[120:121], v[120:121], v[122:123]
	v_pk_add_f32 v[116:117], v[116:117], v[120:121]
	v_add_f32_e32 v126, v116, v117
	v_lshl_add_u32 v7, v35, 7, v1
	v_lshl_add_u32 v8, v35, 6, v125
	v_add_f32_dpp v126, v126, v126 quad_perm:[1,0,3,2] row_mask:0xf bank_mask:0xf
	global_load_dwordx4 v[178:181], v7, s[48:49] sc1
	s_nop 0
	v_add_f32_dpp v126, v126, v126 quad_perm:[2,3,0,1] row_mask:0xf bank_mask:0xf
	global_load_dwordx2 v[182:183], v8, s[48:49] sc1
	s_nop 0
	v_add_f32_dpp v126, v126, v126 row_half_mirror row_mask:0xf bank_mask:0xf
	v_cndmask_b32_e64 v12, v12, v126, s[66:67]
	s_waitcnt vmcnt(45)
	v_cvt_scalef32_pk32_f32_fp6 v[128:159], v[184:189], 1.0
	v_pk_mul_f32 v[116:117], v[128:129], v[80:81]
	v_pk_mul_f32 v[118:119], v[130:131], v[82:83]
	v_pk_mul_f32 v[120:121], v[132:133], v[84:85]
	v_pk_mul_f32 v[122:123], v[134:135], v[86:87]
	v_pk_fma_f32 v[116:117], v[136:137], v[88:89], v[116:117]
	v_pk_fma_f32 v[118:119], v[138:139], v[90:91], v[118:119]
	v_pk_fma_f32 v[120:121], v[140:141], v[92:93], v[120:121]
	v_pk_fma_f32 v[122:123], v[142:143], v[94:95], v[122:123]
	v_pk_fma_f32 v[116:117], v[144:145], v[96:97], v[116:117]
	v_pk_fma_f32 v[118:119], v[146:147], v[98:99], v[118:119]
	v_pk_fma_f32 v[120:121], v[148:149], v[100:101], v[120:121]
	v_pk_fma_f32 v[122:123], v[150:151], v[102:103], v[122:123]
	v_pk_fma_f32 v[116:117], v[152:153], v[104:105], v[116:117]
	v_pk_fma_f32 v[118:119], v[154:155], v[106:107], v[118:119]
	v_pk_fma_f32 v[120:121], v[156:157], v[108:109], v[120:121]
	v_pk_fma_f32 v[122:123], v[158:159], v[110:111], v[122:123]
	v_pk_add_f32 v[116:117], v[116:117], v[118:119]
	v_pk_add_f32 v[120:121], v[120:121], v[122:123]
	v_pk_add_f32 v[116:117], v[116:117], v[120:121]
	v_add_f32_e32 v126, v116, v117
	v_lshl_add_u32 v7, v36, 7, v1
	v_lshl_add_u32 v8, v36, 6, v125
	v_add_f32_dpp v126, v126, v126 quad_perm:[1,0,3,2] row_mask:0xf bank_mask:0xf
	global_load_dwordx4 v[184:187], v7, s[48:49] sc1
	s_nop 0
	v_add_f32_dpp v126, v126, v126 quad_perm:[2,3,0,1] row_mask:0xf bank_mask:0xf
	global_load_dwordx2 v[188:189], v8, s[48:49] sc1
	s_nop 0
	v_add_f32_dpp v126, v126, v126 row_half_mirror row_mask:0xf bank_mask:0xf
	v_cndmask_b32_e64 v12, v12, v126, s[68:69]
	s_waitcnt vmcnt(45)
	v_cvt_scalef32_pk32_f32_fp6 v[128:159], v[190:195], 1.0
	v_pk_mul_f32 v[116:117], v[128:129], v[80:81]
	v_pk_mul_f32 v[118:119], v[130:131], v[82:83]
	v_pk_mul_f32 v[120:121], v[132:133], v[84:85]
	v_pk_mul_f32 v[122:123], v[134:135], v[86:87]
	v_pk_fma_f32 v[116:117], v[136:137], v[88:89], v[116:117]
	v_pk_fma_f32 v[118:119], v[138:139], v[90:91], v[118:119]
	v_pk_fma_f32 v[120:121], v[140:141], v[92:93], v[120:121]
	v_pk_fma_f32 v[122:123], v[142:143], v[94:95], v[122:123]
	v_pk_fma_f32 v[116:117], v[144:145], v[96:97], v[116:117]
	v_pk_fma_f32 v[118:119], v[146:147], v[98:99], v[118:119]
	v_pk_fma_f32 v[120:121], v[148:149], v[100:101], v[120:121]
	v_pk_fma_f32 v[122:123], v[150:151], v[102:103], v[122:123]
	v_pk_fma_f32 v[116:117], v[152:153], v[104:105], v[116:117]
	v_pk_fma_f32 v[118:119], v[154:155], v[106:107], v[118:119]
	v_pk_fma_f32 v[120:121], v[156:157], v[108:109], v[120:121]
	v_pk_fma_f32 v[122:123], v[158:159], v[110:111], v[122:123]
	v_pk_add_f32 v[116:117], v[116:117], v[118:119]
	v_pk_add_f32 v[120:121], v[120:121], v[122:123]
	v_pk_add_f32 v[116:117], v[116:117], v[120:121]
	v_add_f32_e32 v126, v116, v117
	v_lshl_add_u32 v7, v37, 7, v1
	v_lshl_add_u32 v8, v37, 6, v125
	v_add_f32_dpp v126, v126, v126 quad_perm:[1,0,3,2] row_mask:0xf bank_mask:0xf
	global_load_dwordx4 v[190:193], v7, s[48:49] sc1
	s_nop 0
	v_add_f32_dpp v126, v126, v126 quad_perm:[2,3,0,1] row_mask:0xf bank_mask:0xf
	global_load_dwordx2 v[194:195], v8, s[48:49] sc1
	s_nop 0
	v_add_f32_dpp v126, v126, v126 row_half_mirror row_mask:0xf bank_mask:0xf
	v_cndmask_b32_e64 v12, v12, v126, s[70:71]
	s_waitcnt vmcnt(45)
	v_cvt_scalef32_pk32_f32_fp6 v[128:159], v[196:201], 1.0
	v_pk_mul_f32 v[116:117], v[128:129], v[80:81]
	v_pk_mul_f32 v[118:119], v[130:131], v[82:83]
	v_pk_mul_f32 v[120:121], v[132:133], v[84:85]
	v_pk_mul_f32 v[122:123], v[134:135], v[86:87]
	v_pk_fma_f32 v[116:117], v[136:137], v[88:89], v[116:117]
	v_pk_fma_f32 v[118:119], v[138:139], v[90:91], v[118:119]
	v_pk_fma_f32 v[120:121], v[140:141], v[92:93], v[120:121]
	v_pk_fma_f32 v[122:123], v[142:143], v[94:95], v[122:123]
	v_pk_fma_f32 v[116:117], v[144:145], v[96:97], v[116:117]
	v_pk_fma_f32 v[118:119], v[146:147], v[98:99], v[118:119]
	v_pk_fma_f32 v[120:121], v[148:149], v[100:101], v[120:121]
	v_pk_fma_f32 v[122:123], v[150:151], v[102:103], v[122:123]
	v_pk_fma_f32 v[116:117], v[152:153], v[104:105], v[116:117]
	v_pk_fma_f32 v[118:119], v[154:155], v[106:107], v[118:119]
	v_pk_fma_f32 v[120:121], v[156:157], v[108:109], v[120:121]
	v_pk_fma_f32 v[122:123], v[158:159], v[110:111], v[122:123]
	v_pk_add_f32 v[116:117], v[116:117], v[118:119]
	v_pk_add_f32 v[120:121], v[120:121], v[122:123]
	v_pk_add_f32 v[116:117], v[116:117], v[120:121]
	v_add_f32_e32 v126, v116, v117
	v_lshl_add_u32 v7, v38, 7, v1
	v_lshl_add_u32 v8, v38, 6, v125
	v_add_f32_dpp v126, v126, v126 quad_perm:[1,0,3,2] row_mask:0xf bank_mask:0xf
	global_load_dwordx4 v[196:199], v7, s[48:49] sc1
	s_nop 0
	v_add_f32_dpp v126, v126, v126 quad_perm:[2,3,0,1] row_mask:0xf bank_mask:0xf
	global_load_dwordx2 v[200:201], v8, s[48:49] sc1
	s_nop 0
	v_add_f32_dpp v126, v126, v126 row_half_mirror row_mask:0xf bank_mask:0xf
	v_cndmask_b32_e64 v12, v12, v126, s[72:73]
	s_waitcnt vmcnt(45)
	v_cvt_scalef32_pk32_f32_fp6 v[128:159], v[202:207], 1.0
	v_pk_mul_f32 v[116:117], v[128:129], v[80:81]
	v_pk_mul_f32 v[118:119], v[130:131], v[82:83]
	v_pk_mul_f32 v[120:121], v[132:133], v[84:85]
	v_pk_mul_f32 v[122:123], v[134:135], v[86:87]
	v_pk_fma_f32 v[116:117], v[136:137], v[88:89], v[116:117]
	v_pk_fma_f32 v[118:119], v[138:139], v[90:91], v[118:119]
	v_pk_fma_f32 v[120:121], v[140:141], v[92:93], v[120:121]
	v_pk_fma_f32 v[122:123], v[142:143], v[94:95], v[122:123]
	v_pk_fma_f32 v[116:117], v[144:145], v[96:97], v[116:117]
	v_pk_fma_f32 v[118:119], v[146:147], v[98:99], v[118:119]
	v_pk_fma_f32 v[120:121], v[148:149], v[100:101], v[120:121]
	v_pk_fma_f32 v[122:123], v[150:151], v[102:103], v[122:123]
	v_pk_fma_f32 v[116:117], v[152:153], v[104:105], v[116:117]
	v_pk_fma_f32 v[118:119], v[154:155], v[106:107], v[118:119]
	v_pk_fma_f32 v[120:121], v[156:157], v[108:109], v[120:121]
	v_pk_fma_f32 v[122:123], v[158:159], v[110:111], v[122:123]
	v_pk_add_f32 v[116:117], v[116:117], v[118:119]
	v_pk_add_f32 v[120:121], v[120:121], v[122:123]
	v_pk_add_f32 v[116:117], v[116:117], v[120:121]
	v_add_f32_e32 v126, v116, v117
	v_lshl_add_u32 v7, v39, 7, v1
	v_lshl_add_u32 v8, v39, 6, v125
	v_add_f32_dpp v126, v126, v126 quad_perm:[1,0,3,2] row_mask:0xf bank_mask:0xf
	global_load_dwordx4 v[202:205], v7, s[48:49] sc1
	s_nop 0
	v_add_f32_dpp v126, v126, v126 quad_perm:[2,3,0,1] row_mask:0xf bank_mask:0xf
	global_load_dwordx2 v[206:207], v8, s[48:49] sc1
	s_nop 0
	v_add_f32_dpp v126, v126, v126 row_half_mirror row_mask:0xf bank_mask:0xf
	v_cndmask_b32_e64 v12, v12, v126, s[74:75]
	s_waitcnt vmcnt(45)
	v_cvt_scalef32_pk32_f32_fp6 v[128:159], v[208:213], 1.0
	v_pk_mul_f32 v[116:117], v[128:129], v[80:81]
	v_pk_mul_f32 v[118:119], v[130:131], v[82:83]
	v_pk_mul_f32 v[120:121], v[132:133], v[84:85]
	v_pk_mul_f32 v[122:123], v[134:135], v[86:87]
	v_pk_fma_f32 v[116:117], v[136:137], v[88:89], v[116:117]
	v_pk_fma_f32 v[118:119], v[138:139], v[90:91], v[118:119]
	v_pk_fma_f32 v[120:121], v[140:141], v[92:93], v[120:121]
	v_pk_fma_f32 v[122:123], v[142:143], v[94:95], v[122:123]
	v_pk_fma_f32 v[116:117], v[144:145], v[96:97], v[116:117]
	v_pk_fma_f32 v[118:119], v[146:147], v[98:99], v[118:119]
	v_pk_fma_f32 v[120:121], v[148:149], v[100:101], v[120:121]
	v_pk_fma_f32 v[122:123], v[150:151], v[102:103], v[122:123]
	v_pk_fma_f32 v[116:117], v[152:153], v[104:105], v[116:117]
	v_pk_fma_f32 v[118:119], v[154:155], v[106:107], v[118:119]
	v_pk_fma_f32 v[120:121], v[156:157], v[108:109], v[120:121]
	v_pk_fma_f32 v[122:123], v[158:159], v[110:111], v[122:123]
	v_pk_add_f32 v[116:117], v[116:117], v[118:119]
	v_pk_add_f32 v[120:121], v[120:121], v[122:123]
	v_pk_add_f32 v[116:117], v[116:117], v[120:121]
	v_add_f32_e32 v126, v116, v117
	v_lshl_add_u32 v7, v40, 7, v1
	v_lshl_add_u32 v8, v40, 6, v125
	v_add_f32_dpp v126, v126, v126 quad_perm:[1,0,3,2] row_mask:0xf bank_mask:0xf
	global_load_dwordx4 v[208:211], v7, s[48:49] sc1
	s_nop 0
	v_add_f32_dpp v126, v126, v126 quad_perm:[2,3,0,1] row_mask:0xf bank_mask:0xf
	global_load_dwordx2 v[212:213], v8, s[48:49] sc1
	s_nop 0
	v_add_f32_dpp v126, v126, v126 row_half_mirror row_mask:0xf bank_mask:0xf
	v_cndmask_b32_e64 v15, v15, v126, s[60:61]
	s_waitcnt vmcnt(45)
	v_cvt_scalef32_pk32_f32_fp6 v[128:159], v[214:219], 1.0
	v_pk_mul_f32 v[116:117], v[128:129], v[80:81]
	v_pk_mul_f32 v[118:119], v[130:131], v[82:83]
	v_pk_mul_f32 v[120:121], v[132:133], v[84:85]
	v_pk_mul_f32 v[122:123], v[134:135], v[86:87]
	v_pk_fma_f32 v[116:117], v[136:137], v[88:89], v[116:117]
	v_pk_fma_f32 v[118:119], v[138:139], v[90:91], v[118:119]
	v_pk_fma_f32 v[120:121], v[140:141], v[92:93], v[120:121]
	v_pk_fma_f32 v[122:123], v[142:143], v[94:95], v[122:123]
	v_pk_fma_f32 v[116:117], v[144:145], v[96:97], v[116:117]
	v_pk_fma_f32 v[118:119], v[146:147], v[98:99], v[118:119]
	v_pk_fma_f32 v[120:121], v[148:149], v[100:101], v[120:121]
	v_pk_fma_f32 v[122:123], v[150:151], v[102:103], v[122:123]
	v_pk_fma_f32 v[116:117], v[152:153], v[104:105], v[116:117]
	v_pk_fma_f32 v[118:119], v[154:155], v[106:107], v[118:119]
	v_pk_fma_f32 v[120:121], v[156:157], v[108:109], v[120:121]
	v_pk_fma_f32 v[122:123], v[158:159], v[110:111], v[122:123]
	v_pk_add_f32 v[116:117], v[116:117], v[118:119]
	v_pk_add_f32 v[120:121], v[120:121], v[122:123]
	v_pk_add_f32 v[116:117], v[116:117], v[120:121]
	v_add_f32_e32 v126, v116, v117
	v_lshl_add_u32 v7, v41, 7, v1
	v_lshl_add_u32 v8, v41, 6, v125
	v_add_f32_dpp v126, v126, v126 quad_perm:[1,0,3,2] row_mask:0xf bank_mask:0xf
	global_load_dwordx4 v[214:217], v7, s[48:49] sc1
	s_nop 0
	v_add_f32_dpp v126, v126, v126 quad_perm:[2,3,0,1] row_mask:0xf bank_mask:0xf
	global_load_dwordx2 v[218:219], v8, s[48:49] sc1
	s_nop 0
	v_add_f32_dpp v126, v126, v126 row_half_mirror row_mask:0xf bank_mask:0xf
	v_cndmask_b32_e64 v15, v15, v126, s[62:63]
	s_waitcnt vmcnt(45)
	v_cvt_scalef32_pk32_f32_fp6 v[128:159], v[220:225], 1.0
	v_pk_mul_f32 v[116:117], v[128:129], v[80:81]
	v_pk_mul_f32 v[118:119], v[130:131], v[82:83]
	v_pk_mul_f32 v[120:121], v[132:133], v[84:85]
	v_pk_mul_f32 v[122:123], v[134:135], v[86:87]
	v_pk_fma_f32 v[116:117], v[136:137], v[88:89], v[116:117]
	v_pk_fma_f32 v[118:119], v[138:139], v[90:91], v[118:119]
	v_pk_fma_f32 v[120:121], v[140:141], v[92:93], v[120:121]
	v_pk_fma_f32 v[122:123], v[142:143], v[94:95], v[122:123]
	v_pk_fma_f32 v[116:117], v[144:145], v[96:97], v[116:117]
	v_pk_fma_f32 v[118:119], v[146:147], v[98:99], v[118:119]
	v_pk_fma_f32 v[120:121], v[148:149], v[100:101], v[120:121]
	v_pk_fma_f32 v[122:123], v[150:151], v[102:103], v[122:123]
	v_pk_fma_f32 v[116:117], v[152:153], v[104:105], v[116:117]
	v_pk_fma_f32 v[118:119], v[154:155], v[106:107], v[118:119]
	v_pk_fma_f32 v[120:121], v[156:157], v[108:109], v[120:121]
	v_pk_fma_f32 v[122:123], v[158:159], v[110:111], v[122:123]
	v_pk_add_f32 v[116:117], v[116:117], v[118:119]
	v_pk_add_f32 v[120:121], v[120:121], v[122:123]
	v_pk_add_f32 v[116:117], v[116:117], v[120:121]
	v_add_f32_e32 v126, v116, v117
	v_lshl_add_u32 v7, v42, 7, v1
	v_lshl_add_u32 v8, v42, 6, v125
	v_add_f32_dpp v126, v126, v126 quad_perm:[1,0,3,2] row_mask:0xf bank_mask:0xf
	global_load_dwordx4 v[220:223], v7, s[48:49] sc1
	s_nop 0
	v_add_f32_dpp v126, v126, v126 quad_perm:[2,3,0,1] row_mask:0xf bank_mask:0xf
	global_load_dwordx2 v[224:225], v8, s[48:49] sc1
	s_nop 0
	v_add_f32_dpp v126, v126, v126 row_half_mirror row_mask:0xf bank_mask:0xf
	v_cndmask_b32_e64 v15, v15, v126, s[64:65]
	s_waitcnt vmcnt(45)
	v_cvt_scalef32_pk32_f32_fp6 v[128:159], v[226:231], 1.0
	v_pk_mul_f32 v[116:117], v[128:129], v[80:81]
	v_pk_mul_f32 v[118:119], v[130:131], v[82:83]
	v_pk_mul_f32 v[120:121], v[132:133], v[84:85]
	v_pk_mul_f32 v[122:123], v[134:135], v[86:87]
	v_pk_fma_f32 v[116:117], v[136:137], v[88:89], v[116:117]
	v_pk_fma_f32 v[118:119], v[138:139], v[90:91], v[118:119]
	v_pk_fma_f32 v[120:121], v[140:141], v[92:93], v[120:121]
	v_pk_fma_f32 v[122:123], v[142:143], v[94:95], v[122:123]
	v_pk_fma_f32 v[116:117], v[144:145], v[96:97], v[116:117]
	v_pk_fma_f32 v[118:119], v[146:147], v[98:99], v[118:119]
	v_pk_fma_f32 v[120:121], v[148:149], v[100:101], v[120:121]
	v_pk_fma_f32 v[122:123], v[150:151], v[102:103], v[122:123]
	v_pk_fma_f32 v[116:117], v[152:153], v[104:105], v[116:117]
	v_pk_fma_f32 v[118:119], v[154:155], v[106:107], v[118:119]
	v_pk_fma_f32 v[120:121], v[156:157], v[108:109], v[120:121]
	v_pk_fma_f32 v[122:123], v[158:159], v[110:111], v[122:123]
	v_pk_add_f32 v[116:117], v[116:117], v[118:119]
	v_pk_add_f32 v[120:121], v[120:121], v[122:123]
	v_pk_add_f32 v[116:117], v[116:117], v[120:121]
	v_add_f32_e32 v126, v116, v117
	v_lshl_add_u32 v7, v43, 7, v1
	v_lshl_add_u32 v8, v43, 6, v125
	v_add_f32_dpp v126, v126, v126 quad_perm:[1,0,3,2] row_mask:0xf bank_mask:0xf
	global_load_dwordx4 v[226:229], v7, s[48:49] sc1
	s_nop 0
	v_add_f32_dpp v126, v126, v126 quad_perm:[2,3,0,1] row_mask:0xf bank_mask:0xf
	global_load_dwordx2 v[230:231], v8, s[48:49] sc1
	s_nop 0
	v_add_f32_dpp v126, v126, v126 row_half_mirror row_mask:0xf bank_mask:0xf
	v_cndmask_b32_e64 v15, v15, v126, s[66:67]
	s_waitcnt vmcnt(45)
	v_cvt_scalef32_pk32_f32_fp6 v[128:159], v[232:237], 1.0
	v_pk_mul_f32 v[116:117], v[128:129], v[80:81]
	v_pk_mul_f32 v[118:119], v[130:131], v[82:83]
	v_pk_mul_f32 v[120:121], v[132:133], v[84:85]
	v_pk_mul_f32 v[122:123], v[134:135], v[86:87]
	v_pk_fma_f32 v[116:117], v[136:137], v[88:89], v[116:117]
	v_pk_fma_f32 v[118:119], v[138:139], v[90:91], v[118:119]
	v_pk_fma_f32 v[120:121], v[140:141], v[92:93], v[120:121]
	v_pk_fma_f32 v[122:123], v[142:143], v[94:95], v[122:123]
	v_pk_fma_f32 v[116:117], v[144:145], v[96:97], v[116:117]
	v_pk_fma_f32 v[118:119], v[146:147], v[98:99], v[118:119]
	v_pk_fma_f32 v[120:121], v[148:149], v[100:101], v[120:121]
	v_pk_fma_f32 v[122:123], v[150:151], v[102:103], v[122:123]
	v_pk_fma_f32 v[116:117], v[152:153], v[104:105], v[116:117]
	v_pk_fma_f32 v[118:119], v[154:155], v[106:107], v[118:119]
	v_pk_fma_f32 v[120:121], v[156:157], v[108:109], v[120:121]
	v_pk_fma_f32 v[122:123], v[158:159], v[110:111], v[122:123]
	v_pk_add_f32 v[116:117], v[116:117], v[118:119]
	v_pk_add_f32 v[120:121], v[120:121], v[122:123]
	v_pk_add_f32 v[116:117], v[116:117], v[120:121]
	v_add_f32_e32 v126, v116, v117
	v_lshl_add_u32 v7, v44, 7, v1
	v_lshl_add_u32 v8, v44, 6, v125
	v_add_f32_dpp v126, v126, v126 quad_perm:[1,0,3,2] row_mask:0xf bank_mask:0xf
	global_load_dwordx4 v[232:235], v7, s[48:49] sc1
	s_nop 0
	v_add_f32_dpp v126, v126, v126 quad_perm:[2,3,0,1] row_mask:0xf bank_mask:0xf
	global_load_dwordx2 v[236:237], v8, s[48:49] sc1
	s_nop 0
	v_add_f32_dpp v126, v126, v126 row_half_mirror row_mask:0xf bank_mask:0xf
	v_cndmask_b32_e64 v15, v15, v126, s[68:69]
	s_waitcnt vmcnt(45)
	v_cvt_scalef32_pk32_f32_fp6 v[128:159], v[238:243], 1.0
	v_pk_mul_f32 v[116:117], v[128:129], v[80:81]
	v_pk_mul_f32 v[118:119], v[130:131], v[82:83]
	v_pk_mul_f32 v[120:121], v[132:133], v[84:85]
	v_pk_mul_f32 v[122:123], v[134:135], v[86:87]
	v_pk_fma_f32 v[116:117], v[136:137], v[88:89], v[116:117]
	v_pk_fma_f32 v[118:119], v[138:139], v[90:91], v[118:119]
	v_pk_fma_f32 v[120:121], v[140:141], v[92:93], v[120:121]
	v_pk_fma_f32 v[122:123], v[142:143], v[94:95], v[122:123]
	v_pk_fma_f32 v[116:117], v[144:145], v[96:97], v[116:117]
	v_pk_fma_f32 v[118:119], v[146:147], v[98:99], v[118:119]
	v_pk_fma_f32 v[120:121], v[148:149], v[100:101], v[120:121]
	v_pk_fma_f32 v[122:123], v[150:151], v[102:103], v[122:123]
	v_pk_fma_f32 v[116:117], v[152:153], v[104:105], v[116:117]
	v_pk_fma_f32 v[118:119], v[154:155], v[106:107], v[118:119]
	v_pk_fma_f32 v[120:121], v[156:157], v[108:109], v[120:121]
	v_pk_fma_f32 v[122:123], v[158:159], v[110:111], v[122:123]
	v_pk_add_f32 v[116:117], v[116:117], v[118:119]
	v_pk_add_f32 v[120:121], v[120:121], v[122:123]
	v_pk_add_f32 v[116:117], v[116:117], v[120:121]
	v_add_f32_e32 v126, v116, v117
	v_lshl_add_u32 v7, v45, 7, v1
	v_lshl_add_u32 v8, v45, 6, v125
	v_add_f32_dpp v126, v126, v126 quad_perm:[1,0,3,2] row_mask:0xf bank_mask:0xf
	global_load_dwordx4 v[238:241], v7, s[48:49] sc1
	s_nop 0
	v_add_f32_dpp v126, v126, v126 quad_perm:[2,3,0,1] row_mask:0xf bank_mask:0xf
	global_load_dwordx2 v[242:243], v8, s[48:49] sc1
	s_nop 0
	v_add_f32_dpp v126, v126, v126 row_half_mirror row_mask:0xf bank_mask:0xf
	v_cndmask_b32_e64 v15, v15, v126, s[70:71]
	s_waitcnt vmcnt(45)
	v_cvt_scalef32_pk32_f32_fp6 v[128:159], v[244:249], 1.0
	v_pk_mul_f32 v[116:117], v[128:129], v[80:81]
	v_pk_mul_f32 v[118:119], v[130:131], v[82:83]
	v_pk_mul_f32 v[120:121], v[132:133], v[84:85]
	v_pk_mul_f32 v[122:123], v[134:135], v[86:87]
	v_pk_fma_f32 v[116:117], v[136:137], v[88:89], v[116:117]
	v_pk_fma_f32 v[118:119], v[138:139], v[90:91], v[118:119]
	v_pk_fma_f32 v[120:121], v[140:141], v[92:93], v[120:121]
	v_pk_fma_f32 v[122:123], v[142:143], v[94:95], v[122:123]
	v_pk_fma_f32 v[116:117], v[144:145], v[96:97], v[116:117]
	v_pk_fma_f32 v[118:119], v[146:147], v[98:99], v[118:119]
	v_pk_fma_f32 v[120:121], v[148:149], v[100:101], v[120:121]
	v_pk_fma_f32 v[122:123], v[150:151], v[102:103], v[122:123]
	v_pk_fma_f32 v[116:117], v[152:153], v[104:105], v[116:117]
	v_pk_fma_f32 v[118:119], v[154:155], v[106:107], v[118:119]
	v_pk_fma_f32 v[120:121], v[156:157], v[108:109], v[120:121]
	v_pk_fma_f32 v[122:123], v[158:159], v[110:111], v[122:123]
	v_pk_add_f32 v[116:117], v[116:117], v[118:119]
	v_pk_add_f32 v[120:121], v[120:121], v[122:123]
	v_pk_add_f32 v[116:117], v[116:117], v[120:121]
	v_add_f32_e32 v126, v116, v117
	v_lshl_add_u32 v7, v46, 7, v1
	v_lshl_add_u32 v8, v46, 6, v125
	v_add_f32_dpp v126, v126, v126 quad_perm:[1,0,3,2] row_mask:0xf bank_mask:0xf
	global_load_dwordx4 v[244:247], v7, s[48:49] sc1
	s_nop 0
	v_add_f32_dpp v126, v126, v126 quad_perm:[2,3,0,1] row_mask:0xf bank_mask:0xf
	global_load_dwordx2 v[248:249], v8, s[48:49] sc1
	s_nop 0
	v_add_f32_dpp v126, v126, v126 row_half_mirror row_mask:0xf bank_mask:0xf
	v_cndmask_b32_e64 v15, v15, v126, s[72:73]
	s_waitcnt vmcnt(45)
	v_cvt_scalef32_pk32_f32_fp6 v[128:159], v[250:255], 1.0
	v_pk_mul_f32 v[116:117], v[128:129], v[80:81]
	v_pk_mul_f32 v[118:119], v[130:131], v[82:83]
	v_pk_mul_f32 v[120:121], v[132:133], v[84:85]
	v_pk_mul_f32 v[122:123], v[134:135], v[86:87]
	v_pk_fma_f32 v[116:117], v[136:137], v[88:89], v[116:117]
	v_pk_fma_f32 v[118:119], v[138:139], v[90:91], v[118:119]
	v_pk_fma_f32 v[120:121], v[140:141], v[92:93], v[120:121]
	v_pk_fma_f32 v[122:123], v[142:143], v[94:95], v[122:123]
	v_pk_fma_f32 v[116:117], v[144:145], v[96:97], v[116:117]
	v_pk_fma_f32 v[118:119], v[146:147], v[98:99], v[118:119]
	v_pk_fma_f32 v[120:121], v[148:149], v[100:101], v[120:121]
	v_pk_fma_f32 v[122:123], v[150:151], v[102:103], v[122:123]
	v_pk_fma_f32 v[116:117], v[152:153], v[104:105], v[116:117]
	v_pk_fma_f32 v[118:119], v[154:155], v[106:107], v[118:119]
	v_pk_fma_f32 v[120:121], v[156:157], v[108:109], v[120:121]
	v_pk_fma_f32 v[122:123], v[158:159], v[110:111], v[122:123]
	v_pk_add_f32 v[116:117], v[116:117], v[118:119]
	v_pk_add_f32 v[120:121], v[120:121], v[122:123]
	v_pk_add_f32 v[116:117], v[116:117], v[120:121]
	v_add_f32_e32 v126, v116, v117
	v_lshl_add_u32 v7, v47, 7, v1
	v_lshl_add_u32 v8, v47, 6, v125
	v_add_f32_dpp v126, v126, v126 quad_perm:[1,0,3,2] row_mask:0xf bank_mask:0xf
	global_load_dwordx4 v[250:253], v7, s[48:49] sc1
	s_nop 0
	v_add_f32_dpp v126, v126, v126 quad_perm:[2,3,0,1] row_mask:0xf bank_mask:0xf
	global_load_dwordx2 v[254:255], v8, s[48:49] sc1
	s_nop 0
	v_add_f32_dpp v126, v126, v126 row_half_mirror row_mask:0xf bank_mask:0xf
	v_cndmask_b32_e64 v15, v15, v126, s[74:75]
	v_mul_f32_e32 v12, v12, v127
	v_mul_f32_e32 v15, v15, v127
	global_store_dword v9, v12, s[44:45]
	global_store_dword v9, v15, s[44:45] offset:32
	s_add_u32 s28, s28, 1
	s_waitcnt vmcnt(34)
	ds_read_b128 v[128:131], v124 offset:0
	ds_read_b128 v[132:135], v124 offset:16
	ds_read_b128 v[136:139], v124 offset:32
	ds_read_b128 v[140:143], v124 offset:48
	ds_read_b128 v[144:147], v124 offset:64
	ds_read_b128 v[148:151], v124 offset:80
	ds_read_b128 v[152:155], v124 offset:96
	ds_read_b128 v[156:159], v124 offset:112
	v_add_f32_e32 v126, v112, v113
	v_add_f32_e32 v127, v114, v115
	v_add_f32_e32 v126, v126, v127
	s_nop 1
	v_add_f32_dpp v126, v126, v126 quad_perm:[1,0,3,2] row_mask:0xf bank_mask:0xf
	s_nop 1
	v_add_f32_dpp v126, v126, v126 quad_perm:[2,3,0,1] row_mask:0xf bank_mask:0xf
	s_nop 1
	v_add_f32_dpp v126, v126, v126 row_half_mirror row_mask:0xf bank_mask:0xf
	s_nop 1
	v_mov_b32_e32 v127, 0x358637bd
	v_fmac_f32_e32 v127, 0x3a000000, v126
	v_rsq_f32_e32 v127, v127
	s_waitcnt lgkmcnt(0)
	v_pk_mul_f32 v[80:81], v[48:49], v[128:129]
	v_pk_mul_f32 v[82:83], v[50:51], v[130:131]
	v_pk_mul_f32 v[84:85], v[52:53], v[132:133]
	v_pk_mul_f32 v[86:87], v[54:55], v[134:135]
	v_pk_mul_f32 v[88:89], v[56:57], v[136:137]
	v_pk_mul_f32 v[90:91], v[58:59], v[138:139]
	v_pk_mul_f32 v[92:93], v[60:61], v[140:141]
	v_pk_mul_f32 v[94:95], v[62:63], v[142:143]
	v_pk_mul_f32 v[96:97], v[64:65], v[144:145]
	v_pk_mul_f32 v[98:99], v[66:67], v[146:147]
	v_pk_mul_f32 v[100:101], v[68:69], v[148:149]
	v_pk_mul_f32 v[102:103], v[70:71], v[150:151]
	v_pk_mul_f32 v[104:105], v[72:73], v[152:153]
	v_pk_mul_f32 v[106:107], v[74:75], v[154:155]
	v_pk_mul_f32 v[108:109], v[76:77], v[156:157]
	v_pk_mul_f32 v[110:111], v[78:79], v[158:159]
	s_add_u32 s40, s28, 0
	s_min_u32 s40, s40, 127
	s_lshl_b32 s40, s40, 8
	s_add_u32 s40, s40, s24
	s_lshl_b32 s29, s40, 12
	s_add_u32 s44, s50, s29
	s_addc_u32 s45, s51, 0
	s_add_u32 s40, s28, 1
	s_min_u32 s40, s40, 127
	s_lshl_b32 s40, s40, 8
	s_add_u32 s40, s40, s24
	s_lshl_b32 s29, s40, 13
	s_add_u32 s34, s10, s29
	s_addc_u32 s35, s11, 0
	global_load_dwordx4 v[48:51], v13, s[34:35] offset:0
	global_load_dwordx4 v[52:55], v13, s[34:35] offset:1024
	global_load_dwordx4 v[56:59], v13, s[34:35] offset:2048
	global_load_dwordx4 v[60:63], v13, s[34:35] offset:3072
	global_load_dwordx4 v[64:67], v14, s[34:35] offset:0
	global_load_dwordx4 v[68:71], v14, s[34:35] offset:1024
	global_load_dwordx4 v[72:75], v14, s[34:35] offset:2048
	global_load_dwordx4 v[76:79], v14, s[34:35] offset:3072
	s_lshl_b32 s29, s40, 7
	s_add_u32 s38, s54, s29
	s_addc_u32 s39, s55, 0
	global_load_dwordx4 v[112:115], v1, s[38:39]
	s_add_u32 s40, s28, 2
	s_min_u32 s40, s40, 127
	s_lshl_b32 s40, s40, 8
	s_add_u32 s40, s40, s24
	s_lshl_b32 s29, s40, 9
	s_add_u32 s30, s4, s29
	s_addc_u32 s31, s5, 0
	global_load_dwordx4 v[32:35], v2, s[30:31] offset:0
	global_load_dwordx4 v[36:39], v2, s[30:31] offset:16
	global_load_dwordx4 v[40:43], v2, s[30:31] offset:32
	global_load_dwordx4 v[44:47], v2, s[30:31] offset:48
	s_waitcnt vmcnt(45)
	v_cvt_scalef32_pk32_f32_fp6 v[128:159], v[160:165], 1.0
	v_pk_mul_f32 v[116:117], v[128:129], v[80:81]
	v_pk_mul_f32 v[118:119], v[130:131], v[82:83]
	v_pk_mul_f32 v[120:121], v[132:133], v[84:85]
	v_pk_mul_f32 v[122:123], v[134:135], v[86:87]
	v_pk_fma_f32 v[116:117], v[136:137], v[88:89], v[116:117]
	v_pk_fma_f32 v[118:119], v[138:139], v[90:91], v[118:119]
	v_pk_fma_f32 v[120:121], v[140:141], v[92:93], v[120:121]
	v_pk_fma_f32 v[122:123], v[142:143], v[94:95], v[122:123]
	v_pk_fma_f32 v[116:117], v[144:145], v[96:97], v[116:117]
	v_pk_fma_f32 v[118:119], v[146:147], v[98:99], v[118:119]
	v_pk_fma_f32 v[120:121], v[148:149], v[100:101], v[120:121]
	v_pk_fma_f32 v[122:123], v[150:151], v[102:103], v[122:123]
	v_pk_fma_f32 v[116:117], v[152:153], v[104:105], v[116:117]
	v_pk_fma_f32 v[118:119], v[154:155], v[106:107], v[118:119]
	v_pk_fma_f32 v[120:121], v[156:157], v[108:109], v[120:121]
	v_pk_fma_f32 v[122:123], v[158:159], v[110:111], v[122:123]
	v_pk_add_f32 v[116:117], v[116:117], v[118:119]
	v_pk_add_f32 v[120:121], v[120:121], v[122:123]
	v_pk_add_f32 v[116:117], v[116:117], v[120:121]
	v_add_f32_e32 v126, v116, v117
	v_lshl_add_u32 v7, v16, 7, v1
	v_lshl_add_u32 v8, v16, 6, v125
	v_add_f32_dpp v126, v126, v126 quad_perm:[1,0,3,2] row_mask:0xf bank_mask:0xf
	global_load_dwordx4 v[160:163], v7, s[48:49] sc1
	s_nop 0
	v_add_f32_dpp v126, v126, v126 quad_perm:[2,3,0,1] row_mask:0xf bank_mask:0xf
	global_load_dwordx2 v[164:165], v8, s[48:49] sc1
	s_nop 0
	v_add_f32_dpp v126, v126, v126 row_half_mirror row_mask:0xf bank_mask:0xf
	v_cndmask_b32_e64 v12, v12, v126, s[60:61]
	s_waitcnt vmcnt(45)
	v_cvt_scalef32_pk32_f32_fp6 v[128:159], v[166:171], 1.0
	v_pk_mul_f32 v[116:117], v[128:129], v[80:81]
	v_pk_mul_f32 v[118:119], v[130:131], v[82:83]
	v_pk_mul_f32 v[120:121], v[132:133], v[84:85]
	v_pk_mul_f32 v[122:123], v[134:135], v[86:87]
	v_pk_fma_f32 v[116:117], v[136:137], v[88:89], v[116:117]
	v_pk_fma_f32 v[118:119], v[138:139], v[90:91], v[118:119]
	v_pk_fma_f32 v[120:121], v[140:141], v[92:93], v[120:121]
	v_pk_fma_f32 v[122:123], v[142:143], v[94:95], v[122:123]
	v_pk_fma_f32 v[116:117], v[144:145], v[96:97], v[116:117]
	v_pk_fma_f32 v[118:119], v[146:147], v[98:99], v[118:119]
	v_pk_fma_f32 v[120:121], v[148:149], v[100:101], v[120:121]
	v_pk_fma_f32 v[122:123], v[150:151], v[102:103], v[122:123]
	v_pk_fma_f32 v[116:117], v[152:153], v[104:105], v[116:117]
	v_pk_fma_f32 v[118:119], v[154:155], v[106:107], v[118:119]
	v_pk_fma_f32 v[120:121], v[156:157], v[108:109], v[120:121]
	v_pk_fma_f32 v[122:123], v[158:159], v[110:111], v[122:123]
	v_pk_add_f32 v[116:117], v[116:117], v[118:119]
	v_pk_add_f32 v[120:121], v[120:121], v[122:123]
	v_pk_add_f32 v[116:117], v[116:117], v[120:121]
	v_add_f32_e32 v126, v116, v117
	v_lshl_add_u32 v7, v17, 7, v1
	v_lshl_add_u32 v8, v17, 6, v125
	v_add_f32_dpp v126, v126, v126 quad_perm:[1,0,3,2] row_mask:0xf bank_mask:0xf
	global_load_dwordx4 v[166:169], v7, s[48:49] sc1
	s_nop 0
	v_add_f32_dpp v126, v126, v126 quad_perm:[2,3,0,1] row_mask:0xf bank_mask:0xf
	global_load_dwordx2 v[170:171], v8, s[48:49] sc1
	s_nop 0
	v_add_f32_dpp v126, v126, v126 row_half_mirror row_mask:0xf bank_mask:0xf
	v_cndmask_b32_e64 v12, v12, v126, s[62:63]
	s_waitcnt vmcnt(45)
	v_cvt_scalef32_pk32_f32_fp6 v[128:159], v[172:177], 1.0
	v_pk_mul_f32 v[116:117], v[128:129], v[80:81]
	v_pk_mul_f32 v[118:119], v[130:131], v[82:83]
	v_pk_mul_f32 v[120:121], v[132:133], v[84:85]
	v_pk_mul_f32 v[122:123], v[134:135], v[86:87]
	v_pk_fma_f32 v[116:117], v[136:137], v[88:89], v[116:117]
	v_pk_fma_f32 v[118:119], v[138:139], v[90:91], v[118:119]
	v_pk_fma_f32 v[120:121], v[140:141], v[92:93], v[120:121]
	v_pk_fma_f32 v[122:123], v[142:143], v[94:95], v[122:123]
	v_pk_fma_f32 v[116:117], v[144:145], v[96:97], v[116:117]
	v_pk_fma_f32 v[118:119], v[146:147], v[98:99], v[118:119]
	v_pk_fma_f32 v[120:121], v[148:149], v[100:101], v[120:121]
	v_pk_fma_f32 v[122:123], v[150:151], v[102:103], v[122:123]
	v_pk_fma_f32 v[116:117], v[152:153], v[104:105], v[116:117]
	v_pk_fma_f32 v[118:119], v[154:155], v[106:107], v[118:119]
	v_pk_fma_f32 v[120:121], v[156:157], v[108:109], v[120:121]
	v_pk_fma_f32 v[122:123], v[158:159], v[110:111], v[122:123]
	v_pk_add_f32 v[116:117], v[116:117], v[118:119]
	v_pk_add_f32 v[120:121], v[120:121], v[122:123]
	v_pk_add_f32 v[116:117], v[116:117], v[120:121]
	v_add_f32_e32 v126, v116, v117
	v_lshl_add_u32 v7, v18, 7, v1
	v_lshl_add_u32 v8, v18, 6, v125
	v_add_f32_dpp v126, v126, v126 quad_perm:[1,0,3,2] row_mask:0xf bank_mask:0xf
	global_load_dwordx4 v[172:175], v7, s[48:49] sc1
	s_nop 0
	v_add_f32_dpp v126, v126, v126 quad_perm:[2,3,0,1] row_mask:0xf bank_mask:0xf
	global_load_dwordx2 v[176:177], v8, s[48:49] sc1
	s_nop 0
	v_add_f32_dpp v126, v126, v126 row_half_mirror row_mask:0xf bank_mask:0xf
	v_cndmask_b32_e64 v12, v12, v126, s[64:65]
	s_waitcnt vmcnt(45)
	v_cvt_scalef32_pk32_f32_fp6 v[128:159], v[178:183], 1.0
	v_pk_mul_f32 v[116:117], v[128:129], v[80:81]
	v_pk_mul_f32 v[118:119], v[130:131], v[82:83]
	v_pk_mul_f32 v[120:121], v[132:133], v[84:85]
	v_pk_mul_f32 v[122:123], v[134:135], v[86:87]
	v_pk_fma_f32 v[116:117], v[136:137], v[88:89], v[116:117]
	v_pk_fma_f32 v[118:119], v[138:139], v[90:91], v[118:119]
	v_pk_fma_f32 v[120:121], v[140:141], v[92:93], v[120:121]
	v_pk_fma_f32 v[122:123], v[142:143], v[94:95], v[122:123]
	v_pk_fma_f32 v[116:117], v[144:145], v[96:97], v[116:117]
	v_pk_fma_f32 v[118:119], v[146:147], v[98:99], v[118:119]
	v_pk_fma_f32 v[120:121], v[148:149], v[100:101], v[120:121]
	v_pk_fma_f32 v[122:123], v[150:151], v[102:103], v[122:123]
	v_pk_fma_f32 v[116:117], v[152:153], v[104:105], v[116:117]
	v_pk_fma_f32 v[118:119], v[154:155], v[106:107], v[118:119]
	v_pk_fma_f32 v[120:121], v[156:157], v[108:109], v[120:121]
	v_pk_fma_f32 v[122:123], v[158:159], v[110:111], v[122:123]
	v_pk_add_f32 v[116:117], v[116:117], v[118:119]
	v_pk_add_f32 v[120:121], v[120:121], v[122:123]
	v_pk_add_f32 v[116:117], v[116:117], v[120:121]
	v_add_f32_e32 v126, v116, v117
	v_lshl_add_u32 v7, v19, 7, v1
	v_lshl_add_u32 v8, v19, 6, v125
	v_add_f32_dpp v126, v126, v126 quad_perm:[1,0,3,2] row_mask:0xf bank_mask:0xf
	global_load_dwordx4 v[178:181], v7, s[48:49] sc1
	s_nop 0
	v_add_f32_dpp v126, v126, v126 quad_perm:[2,3,0,1] row_mask:0xf bank_mask:0xf
	global_load_dwordx2 v[182:183], v8, s[48:49] sc1
	s_nop 0
	v_add_f32_dpp v126, v126, v126 row_half_mirror row_mask:0xf bank_mask:0xf
	v_cndmask_b32_e64 v12, v12, v126, s[66:67]
	s_waitcnt vmcnt(45)
	v_cvt_scalef32_pk32_f32_fp6 v[128:159], v[184:189], 1.0
	v_pk_mul_f32 v[116:117], v[128:129], v[80:81]
	v_pk_mul_f32 v[118:119], v[130:131], v[82:83]
	v_pk_mul_f32 v[120:121], v[132:133], v[84:85]
	v_pk_mul_f32 v[122:123], v[134:135], v[86:87]
	v_pk_fma_f32 v[116:117], v[136:137], v[88:89], v[116:117]
	v_pk_fma_f32 v[118:119], v[138:139], v[90:91], v[118:119]
	v_pk_fma_f32 v[120:121], v[140:141], v[92:93], v[120:121]
	v_pk_fma_f32 v[122:123], v[142:143], v[94:95], v[122:123]
	v_pk_fma_f32 v[116:117], v[144:145], v[96:97], v[116:117]
	v_pk_fma_f32 v[118:119], v[146:147], v[98:99], v[118:119]
	v_pk_fma_f32 v[120:121], v[148:149], v[100:101], v[120:121]
	v_pk_fma_f32 v[122:123], v[150:151], v[102:103], v[122:123]
	v_pk_fma_f32 v[116:117], v[152:153], v[104:105], v[116:117]
	v_pk_fma_f32 v[118:119], v[154:155], v[106:107], v[118:119]
	v_pk_fma_f32 v[120:121], v[156:157], v[108:109], v[120:121]
	v_pk_fma_f32 v[122:123], v[158:159], v[110:111], v[122:123]
	v_pk_add_f32 v[116:117], v[116:117], v[118:119]
	v_pk_add_f32 v[120:121], v[120:121], v[122:123]
	v_pk_add_f32 v[116:117], v[116:117], v[120:121]
	v_add_f32_e32 v126, v116, v117
	v_lshl_add_u32 v7, v20, 7, v1
	v_lshl_add_u32 v8, v20, 6, v125
	v_add_f32_dpp v126, v126, v126 quad_perm:[1,0,3,2] row_mask:0xf bank_mask:0xf
	global_load_dwordx4 v[184:187], v7, s[48:49] sc1
	s_nop 0
	v_add_f32_dpp v126, v126, v126 quad_perm:[2,3,0,1] row_mask:0xf bank_mask:0xf
	global_load_dwordx2 v[188:189], v8, s[48:49] sc1
	s_nop 0
	v_add_f32_dpp v126, v126, v126 row_half_mirror row_mask:0xf bank_mask:0xf
	v_cndmask_b32_e64 v12, v12, v126, s[68:69]
	s_waitcnt vmcnt(45)
	v_cvt_scalef32_pk32_f32_fp6 v[128:159], v[190:195], 1.0
	v_pk_mul_f32 v[116:117], v[128:129], v[80:81]
	v_pk_mul_f32 v[118:119], v[130:131], v[82:83]
	v_pk_mul_f32 v[120:121], v[132:133], v[84:85]
	v_pk_mul_f32 v[122:123], v[134:135], v[86:87]
	v_pk_fma_f32 v[116:117], v[136:137], v[88:89], v[116:117]
	v_pk_fma_f32 v[118:119], v[138:139], v[90:91], v[118:119]
	v_pk_fma_f32 v[120:121], v[140:141], v[92:93], v[120:121]
	v_pk_fma_f32 v[122:123], v[142:143], v[94:95], v[122:123]
	v_pk_fma_f32 v[116:117], v[144:145], v[96:97], v[116:117]
	v_pk_fma_f32 v[118:119], v[146:147], v[98:99], v[118:119]
	v_pk_fma_f32 v[120:121], v[148:149], v[100:101], v[120:121]
	v_pk_fma_f32 v[122:123], v[150:151], v[102:103], v[122:123]
	v_pk_fma_f32 v[116:117], v[152:153], v[104:105], v[116:117]
	v_pk_fma_f32 v[118:119], v[154:155], v[106:107], v[118:119]
	v_pk_fma_f32 v[120:121], v[156:157], v[108:109], v[120:121]
	v_pk_fma_f32 v[122:123], v[158:159], v[110:111], v[122:123]
	v_pk_add_f32 v[116:117], v[116:117], v[118:119]
	v_pk_add_f32 v[120:121], v[120:121], v[122:123]
	v_pk_add_f32 v[116:117], v[116:117], v[120:121]
	v_add_f32_e32 v126, v116, v117
	v_lshl_add_u32 v7, v21, 7, v1
	v_lshl_add_u32 v8, v21, 6, v125
	v_add_f32_dpp v126, v126, v126 quad_perm:[1,0,3,2] row_mask:0xf bank_mask:0xf
	global_load_dwordx4 v[190:193], v7, s[48:49] sc1
	s_nop 0
	v_add_f32_dpp v126, v126, v126 quad_perm:[2,3,0,1] row_mask:0xf bank_mask:0xf
	global_load_dwordx2 v[194:195], v8, s[48:49] sc1
	s_nop 0
	v_add_f32_dpp v126, v126, v126 row_half_mirror row_mask:0xf bank_mask:0xf
	v_cndmask_b32_e64 v12, v12, v126, s[70:71]
	s_waitcnt vmcnt(45)
	v_cvt_scalef32_pk32_f32_fp6 v[128:159], v[196:201], 1.0
	v_pk_mul_f32 v[116:117], v[128:129], v[80:81]
	v_pk_mul_f32 v[118:119], v[130:131], v[82:83]
	v_pk_mul_f32 v[120:121], v[132:133], v[84:85]
	v_pk_mul_f32 v[122:123], v[134:135], v[86:87]
	v_pk_fma_f32 v[116:117], v[136:137], v[88:89], v[116:117]
	v_pk_fma_f32 v[118:119], v[138:139], v[90:91], v[118:119]
	v_pk_fma_f32 v[120:121], v[140:141], v[92:93], v[120:121]
	v_pk_fma_f32 v[122:123], v[142:143], v[94:95], v[122:123]
	v_pk_fma_f32 v[116:117], v[144:145], v[96:97], v[116:117]
	v_pk_fma_f32 v[118:119], v[146:147], v[98:99], v[118:119]
	v_pk_fma_f32 v[120:121], v[148:149], v[100:101], v[120:121]
	v_pk_fma_f32 v[122:123], v[150:151], v[102:103], v[122:123]
	v_pk_fma_f32 v[116:117], v[152:153], v[104:105], v[116:117]
	v_pk_fma_f32 v[118:119], v[154:155], v[106:107], v[118:119]
	v_pk_fma_f32 v[120:121], v[156:157], v[108:109], v[120:121]
	v_pk_fma_f32 v[122:123], v[158:159], v[110:111], v[122:123]
	v_pk_add_f32 v[116:117], v[116:117], v[118:119]
	v_pk_add_f32 v[120:121], v[120:121], v[122:123]
	v_pk_add_f32 v[116:117], v[116:117], v[120:121]
	v_add_f32_e32 v126, v116, v117
	v_lshl_add_u32 v7, v22, 7, v1
	v_lshl_add_u32 v8, v22, 6, v125
	v_add_f32_dpp v126, v126, v126 quad_perm:[1,0,3,2] row_mask:0xf bank_mask:0xf
	global_load_dwordx4 v[196:199], v7, s[48:49] sc1
	s_nop 0
	v_add_f32_dpp v126, v126, v126 quad_perm:[2,3,0,1] row_mask:0xf bank_mask:0xf
	global_load_dwordx2 v[200:201], v8, s[48:49] sc1
	s_nop 0
	v_add_f32_dpp v126, v126, v126 row_half_mirror row_mask:0xf bank_mask:0xf
	v_cndmask_b32_e64 v12, v12, v126, s[72:73]
	s_waitcnt vmcnt(45)
	v_cvt_scalef32_pk32_f32_fp6 v[128:159], v[202:207], 1.0
	v_pk_mul_f32 v[116:117], v[128:129], v[80:81]
	v_pk_mul_f32 v[118:119], v[130:131], v[82:83]
	v_pk_mul_f32 v[120:121], v[132:133], v[84:85]
	v_pk_mul_f32 v[122:123], v[134:135], v[86:87]
	v_pk_fma_f32 v[116:117], v[136:137], v[88:89], v[116:117]
	v_pk_fma_f32 v[118:119], v[138:139], v[90:91], v[118:119]
	v_pk_fma_f32 v[120:121], v[140:141], v[92:93], v[120:121]
	v_pk_fma_f32 v[122:123], v[142:143], v[94:95], v[122:123]
	v_pk_fma_f32 v[116:117], v[144:145], v[96:97], v[116:117]
	v_pk_fma_f32 v[118:119], v[146:147], v[98:99], v[118:119]
	v_pk_fma_f32 v[120:121], v[148:149], v[100:101], v[120:121]
	v_pk_fma_f32 v[122:123], v[150:151], v[102:103], v[122:123]
	v_pk_fma_f32 v[116:117], v[152:153], v[104:105], v[116:117]
	v_pk_fma_f32 v[118:119], v[154:155], v[106:107], v[118:119]
	v_pk_fma_f32 v[120:121], v[156:157], v[108:109], v[120:121]
	v_pk_fma_f32 v[122:123], v[158:159], v[110:111], v[122:123]
	v_pk_add_f32 v[116:117], v[116:117], v[118:119]
	v_pk_add_f32 v[120:121], v[120:121], v[122:123]
	v_pk_add_f32 v[116:117], v[116:117], v[120:121]
	v_add_f32_e32 v126, v116, v117
	v_lshl_add_u32 v7, v23, 7, v1
	v_lshl_add_u32 v8, v23, 6, v125
	v_add_f32_dpp v126, v126, v126 quad_perm:[1,0,3,2] row_mask:0xf bank_mask:0xf
	global_load_dwordx4 v[202:205], v7, s[48:49] sc1
	s_nop 0
	v_add_f32_dpp v126, v126, v126 quad_perm:[2,3,0,1] row_mask:0xf bank_mask:0xf
	global_load_dwordx2 v[206:207], v8, s[48:49] sc1
	s_nop 0
	v_add_f32_dpp v126, v126, v126 row_half_mirror row_mask:0xf bank_mask:0xf
	v_cndmask_b32_e64 v12, v12, v126, s[74:75]
	s_waitcnt vmcnt(45)
	v_cvt_scalef32_pk32_f32_fp6 v[128:159], v[208:213], 1.0
	v_pk_mul_f32 v[116:117], v[128:129], v[80:81]
	v_pk_mul_f32 v[118:119], v[130:131], v[82:83]
	v_pk_mul_f32 v[120:121], v[132:133], v[84:85]
	v_pk_mul_f32 v[122:123], v[134:135], v[86:87]
	v_pk_fma_f32 v[116:117], v[136:137], v[88:89], v[116:117]
	v_pk_fma_f32 v[118:119], v[138:139], v[90:91], v[118:119]
	v_pk_fma_f32 v[120:121], v[140:141], v[92:93], v[120:121]
	v_pk_fma_f32 v[122:123], v[142:143], v[94:95], v[122:123]
	v_pk_fma_f32 v[116:117], v[144:145], v[96:97], v[116:117]
	v_pk_fma_f32 v[118:119], v[146:147], v[98:99], v[118:119]
	v_pk_fma_f32 v[120:121], v[148:149], v[100:101], v[120:121]
	v_pk_fma_f32 v[122:123], v[150:151], v[102:103], v[122:123]
	v_pk_fma_f32 v[116:117], v[152:153], v[104:105], v[116:117]
	v_pk_fma_f32 v[118:119], v[154:155], v[106:107], v[118:119]
	v_pk_fma_f32 v[120:121], v[156:157], v[108:109], v[120:121]
	v_pk_fma_f32 v[122:123], v[158:159], v[110:111], v[122:123]
	v_pk_add_f32 v[116:117], v[116:117], v[118:119]
	v_pk_add_f32 v[120:121], v[120:121], v[122:123]
	v_pk_add_f32 v[116:117], v[116:117], v[120:121]
	v_add_f32_e32 v126, v116, v117
	v_lshl_add_u32 v7, v24, 7, v1
	v_lshl_add_u32 v8, v24, 6, v125
	v_add_f32_dpp v126, v126, v126 quad_perm:[1,0,3,2] row_mask:0xf bank_mask:0xf
	global_load_dwordx4 v[208:211], v7, s[48:49] sc1
	s_nop 0
	v_add_f32_dpp v126, v126, v126 quad_perm:[2,3,0,1] row_mask:0xf bank_mask:0xf
	global_load_dwordx2 v[212:213], v8, s[48:49] sc1
	s_nop 0
	v_add_f32_dpp v126, v126, v126 row_half_mirror row_mask:0xf bank_mask:0xf
	v_cndmask_b32_e64 v15, v15, v126, s[60:61]
	s_waitcnt vmcnt(45)
	v_cvt_scalef32_pk32_f32_fp6 v[128:159], v[214:219], 1.0
	v_pk_mul_f32 v[116:117], v[128:129], v[80:81]
	v_pk_mul_f32 v[118:119], v[130:131], v[82:83]
	v_pk_mul_f32 v[120:121], v[132:133], v[84:85]
	v_pk_mul_f32 v[122:123], v[134:135], v[86:87]
	v_pk_fma_f32 v[116:117], v[136:137], v[88:89], v[116:117]
	v_pk_fma_f32 v[118:119], v[138:139], v[90:91], v[118:119]
	v_pk_fma_f32 v[120:121], v[140:141], v[92:93], v[120:121]
	v_pk_fma_f32 v[122:123], v[142:143], v[94:95], v[122:123]
	v_pk_fma_f32 v[116:117], v[144:145], v[96:97], v[116:117]
	v_pk_fma_f32 v[118:119], v[146:147], v[98:99], v[118:119]
	v_pk_fma_f32 v[120:121], v[148:149], v[100:101], v[120:121]
	v_pk_fma_f32 v[122:123], v[150:151], v[102:103], v[122:123]
	v_pk_fma_f32 v[116:117], v[152:153], v[104:105], v[116:117]
	v_pk_fma_f32 v[118:119], v[154:155], v[106:107], v[118:119]
	v_pk_fma_f32 v[120:121], v[156:157], v[108:109], v[120:121]
	v_pk_fma_f32 v[122:123], v[158:159], v[110:111], v[122:123]
	v_pk_add_f32 v[116:117], v[116:117], v[118:119]
	v_pk_add_f32 v[120:121], v[120:121], v[122:123]
	v_pk_add_f32 v[116:117], v[116:117], v[120:121]
	v_add_f32_e32 v126, v116, v117
	v_lshl_add_u32 v7, v25, 7, v1
	v_lshl_add_u32 v8, v25, 6, v125
	v_add_f32_dpp v126, v126, v126 quad_perm:[1,0,3,2] row_mask:0xf bank_mask:0xf
	global_load_dwordx4 v[214:217], v7, s[48:49] sc1
	s_nop 0
	v_add_f32_dpp v126, v126, v126 quad_perm:[2,3,0,1] row_mask:0xf bank_mask:0xf
	global_load_dwordx2 v[218:219], v8, s[48:49] sc1
	s_nop 0
	v_add_f32_dpp v126, v126, v126 row_half_mirror row_mask:0xf bank_mask:0xf
	v_cndmask_b32_e64 v15, v15, v126, s[62:63]
	s_waitcnt vmcnt(45)
	v_cvt_scalef32_pk32_f32_fp6 v[128:159], v[220:225], 1.0
	v_pk_mul_f32 v[116:117], v[128:129], v[80:81]
	v_pk_mul_f32 v[118:119], v[130:131], v[82:83]
	v_pk_mul_f32 v[120:121], v[132:133], v[84:85]
	v_pk_mul_f32 v[122:123], v[134:135], v[86:87]
	v_pk_fma_f32 v[116:117], v[136:137], v[88:89], v[116:117]
	v_pk_fma_f32 v[118:119], v[138:139], v[90:91], v[118:119]
	v_pk_fma_f32 v[120:121], v[140:141], v[92:93], v[120:121]
	v_pk_fma_f32 v[122:123], v[142:143], v[94:95], v[122:123]
	v_pk_fma_f32 v[116:117], v[144:145], v[96:97], v[116:117]
	v_pk_fma_f32 v[118:119], v[146:147], v[98:99], v[118:119]
	v_pk_fma_f32 v[120:121], v[148:149], v[100:101], v[120:121]
	v_pk_fma_f32 v[122:123], v[150:151], v[102:103], v[122:123]
	v_pk_fma_f32 v[116:117], v[152:153], v[104:105], v[116:117]
	v_pk_fma_f32 v[118:119], v[154:155], v[106:107], v[118:119]
	v_pk_fma_f32 v[120:121], v[156:157], v[108:109], v[120:121]
	v_pk_fma_f32 v[122:123], v[158:159], v[110:111], v[122:123]
	v_pk_add_f32 v[116:117], v[116:117], v[118:119]
	v_pk_add_f32 v[120:121], v[120:121], v[122:123]
	v_pk_add_f32 v[116:117], v[116:117], v[120:121]
	v_add_f32_e32 v126, v116, v117
	v_lshl_add_u32 v7, v26, 7, v1
	v_lshl_add_u32 v8, v26, 6, v125
	v_add_f32_dpp v126, v126, v126 quad_perm:[1,0,3,2] row_mask:0xf bank_mask:0xf
	global_load_dwordx4 v[220:223], v7, s[48:49] sc1
	s_nop 0
	v_add_f32_dpp v126, v126, v126 quad_perm:[2,3,0,1] row_mask:0xf bank_mask:0xf
	global_load_dwordx2 v[224:225], v8, s[48:49] sc1
	s_nop 0
	v_add_f32_dpp v126, v126, v126 row_half_mirror row_mask:0xf bank_mask:0xf
	v_cndmask_b32_e64 v15, v15, v126, s[64:65]
	s_waitcnt vmcnt(45)
	v_cvt_scalef32_pk32_f32_fp6 v[128:159], v[226:231], 1.0
	v_pk_mul_f32 v[116:117], v[128:129], v[80:81]
	v_pk_mul_f32 v[118:119], v[130:131], v[82:83]
	v_pk_mul_f32 v[120:121], v[132:133], v[84:85]
	v_pk_mul_f32 v[122:123], v[134:135], v[86:87]
	v_pk_fma_f32 v[116:117], v[136:137], v[88:89], v[116:117]
	v_pk_fma_f32 v[118:119], v[138:139], v[90:91], v[118:119]
	v_pk_fma_f32 v[120:121], v[140:141], v[92:93], v[120:121]
	v_pk_fma_f32 v[122:123], v[142:143], v[94:95], v[122:123]
	v_pk_fma_f32 v[116:117], v[144:145], v[96:97], v[116:117]
	v_pk_fma_f32 v[118:119], v[146:147], v[98:99], v[118:119]
	v_pk_fma_f32 v[120:121], v[148:149], v[100:101], v[120:121]
	v_pk_fma_f32 v[122:123], v[150:151], v[102:103], v[122:123]
	v_pk_fma_f32 v[116:117], v[152:153], v[104:105], v[116:117]
	v_pk_fma_f32 v[118:119], v[154:155], v[106:107], v[118:119]
	v_pk_fma_f32 v[120:121], v[156:157], v[108:109], v[120:121]
	v_pk_fma_f32 v[122:123], v[158:159], v[110:111], v[122:123]
	v_pk_add_f32 v[116:117], v[116:117], v[118:119]
	v_pk_add_f32 v[120:121], v[120:121], v[122:123]
	v_pk_add_f32 v[116:117], v[116:117], v[120:121]
	v_add_f32_e32 v126, v116, v117
	v_lshl_add_u32 v7, v27, 7, v1
	v_lshl_add_u32 v8, v27, 6, v125
	v_add_f32_dpp v126, v126, v126 quad_perm:[1,0,3,2] row_mask:0xf bank_mask:0xf
	global_load_dwordx4 v[226:229], v7, s[48:49] sc1
	s_nop 0
	v_add_f32_dpp v126, v126, v126 quad_perm:[2,3,0,1] row_mask:0xf bank_mask:0xf
	global_load_dwordx2 v[230:231], v8, s[48:49] sc1
	s_nop 0
	v_add_f32_dpp v126, v126, v126 row_half_mirror row_mask:0xf bank_mask:0xf
	v_cndmask_b32_e64 v15, v15, v126, s[66:67]
	s_waitcnt vmcnt(45)
	v_cvt_scalef32_pk32_f32_fp6 v[128:159], v[232:237], 1.0
	v_pk_mul_f32 v[116:117], v[128:129], v[80:81]
	v_pk_mul_f32 v[118:119], v[130:131], v[82:83]
	v_pk_mul_f32 v[120:121], v[132:133], v[84:85]
	v_pk_mul_f32 v[122:123], v[134:135], v[86:87]
	v_pk_fma_f32 v[116:117], v[136:137], v[88:89], v[116:117]
	v_pk_fma_f32 v[118:119], v[138:139], v[90:91], v[118:119]
	v_pk_fma_f32 v[120:121], v[140:141], v[92:93], v[120:121]
	v_pk_fma_f32 v[122:123], v[142:143], v[94:95], v[122:123]
	v_pk_fma_f32 v[116:117], v[144:145], v[96:97], v[116:117]
	v_pk_fma_f32 v[118:119], v[146:147], v[98:99], v[118:119]
	v_pk_fma_f32 v[120:121], v[148:149], v[100:101], v[120:121]
	v_pk_fma_f32 v[122:123], v[150:151], v[102:103], v[122:123]
	v_pk_fma_f32 v[116:117], v[152:153], v[104:105], v[116:117]
	v_pk_fma_f32 v[118:119], v[154:155], v[106:107], v[118:119]
	v_pk_fma_f32 v[120:121], v[156:157], v[108:109], v[120:121]
	v_pk_fma_f32 v[122:123], v[158:159], v[110:111], v[122:123]
	v_pk_add_f32 v[116:117], v[116:117], v[118:119]
	v_pk_add_f32 v[120:121], v[120:121], v[122:123]
	v_pk_add_f32 v[116:117], v[116:117], v[120:121]
	v_add_f32_e32 v126, v116, v117
	v_lshl_add_u32 v7, v28, 7, v1
	v_lshl_add_u32 v8, v28, 6, v125
	v_add_f32_dpp v126, v126, v126 quad_perm:[1,0,3,2] row_mask:0xf bank_mask:0xf
	global_load_dwordx4 v[232:235], v7, s[48:49] sc1
	s_nop 0
	v_add_f32_dpp v126, v126, v126 quad_perm:[2,3,0,1] row_mask:0xf bank_mask:0xf
	global_load_dwordx2 v[236:237], v8, s[48:49] sc1
	s_nop 0
	v_add_f32_dpp v126, v126, v126 row_half_mirror row_mask:0xf bank_mask:0xf
	v_cndmask_b32_e64 v15, v15, v126, s[68:69]
	s_waitcnt vmcnt(45)
	v_cvt_scalef32_pk32_f32_fp6 v[128:159], v[238:243], 1.0
	v_pk_mul_f32 v[116:117], v[128:129], v[80:81]
	v_pk_mul_f32 v[118:119], v[130:131], v[82:83]
	v_pk_mul_f32 v[120:121], v[132:133], v[84:85]
	v_pk_mul_f32 v[122:123], v[134:135], v[86:87]
	v_pk_fma_f32 v[116:117], v[136:137], v[88:89], v[116:117]
	v_pk_fma_f32 v[118:119], v[138:139], v[90:91], v[118:119]
	v_pk_fma_f32 v[120:121], v[140:141], v[92:93], v[120:121]
	v_pk_fma_f32 v[122:123], v[142:143], v[94:95], v[122:123]
	v_pk_fma_f32 v[116:117], v[144:145], v[96:97], v[116:117]
	v_pk_fma_f32 v[118:119], v[146:147], v[98:99], v[118:119]
	v_pk_fma_f32 v[120:121], v[148:149], v[100:101], v[120:121]
	v_pk_fma_f32 v[122:123], v[150:151], v[102:103], v[122:123]
	v_pk_fma_f32 v[116:117], v[152:153], v[104:105], v[116:117]
	v_pk_fma_f32 v[118:119], v[154:155], v[106:107], v[118:119]
	v_pk_fma_f32 v[120:121], v[156:157], v[108:109], v[120:121]
	v_pk_fma_f32 v[122:123], v[158:159], v[110:111], v[122:123]
	v_pk_add_f32 v[116:117], v[116:117], v[118:119]
	v_pk_add_f32 v[120:121], v[120:121], v[122:123]
	v_pk_add_f32 v[116:117], v[116:117], v[120:121]
	v_add_f32_e32 v126, v116, v117
	v_lshl_add_u32 v7, v29, 7, v1
	v_lshl_add_u32 v8, v29, 6, v125
	v_add_f32_dpp v126, v126, v126 quad_perm:[1,0,3,2] row_mask:0xf bank_mask:0xf
	global_load_dwordx4 v[238:241], v7, s[48:49] sc1
	s_nop 0
	v_add_f32_dpp v126, v126, v126 quad_perm:[2,3,0,1] row_mask:0xf bank_mask:0xf
	global_load_dwordx2 v[242:243], v8, s[48:49] sc1
	s_nop 0
	v_add_f32_dpp v126, v126, v126 row_half_mirror row_mask:0xf bank_mask:0xf
	v_cndmask_b32_e64 v15, v15, v126, s[70:71]
	s_waitcnt vmcnt(45)
	v_cvt_scalef32_pk32_f32_fp6 v[128:159], v[244:249], 1.0
	v_pk_mul_f32 v[116:117], v[128:129], v[80:81]
	v_pk_mul_f32 v[118:119], v[130:131], v[82:83]
	v_pk_mul_f32 v[120:121], v[132:133], v[84:85]
	v_pk_mul_f32 v[122:123], v[134:135], v[86:87]
	v_pk_fma_f32 v[116:117], v[136:137], v[88:89], v[116:117]
	v_pk_fma_f32 v[118:119], v[138:139], v[90:91], v[118:119]
	v_pk_fma_f32 v[120:121], v[140:141], v[92:93], v[120:121]
	v_pk_fma_f32 v[122:123], v[142:143], v[94:95], v[122:123]
	v_pk_fma_f32 v[116:117], v[144:145], v[96:97], v[116:117]
	v_pk_fma_f32 v[118:119], v[146:147], v[98:99], v[118:119]
	v_pk_fma_f32 v[120:121], v[148:149], v[100:101], v[120:121]
	v_pk_fma_f32 v[122:123], v[150:151], v[102:103], v[122:123]
	v_pk_fma_f32 v[116:117], v[152:153], v[104:105], v[116:117]
	v_pk_fma_f32 v[118:119], v[154:155], v[106:107], v[118:119]
	v_pk_fma_f32 v[120:121], v[156:157], v[108:109], v[120:121]
	v_pk_fma_f32 v[122:123], v[158:159], v[110:111], v[122:123]
	v_pk_add_f32 v[116:117], v[116:117], v[118:119]
	v_pk_add_f32 v[120:121], v[120:121], v[122:123]
	v_pk_add_f32 v[116:117], v[116:117], v[120:121]
	v_add_f32_e32 v126, v116, v117
	v_lshl_add_u32 v7, v30, 7, v1
	v_lshl_add_u32 v8, v30, 6, v125
	v_add_f32_dpp v126, v126, v126 quad_perm:[1,0,3,2] row_mask:0xf bank_mask:0xf
	global_load_dwordx4 v[244:247], v7, s[48:49] sc1
	s_nop 0
	v_add_f32_dpp v126, v126, v126 quad_perm:[2,3,0,1] row_mask:0xf bank_mask:0xf
	global_load_dwordx2 v[248:249], v8, s[48:49] sc1
	s_nop 0
	v_add_f32_dpp v126, v126, v126 row_half_mirror row_mask:0xf bank_mask:0xf
	v_cndmask_b32_e64 v15, v15, v126, s[72:73]
	s_waitcnt vmcnt(45)
	v_cvt_scalef32_pk32_f32_fp6 v[128:159], v[250:255], 1.0
	v_pk_mul_f32 v[116:117], v[128:129], v[80:81]
	v_pk_mul_f32 v[118:119], v[130:131], v[82:83]
	v_pk_mul_f32 v[120:121], v[132:133], v[84:85]
	v_pk_mul_f32 v[122:123], v[134:135], v[86:87]
	v_pk_fma_f32 v[116:117], v[136:137], v[88:89], v[116:117]
	v_pk_fma_f32 v[118:119], v[138:139], v[90:91], v[118:119]
	v_pk_fma_f32 v[120:121], v[140:141], v[92:93], v[120:121]
	v_pk_fma_f32 v[122:123], v[142:143], v[94:95], v[122:123]
	v_pk_fma_f32 v[116:117], v[144:145], v[96:97], v[116:117]
	v_pk_fma_f32 v[118:119], v[146:147], v[98:99], v[118:119]
	v_pk_fma_f32 v[120:121], v[148:149], v[100:101], v[120:121]
	v_pk_fma_f32 v[122:123], v[150:151], v[102:103], v[122:123]
	v_pk_fma_f32 v[116:117], v[152:153], v[104:105], v[116:117]
	v_pk_fma_f32 v[118:119], v[154:155], v[106:107], v[118:119]
	v_pk_fma_f32 v[120:121], v[156:157], v[108:109], v[120:121]
	v_pk_fma_f32 v[122:123], v[158:159], v[110:111], v[122:123]
	v_pk_add_f32 v[116:117], v[116:117], v[118:119]
	v_pk_add_f32 v[120:121], v[120:121], v[122:123]
	v_pk_add_f32 v[116:117], v[116:117], v[120:121]
	v_add_f32_e32 v126, v116, v117
	v_lshl_add_u32 v7, v31, 7, v1
	v_lshl_add_u32 v8, v31, 6, v125
	v_add_f32_dpp v126, v126, v126 quad_perm:[1,0,3,2] row_mask:0xf bank_mask:0xf
	global_load_dwordx4 v[250:253], v7, s[48:49] sc1
	s_nop 0
	v_add_f32_dpp v126, v126, v126 quad_perm:[2,3,0,1] row_mask:0xf bank_mask:0xf
	global_load_dwordx2 v[254:255], v8, s[48:49] sc1
	s_nop 0
	v_add_f32_dpp v126, v126, v126 row_half_mirror row_mask:0xf bank_mask:0xf
	v_cndmask_b32_e64 v15, v15, v126, s[74:75]
	v_mul_f32_e32 v12, v12, v127
	v_mul_f32_e32 v15, v15, v127
	global_store_dword v9, v12, s[44:45]
	global_store_dword v9, v15, s[44:45] offset:32
	s_add_u32 s28, s28, 1
	s_cmp_lt_u32 s28, 128
	s_cbranch_scc1 .Lpa_tokloop
	s_waitcnt vmcnt(0)
	s_waitcnt vmcnt(0) lgkmcnt(0)
	s_barrier
	s_cmp_lg_u32 s21, 0
	s_cbranch_scc1 .Lpb_skip_g
	s_mov_b64 exec, 1
	v_mov_b32_e32 v10, 0x12000
	ds_read_b32 v12, v10
	ds_read_b32 v13, v10 offset:4
	s_getreg_b32 s44, hwreg(HW_REG_XCC_ID, 0, 4)
	s_and_b32 s44, s44, 15
	s_lshl_b32 s44, s44, 2
	s_waitcnt lgkmcnt(0)
	v_readfirstlane_b32 s45, v12
	v_readfirstlane_b32 s46, v13
	v_mov_b32_e32 v10, s44
	v_mov_b32_e32 v11, 1
	global_atomic_add v12, v10, v11, s[14:15] offset:384 sc0
	s_waitcnt vmcnt(0)
	v_readfirstlane_b32 s47, v12
	s_nop 3
	s_add_u32 s47, s47, 1
	s_cmp_lg_u32 s47, s45
	v_mov_b32_e32 v10, 0
	s_cbranch_scc1 .Lpb_notlast_g
	buffer_wbl2 sc1
	s_waitcnt vmcnt(0)
	global_atomic_add v10, v11, s[14:15] offset:448
	s_waitcnt vmcnt(0)

.Lpb_skip_a:
	s_barrier
	v_and_b32_e32 v10, 7, v0
	v_lshlrev_b32_e32 v10, 3, v10
	v_add_u32_e32 v10, 0x200000, v10
	s_mov_b32 s28, 0
	s_add_u32 s40, s28, 0
	s_min_u32 s40, s40, 127
	s_lshl_b32 s40, s40, 8
	s_add_u32 s40, s40, s24
	s_lshl_b32 s29, s40, 9
	s_add_u32 s30, s4, s29
	s_addc_u32 s31, s5, 0
	global_load_dwordx4 v[16:19], v2, s[30:31] offset:0
	global_load_dwordx4 v[20:23], v2, s[30:31] offset:16
	global_load_dwordx4 v[24:27], v2, s[30:31] offset:32
	global_load_dwordx4 v[28:31], v2, s[30:31] offset:48
	s_add_u32 s40, s28, 0
	s_min_u32 s40, s40, 127
	s_lshl_b32 s40, s40, 8
	s_add_u32 s40, s40, s24
	s_lshl_b32 s29, s40, 9
	s_add_u32 s32, s6, s29
	s_addc_u32 s33, s7, 0
	global_load_dwordx4 v[48:51], v2, s[32:33] offset:0
	global_load_dwordx4 v[52:55], v2, s[32:33] offset:16
	global_load_dwordx4 v[56:59], v2, s[32:33] offset:32
	global_load_dwordx4 v[60:63], v2, s[32:33] offset:48
	s_add_u32 s40, s28, 1
	s_min_u32 s40, s40, 127
	s_lshl_b32 s40, s40, 8
	s_add_u32 s40, s40, s24
	s_lshl_b32 s29, s40, 9
	s_add_u32 s30, s4, s29
	s_addc_u32 s31, s5, 0
	global_load_dwordx4 v[32:35], v2, s[30:31] offset:0
	global_load_dwordx4 v[36:39], v2, s[30:31] offset:16
	global_load_dwordx4 v[40:43], v2, s[30:31] offset:32
	global_load_dwordx4 v[44:47], v2, s[30:31] offset:48
	s_waitcnt vmcnt(0)
	v_lshl_add_u32 v7, v16, 7, v1
	v_lshl_add_u32 v8, v16, 6, v10
	global_load_dwordx4 v[160:163], v7, s[26:27] sc1
	global_load_dwordx2 v[164:165], v8, s[26:27] sc1
	v_lshl_add_u32 v7, v17, 7, v1
	v_lshl_add_u32 v8, v17, 6, v10
	global_load_dwordx4 v[166:169], v7, s[26:27] sc1
	global_load_dwordx2 v[170:171], v8, s[26:27] sc1
	v_lshl_add_u32 v7, v18, 7, v1
	v_lshl_add_u32 v8, v18, 6, v10
	global_load_dwordx4 v[172:175], v7, s[26:27] sc1
	global_load_dwordx2 v[176:177], v8, s[26:27] sc1
	v_lshl_add_u32 v7, v19, 7, v1
	v_lshl_add_u32 v8, v19, 6, v10
	global_load_dwordx4 v[178:181], v7, s[26:27] sc1
	global_load_dwordx2 v[182:183], v8, s[26:27] sc1
	v_lshl_add_u32 v7, v20, 7, v1
	v_lshl_add_u32 v8, v20, 6, v10
	global_load_dwordx4 v[184:187], v7, s[26:27] sc1
	global_load_dwordx2 v[188:189], v8, s[26:27] sc1
	v_lshl_add_u32 v7, v21, 7, v1
	v_lshl_add_u32 v8, v21, 6, v10
	global_load_dwordx4 v[190:193], v7, s[26:27] sc1
	global_load_dwordx2 v[194:195], v8, s[26:27] sc1
	v_lshl_add_u32 v7, v22, 7, v1
	v_lshl_add_u32 v8, v22, 6, v10
	global_load_dwordx4 v[196:199], v7, s[26:27] sc1
	global_load_dwordx2 v[200:201], v8, s[26:27] sc1
	v_lshl_add_u32 v7, v23, 7, v1
	v_lshl_add_u32 v8, v23, 6, v10
	global_load_dwordx4 v[202:205], v7, s[26:27] sc1
	global_load_dwordx2 v[206:207], v8, s[26:27] sc1
	v_lshl_add_u32 v7, v24, 7, v1
	v_lshl_add_u32 v8, v24, 6, v10
	global_load_dwordx4 v[208:211], v7, s[26:27] sc1
	global_load_dwordx2 v[212:213], v8, s[26:27] sc1
	v_lshl_add_u32 v7, v25, 7, v1
	v_lshl_add_u32 v8, v25, 6, v10
	global_load_dwordx4 v[214:217], v7, s[26:27] sc1
	global_load_dwordx2 v[218:219], v8, s[26:27] sc1
	v_lshl_add_u32 v7, v26, 7, v1
	v_lshl_add_u32 v8, v26, 6, v10
	global_load_dwordx4 v[220:223], v7, s[26:27] sc1
	global_load_dwordx2 v[224:225], v8, s[26:27] sc1
	v_lshl_add_u32 v7, v27, 7, v1
	v_lshl_add_u32 v8, v27, 6, v10
	global_load_dwordx4 v[226:229], v7, s[26:27] sc1
	global_load_dwordx2 v[230:231], v8, s[26:27] sc1
	v_lshl_add_u32 v7, v28, 7, v1
	v_lshl_add_u32 v8, v28, 6, v10
	global_load_dwordx4 v[232:235], v7, s[26:27] sc1
	global_load_dwordx2 v[236:237], v8, s[26:27] sc1
	v_lshl_add_u32 v7, v29, 7, v1
	v_lshl_add_u32 v8, v29, 6, v10
	global_load_dwordx4 v[238:241], v7, s[26:27] sc1
	global_load_dwordx2 v[242:243], v8, s[26:27] sc1
	v_lshl_add_u32 v7, v30, 7, v1
	v_lshl_add_u32 v8, v30, 6, v10
	global_load_dwordx4 v[244:247], v7, s[26:27] sc1
	global_load_dwordx2 v[248:249], v8, s[26:27] sc1
	v_lshl_add_u32 v7, v31, 7, v1
	v_lshl_add_u32 v8, v31, 6, v10
	global_load_dwordx4 v[250:253], v7, s[26:27] sc1
	global_load_dwordx2 v[254:255], v8, s[26:27] sc1
	global_store_dword v3, v3, s[14:15] offset:480
	global_store_dword v3, v3, s[14:15] offset:484
.Lpb_tokloop:
	s_add_u32 s40, s28, 0
	s_min_u32 s40, s40, 127
	s_lshl_b32 s40, s40, 8
	s_add_u32 s40, s40, s24
	s_lshl_b32 s29, s40, 13
	s_add_u32 s34, s10, s29
	s_addc_u32 s35, s11, 0
	global_load_dwordx4 v[80:83], v6, s[34:35]
	s_lshl_b32 s29, s40, 5
	s_add_u32 s29, s29, s43
	s_add_u32 s38, s12, s29
	s_addc_u32 s39, s13, 0
	s_add_u32 s40, s28, 2
	s_min_u32 s40, s40, 127
	s_lshl_b32 s40, s40, 8
	s_add_u32 s40, s40, s24
	s_lshl_b32 s29, s40, 9
	s_add_u32 s30, s4, s29
	s_addc_u32 s31, s5, 0
	global_load_dwordx4 v[16:19], v2, s[30:31] offset:0
	global_load_dwordx4 v[20:23], v2, s[30:31] offset:16
	global_load_dwordx4 v[24:27], v2, s[30:31] offset:32
	global_load_dwordx4 v[28:31], v2, s[30:31] offset:48
	s_add_u32 s40, s28, 1
	s_min_u32 s40, s40, 127
	s_lshl_b32 s40, s40, 8
	s_add_u32 s40, s40, s24
	s_lshl_b32 s29, s40, 9
	s_add_u32 s32, s6, s29
	s_addc_u32 s33, s7, 0
	global_load_dwordx4 v[64:67], v2, s[32:33] offset:0
	global_load_dwordx4 v[68:71], v2, s[32:33] offset:16
	global_load_dwordx4 v[72:75], v2, s[32:33] offset:32
	global_load_dwordx4 v[76:79], v2, s[32:33] offset:48
	s_waitcnt vmcnt(41)
	v_cvt_scalef32_pk32_f32_fp6 v[128:159], v[160:165], 1.0
	v_pk_mul_f32 v[84:85], v[128:129], v[48:49] op_sel_hi:[1,0]
	v_pk_mul_f32 v[86:87], v[130:131], v[48:49] op_sel_hi:[1,0]
	v_pk_mul_f32 v[88:89], v[132:133], v[48:49] op_sel_hi:[1,0]
	v_pk_mul_f32 v[90:91], v[134:135], v[48:49] op_sel_hi:[1,0]
	v_pk_mul_f32 v[92:93], v[136:137], v[48:49] op_sel_hi:[1,0]
	v_pk_mul_f32 v[94:95], v[138:139], v[48:49] op_sel_hi:[1,0]
	v_pk_mul_f32 v[96:97], v[140:141], v[48:49] op_sel_hi:[1,0]
	v_pk_mul_f32 v[98:99], v[142:143], v[48:49] op_sel_hi:[1,0]
	v_pk_mul_f32 v[100:101], v[144:145], v[48:49] op_sel_hi:[1,0]
	v_pk_mul_f32 v[102:103], v[146:147], v[48:49] op_sel_hi:[1,0]
	v_pk_mul_f32 v[104:105], v[148:149], v[48:49] op_sel_hi:[1,0]
	v_pk_mul_f32 v[106:107], v[150:151], v[48:49] op_sel_hi:[1,0]
	v_pk_mul_f32 v[108:109], v[152:153], v[48:49] op_sel_hi:[1,0]
	v_pk_mul_f32 v[110:111], v[154:155], v[48:49] op_sel_hi:[1,0]
	v_pk_mul_f32 v[112:113], v[156:157], v[48:49] op_sel_hi:[1,0]
	v_pk_mul_f32 v[114:115], v[158:159], v[48:49] op_sel_hi:[1,0]
	v_lshl_add_u32 v7, v32, 7, v1
	v_lshl_add_u32 v8, v32, 6, v10
	global_load_dwordx4 v[160:163], v7, s[26:27] sc1
	global_load_dwordx2 v[164:165], v8, s[26:27] sc1
	s_waitcnt vmcnt(41)
	v_cvt_scalef32_pk32_f32_fp6 v[128:159], v[166:171], 1.0
	v_pk_fma_f32 v[84:85], v[128:129], v[48:49], v[84:85] op_sel:[0,1,0] op_sel_hi:[1,1,1]
	v_pk_fma_f32 v[86:87], v[130:131], v[48:49], v[86:87] op_sel:[0,1,0] op_sel_hi:[1,1,1]
	v_pk_fma_f32 v[88:89], v[132:133], v[48:49], v[88:89] op_sel:[0,1,0] op_sel_hi:[1,1,1]
	v_pk_fma_f32 v[90:91], v[134:135], v[48:49], v[90:91] op_sel:[0,1,0] op_sel_hi:[1,1,1]
	v_pk_fma_f32 v[92:93], v[136:137], v[48:49], v[92:93] op_sel:[0,1,0] op_sel_hi:[1,1,1]
	v_pk_fma_f32 v[94:95], v[138:139], v[48:49], v[94:95] op_sel:[0,1,0] op_sel_hi:[1,1,1]
	v_pk_fma_f32 v[96:97], v[140:141], v[48:49], v[96:97] op_sel:[0,1,0] op_sel_hi:[1,1,1]
	v_pk_fma_f32 v[98:99], v[142:143], v[48:49], v[98:99] op_sel:[0,1,0] op_sel_hi:[1,1,1]
	v_pk_fma_f32 v[100:101], v[144:145], v[48:49], v[100:101] op_sel:[0,1,0] op_sel_hi:[1,1,1]
	v_pk_fma_f32 v[102:103], v[146:147], v[48:49], v[102:103] op_sel:[0,1,0] op_sel_hi:[1,1,1]
	v_pk_fma_f32 v[104:105], v[148:149], v[48:49], v[104:105] op_sel:[0,1,0] op_sel_hi:[1,1,1]
	v_pk_fma_f32 v[106:107], v[150:151], v[48:49], v[106:107] op_sel:[0,1,0] op_sel_hi:[1,1,1]
	v_pk_fma_f32 v[108:109], v[152:153], v[48:49], v[108:109] op_sel:[0,1,0] op_sel_hi:[1,1,1]
	v_pk_fma_f32 v[110:111], v[154:155], v[48:49], v[110:111] op_sel:[0,1,0] op_sel_hi:[1,1,1]
	v_pk_fma_f32 v[112:113], v[156:157], v[48:49], v[112:113] op_sel:[0,1,0] op_sel_hi:[1,1,1]
	v_pk_fma_f32 v[114:115], v[158:159], v[48:49], v[114:115] op_sel:[0,1,0] op_sel_hi:[1,1,1]
	v_lshl_add_u32 v7, v33, 7, v1
	v_lshl_add_u32 v8, v33, 6, v10
	global_load_dwordx4 v[166:169], v7, s[26:27] sc1
	global_load_dwordx2 v[170:171], v8, s[26:27] sc1
	s_waitcnt vmcnt(41)
	v_cvt_scalef32_pk32_f32_fp6 v[128:159], v[172:177], 1.0
	v_pk_fma_f32 v[84:85], v[128:129], v[50:51], v[84:85] op_sel_hi:[1,0,1]
	v_pk_fma_f32 v[86:87], v[130:131], v[50:51], v[86:87] op_sel_hi:[1,0,1]
	v_pk_fma_f32 v[88:89], v[132:133], v[50:51], v[88:89] op_sel_hi:[1,0,1]
	v_pk_fma_f32 v[90:91], v[134:135], v[50:51], v[90:91] op_sel_hi:[1,0,1]
	v_pk_fma_f32 v[92:93], v[136:137], v[50:51], v[92:93] op_sel_hi:[1,0,1]
	v_pk_fma_f32 v[94:95], v[138:139], v[50:51], v[94:95] op_sel_hi:[1,0,1]
	v_pk_fma_f32 v[96:97], v[140:141], v[50:51], v[96:97] op_sel_hi:[1,0,1]
	v_pk_fma_f32 v[98:99], v[142:143], v[50:51], v[98:99] op_sel_hi:[1,0,1]
	v_pk_fma_f32 v[100:101], v[144:145], v[50:51], v[100:101] op_sel_hi:[1,0,1]
	v_pk_fma_f32 v[102:103], v[146:147], v[50:51], v[102:103] op_sel_hi:[1,0,1]
	v_pk_fma_f32 v[104:105], v[148:149], v[50:51], v[104:105] op_sel_hi:[1,0,1]
	v_pk_fma_f32 v[106:107], v[150:151], v[50:51], v[106:107] op_sel_hi:[1,0,1]
	v_pk_fma_f32 v[108:109], v[152:153], v[50:51], v[108:109] op_sel_hi:[1,0,1]
	v_pk_fma_f32 v[110:111], v[154:155], v[50:51], v[110:111] op_sel_hi:[1,0,1]
	v_pk_fma_f32 v[112:113], v[156:157], v[50:51], v[112:113] op_sel_hi:[1,0,1]
	v_pk_fma_f32 v[114:115], v[158:159], v[50:51], v[114:115] op_sel_hi:[1,0,1]
	v_lshl_add_u32 v7, v34, 7, v1
	v_lshl_add_u32 v8, v34, 6, v10
	global_load_dwordx4 v[172:175], v7, s[26:27] sc1
	global_load_dwordx2 v[176:177], v8, s[26:27] sc1
	s_waitcnt vmcnt(41)
	v_cvt_scalef32_pk32_f32_fp6 v[128:159], v[178:183], 1.0
	v_pk_fma_f32 v[84:85], v[128:129], v[50:51], v[84:85] op_sel:[0,1,0] op_sel_hi:[1,1,1]
	v_pk_fma_f32 v[86:87], v[130:131], v[50:51], v[86:87] op_sel:[0,1,0] op_sel_hi:[1,1,1]
	v_pk_fma_f32 v[88:89], v[132:133], v[50:51], v[88:89] op_sel:[0,1,0] op_sel_hi:[1,1,1]
	v_pk_fma_f32 v[90:91], v[134:135], v[50:51], v[90:91] op_sel:[0,1,0] op_sel_hi:[1,1,1]
	v_pk_fma_f32 v[92:93], v[136:137], v[50:51], v[92:93] op_sel:[0,1,0] op_sel_hi:[1,1,1]
	v_pk_fma_f32 v[94:95], v[138:139], v[50:51], v[94:95] op_sel:[0,1,0] op_sel_hi:[1,1,1]
	v_pk_fma_f32 v[96:97], v[140:141], v[50:51], v[96:97] op_sel:[0,1,0] op_sel_hi:[1,1,1]
	v_pk_fma_f32 v[98:99], v[142:143], v[50:51], v[98:99] op_sel:[0,1,0] op_sel_hi:[1,1,1]
	v_pk_fma_f32 v[100:101], v[144:145], v[50:51], v[100:101] op_sel:[0,1,0] op_sel_hi:[1,1,1]
	v_pk_fma_f32 v[102:103], v[146:147], v[50:51], v[102:103] op_sel:[0,1,0] op_sel_hi:[1,1,1]
	v_pk_fma_f32 v[104:105], v[148:149], v[50:51], v[104:105] op_sel:[0,1,0] op_sel_hi:[1,1,1]
	v_pk_fma_f32 v[106:107], v[150:151], v[50:51], v[106:107] op_sel:[0,1,0] op_sel_hi:[1,1,1]
	v_pk_fma_f32 v[108:109], v[152:153], v[50:51], v[108:109] op_sel:[0,1,0] op_sel_hi:[1,1,1]
	v_pk_fma_f32 v[110:111], v[154:155], v[50:51], v[110:111] op_sel:[0,1,0] op_sel_hi:[1,1,1]
	v_pk_fma_f32 v[112:113], v[156:157], v[50:51], v[112:113] op_sel:[0,1,0] op_sel_hi:[1,1,1]
	v_pk_fma_f32 v[114:115], v[158:159], v[50:51], v[114:115] op_sel:[0,1,0] op_sel_hi:[1,1,1]
	v_lshl_add_u32 v7, v35, 7, v1
	v_lshl_add_u32 v8, v35, 6, v10
	global_load_dwordx4 v[178:181], v7, s[26:27] sc1
	global_load_dwordx2 v[182:183], v8, s[26:27] sc1
	s_waitcnt vmcnt(41)
	v_cvt_scalef32_pk32_f32_fp6 v[128:159], v[184:189], 1.0
	v_pk_fma_f32 v[84:85], v[128:129], v[52:53], v[84:85] op_sel_hi:[1,0,1]
	v_pk_fma_f32 v[86:87], v[130:131], v[52:53], v[86:87] op_sel_hi:[1,0,1]
	v_pk_fma_f32 v[88:89], v[132:133], v[52:53], v[88:89] op_sel_hi:[1,0,1]
	v_pk_fma_f32 v[90:91], v[134:135], v[52:53], v[90:91] op_sel_hi:[1,0,1]
	v_pk_fma_f32 v[92:93], v[136:137], v[52:53], v[92:93] op_sel_hi:[1,0,1]
	v_pk_fma_f32 v[94:95], v[138:139], v[52:53], v[94:95] op_sel_hi:[1,0,1]
	v_pk_fma_f32 v[96:97], v[140:141], v[52:53], v[96:97] op_sel_hi:[1,0,1]
	v_pk_fma_f32 v[98:99], v[142:143], v[52:53], v[98:99] op_sel_hi:[1,0,1]
	v_pk_fma_f32 v[100:101], v[144:145], v[52:53], v[100:101] op_sel_hi:[1,0,1]
	v_pk_fma_f32 v[102:103], v[146:147], v[52:53], v[102:103] op_sel_hi:[1,0,1]
	v_pk_fma_f32 v[104:105], v[148:149], v[52:53], v[104:105] op_sel_hi:[1,0,1]
	v_pk_fma_f32 v[106:107], v[150:151], v[52:53], v[106:107] op_sel_hi:[1,0,1]
	v_pk_fma_f32 v[108:109], v[152:153], v[52:53], v[108:109] op_sel_hi:[1,0,1]
	v_pk_fma_f32 v[110:111], v[154:155], v[52:53], v[110:111] op_sel_hi:[1,0,1]
	v_pk_fma_f32 v[112:113], v[156:157], v[52:53], v[112:113] op_sel_hi:[1,0,1]
	v_pk_fma_f32 v[114:115], v[158:159], v[52:53], v[114:115] op_sel_hi:[1,0,1]
	v_lshl_add_u32 v7, v36, 7, v1
	v_lshl_add_u32 v8, v36, 6, v10
	global_load_dwordx4 v[184:187], v7, s[26:27] sc1
	global_load_dwordx2 v[188:189], v8, s[26:27] sc1
	s_waitcnt vmcnt(41)
	v_cvt_scalef32_pk32_f32_fp6 v[128:159], v[190:195], 1.0
	v_pk_fma_f32 v[84:85], v[128:129], v[52:53], v[84:85] op_sel:[0,1,0] op_sel_hi:[1,1,1]
	v_pk_fma_f32 v[86:87], v[130:131], v[52:53], v[86:87] op_sel:[0,1,0] op_sel_hi:[1,1,1]
	v_pk_fma_f32 v[88:89], v[132:133], v[52:53], v[88:89] op_sel:[0,1,0] op_sel_hi:[1,1,1]
	v_pk_fma_f32 v[90:91], v[134:135], v[52:53], v[90:91] op_sel:[0,1,0] op_sel_hi:[1,1,1]
	v_pk_fma_f32 v[92:93], v[136:137], v[52:53], v[92:93] op_sel:[0,1,0] op_sel_hi:[1,1,1]
	v_pk_fma_f32 v[94:95], v[138:139], v[52:53], v[94:95] op_sel:[0,1,0] op_sel_hi:[1,1,1]
	v_pk_fma_f32 v[96:97], v[140:141], v[52:53], v[96:97] op_sel:[0,1,0] op_sel_hi:[1,1,1]
	v_pk_fma_f32 v[98:99], v[142:143], v[52:53], v[98:99] op_sel:[0,1,0] op_sel_hi:[1,1,1]
	v_pk_fma_f32 v[100:101], v[144:145], v[52:53], v[100:101] op_sel:[0,1,0] op_sel_hi:[1,1,1]
	v_pk_fma_f32 v[102:103], v[146:147], v[52:53], v[102:103] op_sel:[0,1,0] op_sel_hi:[1,1,1]
	v_pk_fma_f32 v[104:105], v[148:149], v[52:53], v[104:105] op_sel:[0,1,0] op_sel_hi:[1,1,1]
	v_pk_fma_f32 v[106:107], v[150:151], v[52:53], v[106:107] op_sel:[0,1,0] op_sel_hi:[1,1,1]
	v_pk_fma_f32 v[108:109], v[152:153], v[52:53], v[108:109] op_sel:[0,1,0] op_sel_hi:[1,1,1]
	v_pk_fma_f32 v[110:111], v[154:155], v[52:53], v[110:111] op_sel:[0,1,0] op_sel_hi:[1,1,1]
	v_pk_fma_f32 v[112:113], v[156:157], v[52:53], v[112:113] op_sel:[0,1,0] op_sel_hi:[1,1,1]
	v_pk_fma_f32 v[114:115], v[158:159], v[52:53], v[114:115] op_sel:[0,1,0] op_sel_hi:[1,1,1]
	v_lshl_add_u32 v7, v37, 7, v1
	v_lshl_add_u32 v8, v37, 6, v10
	global_load_dwordx4 v[190:193], v7, s[26:27] sc1
	global_load_dwordx2 v[194:195], v8, s[26:27] sc1
	s_waitcnt vmcnt(41)
	v_cvt_scalef32_pk32_f32_fp6 v[128:159], v[196:201], 1.0
	v_pk_fma_f32 v[84:85], v[128:129], v[54:55], v[84:85] op_sel_hi:[1,0,1]
	v_pk_fma_f32 v[86:87], v[130:131], v[54:55], v[86:87] op_sel_hi:[1,0,1]
	v_pk_fma_f32 v[88:89], v[132:133], v[54:55], v[88:89] op_sel_hi:[1,0,1]
	v_pk_fma_f32 v[90:91], v[134:135], v[54:55], v[90:91] op_sel_hi:[1,0,1]
	v_pk_fma_f32 v[92:93], v[136:137], v[54:55], v[92:93] op_sel_hi:[1,0,1]
	v_pk_fma_f32 v[94:95], v[138:139], v[54:55], v[94:95] op_sel_hi:[1,0,1]
	v_pk_fma_f32 v[96:97], v[140:141], v[54:55], v[96:97] op_sel_hi:[1,0,1]
	v_pk_fma_f32 v[98:99], v[142:143], v[54:55], v[98:99] op_sel_hi:[1,0,1]
	v_pk_fma_f32 v[100:101], v[144:145], v[54:55], v[100:101] op_sel_hi:[1,0,1]
	v_pk_fma_f32 v[102:103], v[146:147], v[54:55], v[102:103] op_sel_hi:[1,0,1]
	v_pk_fma_f32 v[104:105], v[148:149], v[54:55], v[104:105] op_sel_hi:[1,0,1]
	v_pk_fma_f32 v[106:107], v[150:151], v[54:55], v[106:107] op_sel_hi:[1,0,1]
	v_pk_fma_f32 v[108:109], v[152:153], v[54:55], v[108:109] op_sel_hi:[1,0,1]
	v_pk_fma_f32 v[110:111], v[154:155], v[54:55], v[110:111] op_sel_hi:[1,0,1]
	v_pk_fma_f32 v[112:113], v[156:157], v[54:55], v[112:113] op_sel_hi:[1,0,1]
	v_pk_fma_f32 v[114:115], v[158:159], v[54:55], v[114:115] op_sel_hi:[1,0,1]
	v_lshl_add_u32 v7, v38, 7, v1
	v_lshl_add_u32 v8, v38, 6, v10
	global_load_dwordx4 v[196:199], v7, s[26:27] sc1
	global_load_dwordx2 v[200:201], v8, s[26:27] sc1
	s_waitcnt vmcnt(41)
	v_cvt_scalef32_pk32_f32_fp6 v[128:159], v[202:207], 1.0
	v_pk_fma_f32 v[84:85], v[128:129], v[54:55], v[84:85] op_sel:[0,1,0] op_sel_hi:[1,1,1]
	v_pk_fma_f32 v[86:87], v[130:131], v[54:55], v[86:87] op_sel:[0,1,0] op_sel_hi:[1,1,1]
	v_pk_fma_f32 v[88:89], v[132:133], v[54:55], v[88:89] op_sel:[0,1,0] op_sel_hi:[1,1,1]
	v_pk_fma_f32 v[90:91], v[134:135], v[54:55], v[90:91] op_sel:[0,1,0] op_sel_hi:[1,1,1]
	v_pk_fma_f32 v[92:93], v[136:137], v[54:55], v[92:93] op_sel:[0,1,0] op_sel_hi:[1,1,1]
	v_pk_fma_f32 v[94:95], v[138:139], v[54:55], v[94:95] op_sel:[0,1,0] op_sel_hi:[1,1,1]
	v_pk_fma_f32 v[96:97], v[140:141], v[54:55], v[96:97] op_sel:[0,1,0] op_sel_hi:[1,1,1]
	v_pk_fma_f32 v[98:99], v[142:143], v[54:55], v[98:99] op_sel:[0,1,0] op_sel_hi:[1,1,1]
	v_pk_fma_f32 v[100:101], v[144:145], v[54:55], v[100:101] op_sel:[0,1,0] op_sel_hi:[1,1,1]
	v_pk_fma_f32 v[102:103], v[146:147], v[54:55], v[102:103] op_sel:[0,1,0] op_sel_hi:[1,1,1]
	v_pk_fma_f32 v[104:105], v[148:149], v[54:55], v[104:105] op_sel:[0,1,0] op_sel_hi:[1,1,1]
	v_pk_fma_f32 v[106:107], v[150:151], v[54:55], v[106:107] op_sel:[0,1,0] op_sel_hi:[1,1,1]
	v_pk_fma_f32 v[108:109], v[152:153], v[54:55], v[108:109] op_sel:[0,1,0] op_sel_hi:[1,1,1]
	v_pk_fma_f32 v[110:111], v[154:155], v[54:55], v[110:111] op_sel:[0,1,0] op_sel_hi:[1,1,1]
	v_pk_fma_f32 v[112:113], v[156:157], v[54:55], v[112:113] op_sel:[0,1,0] op_sel_hi:[1,1,1]
	v_pk_fma_f32 v[114:115], v[158:159], v[54:55], v[114:115] op_sel:[0,1,0] op_sel_hi:[1,1,1]
	v_lshl_add_u32 v7, v39, 7, v1
	v_lshl_add_u32 v8, v39, 6, v10
	global_load_dwordx4 v[202:205], v7, s[26:27] sc1
	global_load_dwordx2 v[206:207], v8, s[26:27] sc1
	s_waitcnt vmcnt(41)
	v_cvt_scalef32_pk32_f32_fp6 v[128:159], v[208:213], 1.0
	v_pk_fma_f32 v[84:85], v[128:129], v[56:57], v[84:85] op_sel_hi:[1,0,1]
	v_pk_fma_f32 v[86:87], v[130:131], v[56:57], v[86:87] op_sel_hi:[1,0,1]
	v_pk_fma_f32 v[88:89], v[132:133], v[56:57], v[88:89] op_sel_hi:[1,0,1]
	v_pk_fma_f32 v[90:91], v[134:135], v[56:57], v[90:91] op_sel_hi:[1,0,1]
	v_pk_fma_f32 v[92:93], v[136:137], v[56:57], v[92:93] op_sel_hi:[1,0,1]
	v_pk_fma_f32 v[94:95], v[138:139], v[56:57], v[94:95] op_sel_hi:[1,0,1]
	v_pk_fma_f32 v[96:97], v[140:141], v[56:57], v[96:97] op_sel_hi:[1,0,1]
	v_pk_fma_f32 v[98:99], v[142:143], v[56:57], v[98:99] op_sel_hi:[1,0,1]
	v_pk_fma_f32 v[100:101], v[144:145], v[56:57], v[100:101] op_sel_hi:[1,0,1]
	v_pk_fma_f32 v[102:103], v[146:147], v[56:57], v[102:103] op_sel_hi:[1,0,1]
	v_pk_fma_f32 v[104:105], v[148:149], v[56:57], v[104:105] op_sel_hi:[1,0,1]
	v_pk_fma_f32 v[106:107], v[150:151], v[56:57], v[106:107] op_sel_hi:[1,0,1]
	v_pk_fma_f32 v[108:109], v[152:153], v[56:57], v[108:109] op_sel_hi:[1,0,1]
	v_pk_fma_f32 v[110:111], v[154:155], v[56:57], v[110:111] op_sel_hi:[1,0,1]
	v_pk_fma_f32 v[112:113], v[156:157], v[56:57], v[112:113] op_sel_hi:[1,0,1]
	v_pk_fma_f32 v[114:115], v[158:159], v[56:57], v[114:115] op_sel_hi:[1,0,1]
	v_lshl_add_u32 v7, v40, 7, v1
	v_lshl_add_u32 v8, v40, 6, v10
	global_load_dwordx4 v[208:211], v7, s[26:27] sc1
	global_load_dwordx2 v[212:213], v8, s[26:27] sc1
	s_waitcnt vmcnt(41)
	v_cvt_scalef32_pk32_f32_fp6 v[128:159], v[214:219], 1.0
	v_pk_fma_f32 v[84:85], v[128:129], v[56:57], v[84:85] op_sel:[0,1,0] op_sel_hi:[1,1,1]
	v_pk_fma_f32 v[86:87], v[130:131], v[56:57], v[86:87] op_sel:[0,1,0] op_sel_hi:[1,1,1]
	v_pk_fma_f32 v[88:89], v[132:133], v[56:57], v[88:89] op_sel:[0,1,0] op_sel_hi:[1,1,1]
	v_pk_fma_f32 v[90:91], v[134:135], v[56:57], v[90:91] op_sel:[0,1,0] op_sel_hi:[1,1,1]
	v_pk_fma_f32 v[92:93], v[136:137], v[56:57], v[92:93] op_sel:[0,1,0] op_sel_hi:[1,1,1]
	v_pk_fma_f32 v[94:95], v[138:139], v[56:57], v[94:95] op_sel:[0,1,0] op_sel_hi:[1,1,1]
	v_pk_fma_f32 v[96:97], v[140:141], v[56:57], v[96:97] op_sel:[0,1,0] op_sel_hi:[1,1,1]
	v_pk_fma_f32 v[98:99], v[142:143], v[56:57], v[98:99] op_sel:[0,1,0] op_sel_hi:[1,1,1]
	v_pk_fma_f32 v[100:101], v[144:145], v[56:57], v[100:101] op_sel:[0,1,0] op_sel_hi:[1,1,1]
	v_pk_fma_f32 v[102:103], v[146:147], v[56:57], v[102:103] op_sel:[0,1,0] op_sel_hi:[1,1,1]
	v_pk_fma_f32 v[104:105], v[148:149], v[56:57], v[104:105] op_sel:[0,1,0] op_sel_hi:[1,1,1]
	v_pk_fma_f32 v[106:107], v[150:151], v[56:57], v[106:107] op_sel:[0,1,0] op_sel_hi:[1,1,1]
	v_pk_fma_f32 v[108:109], v[152:153], v[56:57], v[108:109] op_sel:[0,1,0] op_sel_hi:[1,1,1]
	v_pk_fma_f32 v[110:111], v[154:155], v[56:57], v[110:111] op_sel:[0,1,0] op_sel_hi:[1,1,1]
	v_pk_fma_f32 v[112:113], v[156:157], v[56:57], v[112:113] op_sel:[0,1,0] op_sel_hi:[1,1,1]
	v_pk_fma_f32 v[114:115], v[158:159], v[56:57], v[114:115] op_sel:[0,1,0] op_sel_hi:[1,1,1]
	v_lshl_add_u32 v7, v41, 7, v1
	v_lshl_add_u32 v8, v41, 6, v10
	global_load_dwordx4 v[214:217], v7, s[26:27] sc1
	global_load_dwordx2 v[218:219], v8, s[26:27] sc1
	s_waitcnt vmcnt(41)
	v_cvt_scalef32_pk32_f32_fp6 v[128:159], v[220:225], 1.0
	v_pk_fma_f32 v[84:85], v[128:129], v[58:59], v[84:85] op_sel_hi:[1,0,1]
	v_pk_fma_f32 v[86:87], v[130:131], v[58:59], v[86:87] op_sel_hi:[1,0,1]
	v_pk_fma_f32 v[88:89], v[132:133], v[58:59], v[88:89] op_sel_hi:[1,0,1]
	v_pk_fma_f32 v[90:91], v[134:135], v[58:59], v[90:91] op_sel_hi:[1,0,1]
	v_pk_fma_f32 v[92:93], v[136:137], v[58:59], v[92:93] op_sel_hi:[1,0,1]
	v_pk_fma_f32 v[94:95], v[138:139], v[58:59], v[94:95] op_sel_hi:[1,0,1]
	v_pk_fma_f32 v[96:97], v[140:141], v[58:59], v[96:97] op_sel_hi:[1,0,1]
	v_pk_fma_f32 v[98:99], v[142:143], v[58:59], v[98:99] op_sel_hi:[1,0,1]
	v_pk_fma_f32 v[100:101], v[144:145], v[58:59], v[100:101] op_sel_hi:[1,0,1]
	v_pk_fma_f32 v[102:103], v[146:147], v[58:59], v[102:103] op_sel_hi:[1,0,1]
	v_pk_fma_f32 v[104:105], v[148:149], v[58:59], v[104:105] op_sel_hi:[1,0,1]
	v_pk_fma_f32 v[106:107], v[150:151], v[58:59], v[106:107] op_sel_hi:[1,0,1]
	v_pk_fma_f32 v[108:109], v[152:153], v[58:59], v[108:109] op_sel_hi:[1,0,1]
	v_pk_fma_f32 v[110:111], v[154:155], v[58:59], v[110:111] op_sel_hi:[1,0,1]
	v_pk_fma_f32 v[112:113], v[156:157], v[58:59], v[112:113] op_sel_hi:[1,0,1]
	v_pk_fma_f32 v[114:115], v[158:159], v[58:59], v[114:115] op_sel_hi:[1,0,1]
	v_lshl_add_u32 v7, v42, 7, v1
	v_lshl_add_u32 v8, v42, 6, v10
	global_load_dwordx4 v[220:223], v7, s[26:27] sc1
	global_load_dwordx2 v[224:225], v8, s[26:27] sc1
	s_waitcnt vmcnt(41)
	v_cvt_scalef32_pk32_f32_fp6 v[128:159], v[226:231], 1.0
	v_pk_fma_f32 v[84:85], v[128:129], v[58:59], v[84:85] op_sel:[0,1,0] op_sel_hi:[1,1,1]
	v_pk_fma_f32 v[86:87], v[130:131], v[58:59], v[86:87] op_sel:[0,1,0] op_sel_hi:[1,1,1]
	v_pk_fma_f32 v[88:89], v[132:133], v[58:59], v[88:89] op_sel:[0,1,0] op_sel_hi:[1,1,1]
	v_pk_fma_f32 v[90:91], v[134:135], v[58:59], v[90:91] op_sel:[0,1,0] op_sel_hi:[1,1,1]
	v_pk_fma_f32 v[92:93], v[136:137], v[58:59], v[92:93] op_sel:[0,1,0] op_sel_hi:[1,1,1]
	v_pk_fma_f32 v[94:95], v[138:139], v[58:59], v[94:95] op_sel:[0,1,0] op_sel_hi:[1,1,1]
	v_pk_fma_f32 v[96:97], v[140:141], v[58:59], v[96:97] op_sel:[0,1,0] op_sel_hi:[1,1,1]
	v_pk_fma_f32 v[98:99], v[142:143], v[58:59], v[98:99] op_sel:[0,1,0] op_sel_hi:[1,1,1]
	v_pk_fma_f32 v[100:101], v[144:145], v[58:59], v[100:101] op_sel:[0,1,0] op_sel_hi:[1,1,1]
	v_pk_fma_f32 v[102:103], v[146:147], v[58:59], v[102:103] op_sel:[0,1,0] op_sel_hi:[1,1,1]
	v_pk_fma_f32 v[104:105], v[148:149], v[58:59], v[104:105] op_sel:[0,1,0] op_sel_hi:[1,1,1]
	v_pk_fma_f32 v[106:107], v[150:151], v[58:59], v[106:107] op_sel:[0,1,0] op_sel_hi:[1,1,1]
	v_pk_fma_f32 v[108:109], v[152:153], v[58:59], v[108:109] op_sel:[0,1,0] op_sel_hi:[1,1,1]
	v_pk_fma_f32 v[110:111], v[154:155], v[58:59], v[110:111] op_sel:[0,1,0] op_sel_hi:[1,1,1]
	v_pk_fma_f32 v[112:113], v[156:157], v[58:59], v[112:113] op_sel:[0,1,0] op_sel_hi:[1,1,1]
	v_pk_fma_f32 v[114:115], v[158:159], v[58:59], v[114:115] op_sel:[0,1,0] op_sel_hi:[1,1,1]
	v_lshl_add_u32 v7, v43, 7, v1
	v_lshl_add_u32 v8, v43, 6, v10
	global_load_dwordx4 v[226:229], v7, s[26:27] sc1
	global_load_dwordx2 v[230:231], v8, s[26:27] sc1
	s_waitcnt vmcnt(41)
	v_cvt_scalef32_pk32_f32_fp6 v[128:159], v[232:237], 1.0
	v_pk_fma_f32 v[84:85], v[128:129], v[60:61], v[84:85] op_sel_hi:[1,0,1]
	v_pk_fma_f32 v[86:87], v[130:131], v[60:61], v[86:87] op_sel_hi:[1,0,1]
	v_pk_fma_f32 v[88:89], v[132:133], v[60:61], v[88:89] op_sel_hi:[1,0,1]
	v_pk_fma_f32 v[90:91], v[134:135], v[60:61], v[90:91] op_sel_hi:[1,0,1]
	v_pk_fma_f32 v[92:93], v[136:137], v[60:61], v[92:93] op_sel_hi:[1,0,1]
	v_pk_fma_f32 v[94:95], v[138:139], v[60:61], v[94:95] op_sel_hi:[1,0,1]
	v_pk_fma_f32 v[96:97], v[140:141], v[60:61], v[96:97] op_sel_hi:[1,0,1]
	v_pk_fma_f32 v[98:99], v[142:143], v[60:61], v[98:99] op_sel_hi:[1,0,1]
	v_pk_fma_f32 v[100:101], v[144:145], v[60:61], v[100:101] op_sel_hi:[1,0,1]
	v_pk_fma_f32 v[102:103], v[146:147], v[60:61], v[102:103] op_sel_hi:[1,0,1]
	v_pk_fma_f32 v[104:105], v[148:149], v[60:61], v[104:105] op_sel_hi:[1,0,1]
	v_pk_fma_f32 v[106:107], v[150:151], v[60:61], v[106:107] op_sel_hi:[1,0,1]
	v_pk_fma_f32 v[108:109], v[152:153], v[60:61], v[108:109] op_sel_hi:[1,0,1]
	v_pk_fma_f32 v[110:111], v[154:155], v[60:61], v[110:111] op_sel_hi:[1,0,1]
	v_pk_fma_f32 v[112:113], v[156:157], v[60:61], v[112:113] op_sel_hi:[1,0,1]
	v_pk_fma_f32 v[114:115], v[158:159], v[60:61], v[114:115] op_sel_hi:[1,0,1]
	v_lshl_add_u32 v7, v44, 7, v1
	v_lshl_add_u32 v8, v44, 6, v10
	global_load_dwordx4 v[232:235], v7, s[26:27] sc1
	global_load_dwordx2 v[236:237], v8, s[26:27] sc1
	s_waitcnt vmcnt(41)
	v_cvt_scalef32_pk32_f32_fp6 v[128:159], v[238:243], 1.0
	v_pk_fma_f32 v[84:85], v[128:129], v[60:61], v[84:85] op_sel:[0,1,0] op_sel_hi:[1,1,1]
	v_pk_fma_f32 v[86:87], v[130:131], v[60:61], v[86:87] op_sel:[0,1,0] op_sel_hi:[1,1,1]
	v_pk_fma_f32 v[88:89], v[132:133], v[60:61], v[88:89] op_sel:[0,1,0] op_sel_hi:[1,1,1]
	v_pk_fma_f32 v[90:91], v[134:135], v[60:61], v[90:91] op_sel:[0,1,0] op_sel_hi:[1,1,1]
	v_pk_fma_f32 v[92:93], v[136:137], v[60:61], v[92:93] op_sel:[0,1,0] op_sel_hi:[1,1,1]
	v_pk_fma_f32 v[94:95], v[138:139], v[60:61], v[94:95] op_sel:[0,1,0] op_sel_hi:[1,1,1]
	v_pk_fma_f32 v[96:97], v[140:141], v[60:61], v[96:97] op_sel:[0,1,0] op_sel_hi:[1,1,1]
	v_pk_fma_f32 v[98:99], v[142:143], v[60:61], v[98:99] op_sel:[0,1,0] op_sel_hi:[1,1,1]
	v_pk_fma_f32 v[100:101], v[144:145], v[60:61], v[100:101] op_sel:[0,1,0] op_sel_hi:[1,1,1]
	v_pk_fma_f32 v[102:103], v[146:147], v[60:61], v[102:103] op_sel:[0,1,0] op_sel_hi:[1,1,1]
	v_pk_fma_f32 v[104:105], v[148:149], v[60:61], v[104:105] op_sel:[0,1,0] op_sel_hi:[1,1,1]
	v_pk_fma_f32 v[106:107], v[150:151], v[60:61], v[106:107] op_sel:[0,1,0] op_sel_hi:[1,1,1]
	v_pk_fma_f32 v[108:109], v[152:153], v[60:61], v[108:109] op_sel:[0,1,0] op_sel_hi:[1,1,1]
	v_pk_fma_f32 v[110:111], v[154:155], v[60:61], v[110:111] op_sel:[0,1,0] op_sel_hi:[1,1,1]
	v_pk_fma_f32 v[112:113], v[156:157], v[60:61], v[112:113] op_sel:[0,1,0] op_sel_hi:[1,1,1]
	v_pk_fma_f32 v[114:115], v[158:159], v[60:61], v[114:115] op_sel:[0,1,0] op_sel_hi:[1,1,1]
	v_lshl_add_u32 v7, v45, 7, v1
	v_lshl_add_u32 v8, v45, 6, v10
	global_load_dwordx4 v[238:241], v7, s[26:27] sc1
	global_load_dwordx2 v[242:243], v8, s[26:27] sc1
	s_waitcnt vmcnt(41)
	v_cvt_scalef32_pk32_f32_fp6 v[128:159], v[244:249], 1.0
	v_pk_fma_f32 v[84:85], v[128:129], v[62:63], v[84:85] op_sel_hi:[1,0,1]
	v_pk_fma_f32 v[86:87], v[130:131], v[62:63], v[86:87] op_sel_hi:[1,0,1]
	v_pk_fma_f32 v[88:89], v[132:133], v[62:63], v[88:89] op_sel_hi:[1,0,1]
	v_pk_fma_f32 v[90:91], v[134:135], v[62:63], v[90:91] op_sel_hi:[1,0,1]
	v_pk_fma_f32 v[92:93], v[136:137], v[62:63], v[92:93] op_sel_hi:[1,0,1]
	v_pk_fma_f32 v[94:95], v[138:139], v[62:63], v[94:95] op_sel_hi:[1,0,1]
	v_pk_fma_f32 v[96:97], v[140:141], v[62:63], v[96:97] op_sel_hi:[1,0,1]
	v_pk_fma_f32 v[98:99], v[142:143], v[62:63], v[98:99] op_sel_hi:[1,0,1]
	v_pk_fma_f32 v[100:101], v[144:145], v[62:63], v[100:101] op_sel_hi:[1,0,1]
	v_pk_fma_f32 v[102:103], v[146:147], v[62:63], v[102:103] op_sel_hi:[1,0,1]
	v_pk_fma_f32 v[104:105], v[148:149], v[62:63], v[104:105] op_sel_hi:[1,0,1]
	v_pk_fma_f32 v[106:107], v[150:151], v[62:63], v[106:107] op_sel_hi:[1,0,1]
	v_pk_fma_f32 v[108:109], v[152:153], v[62:63], v[108:109] op_sel_hi:[1,0,1]
	v_pk_fma_f32 v[110:111], v[154:155], v[62:63], v[110:111] op_sel_hi:[1,0,1]
	v_pk_fma_f32 v[112:113], v[156:157], v[62:63], v[112:113] op_sel_hi:[1,0,1]
	v_pk_fma_f32 v[114:115], v[158:159], v[62:63], v[114:115] op_sel_hi:[1,0,1]
	v_lshl_add_u32 v7, v46, 7, v1
	v_lshl_add_u32 v8, v46, 6, v10
	global_load_dwordx4 v[244:247], v7, s[26:27] sc1
	global_load_dwordx2 v[248:249], v8, s[26:27] sc1
	s_waitcnt vmcnt(41)
	v_cvt_scalef32_pk32_f32_fp6 v[128:159], v[250:255], 1.0
	v_pk_fma_f32 v[84:85], v[128:129], v[62:63], v[84:85] op_sel:[0,1,0] op_sel_hi:[1,1,1]
	v_pk_fma_f32 v[86:87], v[130:131], v[62:63], v[86:87] op_sel:[0,1,0] op_sel_hi:[1,1,1]
	v_pk_fma_f32 v[88:89], v[132:133], v[62:63], v[88:89] op_sel:[0,1,0] op_sel_hi:[1,1,1]
	v_pk_fma_f32 v[90:91], v[134:135], v[62:63], v[90:91] op_sel:[0,1,0] op_sel_hi:[1,1,1]
	v_pk_fma_f32 v[92:93], v[136:137], v[62:63], v[92:93] op_sel:[0,1,0] op_sel_hi:[1,1,1]
	v_pk_fma_f32 v[94:95], v[138:139], v[62:63], v[94:95] op_sel:[0,1,0] op_sel_hi:[1,1,1]
	v_pk_fma_f32 v[96:97], v[140:141], v[62:63], v[96:97] op_sel:[0,1,0] op_sel_hi:[1,1,1]
	v_pk_fma_f32 v[98:99], v[142:143], v[62:63], v[98:99] op_sel:[0,1,0] op_sel_hi:[1,1,1]
	v_pk_fma_f32 v[100:101], v[144:145], v[62:63], v[100:101] op_sel:[0,1,0] op_sel_hi:[1,1,1]
	v_pk_fma_f32 v[102:103], v[146:147], v[62:63], v[102:103] op_sel:[0,1,0] op_sel_hi:[1,1,1]
	v_pk_fma_f32 v[104:105], v[148:149], v[62:63], v[104:105] op_sel:[0,1,0] op_sel_hi:[1,1,1]
	v_pk_fma_f32 v[106:107], v[150:151], v[62:63], v[106:107] op_sel:[0,1,0] op_sel_hi:[1,1,1]
	v_pk_fma_f32 v[108:109], v[152:153], v[62:63], v[108:109] op_sel:[0,1,0] op_sel_hi:[1,1,1]
	v_pk_fma_f32 v[110:111], v[154:155], v[62:63], v[110:111] op_sel:[0,1,0] op_sel_hi:[1,1,1]
	v_pk_fma_f32 v[112:113], v[156:157], v[62:63], v[112:113] op_sel:[0,1,0] op_sel_hi:[1,1,1]
	v_pk_fma_f32 v[114:115], v[158:159], v[62:63], v[114:115] op_sel:[0,1,0] op_sel_hi:[1,1,1]
	v_lshl_add_u32 v7, v47, 7, v1
	v_lshl_add_u32 v8, v47, 6, v10
	global_load_dwordx4 v[250:253], v7, s[26:27] sc1
	global_load_dwordx2 v[254:255], v8, s[26:27] sc1
	ds_write_b128 v4, v[84:87] offset:0
	ds_write_b128 v4, v[88:91] offset:16
	ds_write_b128 v4, v[92:95] offset:32
	ds_write_b128 v4, v[96:99] offset:48
	ds_write_b128 v4, v[100:103] offset:64
	ds_write_b128 v4, v[104:107] offset:80
	ds_write_b128 v4, v[108:111] offset:96
	ds_write_b128 v4, v[112:115] offset:112
	ds_read_b128 v[128:131], v5 offset:0
	ds_read_b128 v[132:135], v5 offset:1152
	ds_read_b128 v[136:139], v5 offset:2304
	ds_read_b128 v[140:143], v5 offset:3456
	ds_read_b128 v[144:147], v5 offset:4608
	ds_read_b128 v[148:151], v5 offset:5760
	ds_read_b128 v[152:155], v5 offset:6912
	ds_read_b128 v[156:159], v5 offset:8064
	s_waitcnt lgkmcnt(0)
	v_add_f32_e32 v128, v128, v132
	v_add_f32_e32 v136, v136, v140
	v_add_f32_e32 v144, v144, v148
	v_add_f32_e32 v152, v152, v156
	v_add_f32_e32 v129, v129, v133
	v_add_f32_e32 v137, v137, v141
	v_add_f32_e32 v145, v145, v149
	v_add_f32_e32 v153, v153, v157
	v_add_f32_e32 v130, v130, v134
	v_add_f32_e32 v138, v138, v142
	v_add_f32_e32 v146, v146, v150
	v_add_f32_e32 v154, v154, v158
	v_add_f32_e32 v131, v131, v135
	v_add_f32_e32 v139, v139, v143
	v_add_f32_e32 v147, v147, v151
	v_add_f32_e32 v155, v155, v159
	v_add_f32_e32 v128, v128, v136
	v_add_f32_e32 v144, v144, v152
	v_add_f32_e32 v129, v129, v137
	v_add_f32_e32 v145, v145, v153
	v_add_f32_e32 v130, v130, v138
	v_add_f32_e32 v146, v146, v154
	v_add_f32_e32 v131, v131, v139
	v_add_f32_e32 v147, v147, v155
	v_add_f32_e32 v128, v128, v144
	v_add_f32_e32 v129, v129, v145
	v_add_f32_e32 v130, v130, v146
	v_add_f32_e32 v131, v131, v147
	s_waitcnt vmcnt(40)
	v_add_f32_e32 v116, v80, v128
	v_add_f32_e32 v117, v81, v129
	v_add_f32_e32 v118, v82, v130
	v_add_f32_e32 v119, v83, v131
	global_store_dwordx4 v6, v[116:119], s[34:35]
	v_mul_f32_e32 v9, v116, v116
	v_fmac_f32_e32 v9, v117, v117
	v_fmac_f32_e32 v9, v118, v118
	v_fmac_f32_e32 v9, v119, v119
	s_nop 1
	v_add_f32_dpp v9, v9, v9 quad_perm:[1,0,3,2] row_mask:0xf bank_mask:0xf
	s_nop 1
	v_add_f32_dpp v9, v9, v9 quad_perm:[2,3,0,1] row_mask:0xf bank_mask:0xf
	s_nop 1
	v_add_f32_dpp v9, v9, v9 row_half_mirror row_mask:0xf bank_mask:0xf
	s_nop 1
	v_add_f32_dpp v9, v9, v9 row_mirror row_mask:0xf bank_mask:0xf
	s_nop 1
	v_add_f32_dpp v9, v9, v9 row_bcast:15 row_mask:0xa bank_mask:0xf
	s_nop 1
	v_add_f32_dpp v9, v9, v9 row_bcast:31 row_mask:0xc bank_mask:0xf
	s_nop 1
	s_mov_b64 exec, s[36:37]
	s_nop 1
	global_store_dword v3, v9, s[38:39]
	s_mov_b64 exec, -1
	s_add_u32 s28, s28, 1
	s_add_u32 s40, s28, 0
	s_min_u32 s40, s40, 127
	s_lshl_b32 s40, s40, 8
	s_add_u32 s40, s40, s24
	s_lshl_b32 s29, s40, 13
	s_add_u32 s34, s10, s29
	s_addc_u32 s35, s11, 0
	global_load_dwordx4 v[80:83], v6, s[34:35]
	s_lshl_b32 s29, s40, 5
	s_add_u32 s29, s29, s43
	s_add_u32 s38, s12, s29
	s_addc_u32 s39, s13, 0
	s_add_u32 s40, s28, 2
	s_min_u32 s40, s40, 127
	s_lshl_b32 s40, s40, 8
	s_add_u32 s40, s40, s24
	s_lshl_b32 s29, s40, 9
	s_add_u32 s30, s4, s29
	s_addc_u32 s31, s5, 0
	global_load_dwordx4 v[32:35], v2, s[30:31] offset:0
	global_load_dwordx4 v[36:39], v2, s[30:31] offset:16
	global_load_dwordx4 v[40:43], v2, s[30:31] offset:32
	global_load_dwordx4 v[44:47], v2, s[30:31] offset:48
	s_add_u32 s40, s28, 1
	s_min_u32 s40, s40, 127
	s_lshl_b32 s40, s40, 8
	s_add_u32 s40, s40, s24
	s_lshl_b32 s29, s40, 9
	s_add_u32 s32, s6, s29
	s_addc_u32 s33, s7, 0
	global_load_dwordx4 v[48:51], v2, s[32:33] offset:0
	global_load_dwordx4 v[52:55], v2, s[32:33] offset:16
	global_load_dwordx4 v[56:59], v2, s[32:33] offset:32
	global_load_dwordx4 v[60:63], v2, s[32:33] offset:48
	s_waitcnt vmcnt(41)
	v_cvt_scalef32_pk32_f32_fp6 v[128:159], v[160:165], 1.0
	v_pk_mul_f32 v[84:85], v[128:129], v[64:65] op_sel_hi:[1,0]
	v_pk_mul_f32 v[86:87], v[130:131], v[64:65] op_sel_hi:[1,0]
	v_pk_mul_f32 v[88:89], v[132:133], v[64:65] op_sel_hi:[1,0]
	v_pk_mul_f32 v[90:91], v[134:135], v[64:65] op_sel_hi:[1,0]
	v_pk_mul_f32 v[92:93], v[136:137], v[64:65] op_sel_hi:[1,0]
	v_pk_mul_f32 v[94:95], v[138:139], v[64:65] op_sel_hi:[1,0]
	v_pk_mul_f32 v[96:97], v[140:141], v[64:65] op_sel_hi:[1,0]
	v_pk_mul_f32 v[98:99], v[142:143], v[64:65] op_sel_hi:[1,0]
	v_pk_mul_f32 v[100:101], v[144:145], v[64:65] op_sel_hi:[1,0]
	v_pk_mul_f32 v[102:103], v[146:147], v[64:65] op_sel_hi:[1,0]
	v_pk_mul_f32 v[104:105], v[148:149], v[64:65] op_sel_hi:[1,0]
	v_pk_mul_f32 v[106:107], v[150:151], v[64:65] op_sel_hi:[1,0]
	v_pk_mul_f32 v[108:109], v[152:153], v[64:65] op_sel_hi:[1,0]
	v_pk_mul_f32 v[110:111], v[154:155], v[64:65] op_sel_hi:[1,0]
	v_pk_mul_f32 v[112:113], v[156:157], v[64:65] op_sel_hi:[1,0]
	v_pk_mul_f32 v[114:115], v[158:159], v[64:65] op_sel_hi:[1,0]
	v_lshl_add_u32 v7, v16, 7, v1
	v_lshl_add_u32 v8, v16, 6, v10
	global_load_dwordx4 v[160:163], v7, s[26:27] sc1
	global_load_dwordx2 v[164:165], v8, s[26:27] sc1
	s_waitcnt vmcnt(41)
	v_cvt_scalef32_pk32_f32_fp6 v[128:159], v[166:171], 1.0
	v_pk_fma_f32 v[84:85], v[128:129], v[64:65], v[84:85] op_sel:[0,1,0] op_sel_hi:[1,1,1]
	v_pk_fma_f32 v[86:87], v[130:131], v[64:65], v[86:87] op_sel:[0,1,0] op_sel_hi:[1,1,1]
	v_pk_fma_f32 v[88:89], v[132:133], v[64:65], v[88:89] op_sel:[0,1,0] op_sel_hi:[1,1,1]
	v_pk_fma_f32 v[90:91], v[134:135], v[64:65], v[90:91] op_sel:[0,1,0] op_sel_hi:[1,1,1]
	v_pk_fma_f32 v[92:93], v[136:137], v[64:65], v[92:93] op_sel:[0,1,0] op_sel_hi:[1,1,1]
	v_pk_fma_f32 v[94:95], v[138:139], v[64:65], v[94:95] op_sel:[0,1,0] op_sel_hi:[1,1,1]
	v_pk_fma_f32 v[96:97], v[140:141], v[64:65], v[96:97] op_sel:[0,1,0] op_sel_hi:[1,1,1]
	v_pk_fma_f32 v[98:99], v[142:143], v[64:65], v[98:99] op_sel:[0,1,0] op_sel_hi:[1,1,1]
	v_pk_fma_f32 v[100:101], v[144:145], v[64:65], v[100:101] op_sel:[0,1,0] op_sel_hi:[1,1,1]
	v_pk_fma_f32 v[102:103], v[146:147], v[64:65], v[102:103] op_sel:[0,1,0] op_sel_hi:[1,1,1]
	v_pk_fma_f32 v[104:105], v[148:149], v[64:65], v[104:105] op_sel:[0,1,0] op_sel_hi:[1,1,1]
	v_pk_fma_f32 v[106:107], v[150:151], v[64:65], v[106:107] op_sel:[0,1,0] op_sel_hi:[1,1,1]
	v_pk_fma_f32 v[108:109], v[152:153], v[64:65], v[108:109] op_sel:[0,1,0] op_sel_hi:[1,1,1]
	v_pk_fma_f32 v[110:111], v[154:155], v[64:65], v[110:111] op_sel:[0,1,0] op_sel_hi:[1,1,1]
	v_pk_fma_f32 v[112:113], v[156:157], v[64:65], v[112:113] op_sel:[0,1,0] op_sel_hi:[1,1,1]
	v_pk_fma_f32 v[114:115], v[158:159], v[64:65], v[114:115] op_sel:[0,1,0] op_sel_hi:[1,1,1]
	v_lshl_add_u32 v7, v17, 7, v1
	v_lshl_add_u32 v8, v17, 6, v10
	global_load_dwordx4 v[166:169], v7, s[26:27] sc1
	global_load_dwordx2 v[170:171], v8, s[26:27] sc1
	s_waitcnt vmcnt(41)
	v_cvt_scalef32_pk32_f32_fp6 v[128:159], v[172:177], 1.0
	v_pk_fma_f32 v[84:85], v[128:129], v[66:67], v[84:85] op_sel_hi:[1,0,1]
	v_pk_fma_f32 v[86:87], v[130:131], v[66:67], v[86:87] op_sel_hi:[1,0,1]
	v_pk_fma_f32 v[88:89], v[132:133], v[66:67], v[88:89] op_sel_hi:[1,0,1]
	v_pk_fma_f32 v[90:91], v[134:135], v[66:67], v[90:91] op_sel_hi:[1,0,1]
	v_pk_fma_f32 v[92:93], v[136:137], v[66:67], v[92:93] op_sel_hi:[1,0,1]
	v_pk_fma_f32 v[94:95], v[138:139], v[66:67], v[94:95] op_sel_hi:[1,0,1]
	v_pk_fma_f32 v[96:97], v[140:141], v[66:67], v[96:97] op_sel_hi:[1,0,1]
	v_pk_fma_f32 v[98:99], v[142:143], v[66:67], v[98:99] op_sel_hi:[1,0,1]
	v_pk_fma_f32 v[100:101], v[144:145], v[66:67], v[100:101] op_sel_hi:[1,0,1]
	v_pk_fma_f32 v[102:103], v[146:147], v[66:67], v[102:103] op_sel_hi:[1,0,1]
	v_pk_fma_f32 v[104:105], v[148:149], v[66:67], v[104:105] op_sel_hi:[1,0,1]
	v_pk_fma_f32 v[106:107], v[150:151], v[66:67], v[106:107] op_sel_hi:[1,0,1]
	v_pk_fma_f32 v[108:109], v[152:153], v[66:67], v[108:109] op_sel_hi:[1,0,1]
	v_pk_fma_f32 v[110:111], v[154:155], v[66:67], v[110:111] op_sel_hi:[1,0,1]
	v_pk_fma_f32 v[112:113], v[156:157], v[66:67], v[112:113] op_sel_hi:[1,0,1]
	v_pk_fma_f32 v[114:115], v[158:159], v[66:67], v[114:115] op_sel_hi:[1,0,1]
	v_lshl_add_u32 v7, v18, 7, v1
	v_lshl_add_u32 v8, v18, 6, v10
	global_load_dwordx4 v[172:175], v7, s[26:27] sc1
	global_load_dwordx2 v[176:177], v8, s[26:27] sc1
	s_waitcnt vmcnt(41)
	v_cvt_scalef32_pk32_f32_fp6 v[128:159], v[178:183], 1.0
	v_pk_fma_f32 v[84:85], v[128:129], v[66:67], v[84:85] op_sel:[0,1,0] op_sel_hi:[1,1,1]
	v_pk_fma_f32 v[86:87], v[130:131], v[66:67], v[86:87] op_sel:[0,1,0] op_sel_hi:[1,1,1]
	v_pk_fma_f32 v[88:89], v[132:133], v[66:67], v[88:89] op_sel:[0,1,0] op_sel_hi:[1,1,1]
	v_pk_fma_f32 v[90:91], v[134:135], v[66:67], v[90:91] op_sel:[0,1,0] op_sel_hi:[1,1,1]
	v_pk_fma_f32 v[92:93], v[136:137], v[66:67], v[92:93] op_sel:[0,1,0] op_sel_hi:[1,1,1]
	v_pk_fma_f32 v[94:95], v[138:139], v[66:67], v[94:95] op_sel:[0,1,0] op_sel_hi:[1,1,1]
	v_pk_fma_f32 v[96:97], v[140:141], v[66:67], v[96:97] op_sel:[0,1,0] op_sel_hi:[1,1,1]
	v_pk_fma_f32 v[98:99], v[142:143], v[66:67], v[98:99] op_sel:[0,1,0] op_sel_hi:[1,1,1]
	v_pk_fma_f32 v[100:101], v[144:145], v[66:67], v[100:101] op_sel:[0,1,0] op_sel_hi:[1,1,1]
	v_pk_fma_f32 v[102:103], v[146:147], v[66:67], v[102:103] op_sel:[0,1,0] op_sel_hi:[1,1,1]
	v_pk_fma_f32 v[104:105], v[148:149], v[66:67], v[104:105] op_sel:[0,1,0] op_sel_hi:[1,1,1]
	v_pk_fma_f32 v[106:107], v[150:151], v[66:67], v[106:107] op_sel:[0,1,0] op_sel_hi:[1,1,1]
	v_pk_fma_f32 v[108:109], v[152:153], v[66:67], v[108:109] op_sel:[0,1,0] op_sel_hi:[1,1,1]
	v_pk_fma_f32 v[110:111], v[154:155], v[66:67], v[110:111] op_sel:[0,1,0] op_sel_hi:[1,1,1]
	v_pk_fma_f32 v[112:113], v[156:157], v[66:67], v[112:113] op_sel:[0,1,0] op_sel_hi:[1,1,1]
	v_pk_fma_f32 v[114:115], v[158:159], v[66:67], v[114:115] op_sel:[0,1,0] op_sel_hi:[1,1,1]
	v_lshl_add_u32 v7, v19, 7, v1
	v_lshl_add_u32 v8, v19, 6, v10
	global_load_dwordx4 v[178:181], v7, s[26:27] sc1
	global_load_dwordx2 v[182:183], v8, s[26:27] sc1
	s_waitcnt vmcnt(41)
	v_cvt_scalef32_pk32_f32_fp6 v[128:159], v[184:189], 1.0
	v_pk_fma_f32 v[84:85], v[128:129], v[68:69], v[84:85] op_sel_hi:[1,0,1]
	v_pk_fma_f32 v[86:87], v[130:131], v[68:69], v[86:87] op_sel_hi:[1,0,1]
	v_pk_fma_f32 v[88:89], v[132:133], v[68:69], v[88:89] op_sel_hi:[1,0,1]
	v_pk_fma_f32 v[90:91], v[134:135], v[68:69], v[90:91] op_sel_hi:[1,0,1]
	v_pk_fma_f32 v[92:93], v[136:137], v[68:69], v[92:93] op_sel_hi:[1,0,1]
	v_pk_fma_f32 v[94:95], v[138:139], v[68:69], v[94:95] op_sel_hi:[1,0,1]
	v_pk_fma_f32 v[96:97], v[140:141], v[68:69], v[96:97] op_sel_hi:[1,0,1]
	v_pk_fma_f32 v[98:99], v[142:143], v[68:69], v[98:99] op_sel_hi:[1,0,1]
	v_pk_fma_f32 v[100:101], v[144:145], v[68:69], v[100:101] op_sel_hi:[1,0,1]
	v_pk_fma_f32 v[102:103], v[146:147], v[68:69], v[102:103] op_sel_hi:[1,0,1]
	v_pk_fma_f32 v[104:105], v[148:149], v[68:69], v[104:105] op_sel_hi:[1,0,1]
	v_pk_fma_f32 v[106:107], v[150:151], v[68:69], v[106:107] op_sel_hi:[1,0,1]
	v_pk_fma_f32 v[108:109], v[152:153], v[68:69], v[108:109] op_sel_hi:[1,0,1]
	v_pk_fma_f32 v[110:111], v[154:155], v[68:69], v[110:111] op_sel_hi:[1,0,1]
	v_pk_fma_f32 v[112:113], v[156:157], v[68:69], v[112:113] op_sel_hi:[1,0,1]
	v_pk_fma_f32 v[114:115], v[158:159], v[68:69], v[114:115] op_sel_hi:[1,0,1]
	v_lshl_add_u32 v7, v20, 7, v1
	v_lshl_add_u32 v8, v20, 6, v10
	global_load_dwordx4 v[184:187], v7, s[26:27] sc1
	global_load_dwordx2 v[188:189], v8, s[26:27] sc1
	s_waitcnt vmcnt(41)
	v_cvt_scalef32_pk32_f32_fp6 v[128:159], v[190:195], 1.0
	v_pk_fma_f32 v[84:85], v[128:129], v[68:69], v[84:85] op_sel:[0,1,0] op_sel_hi:[1,1,1]
	v_pk_fma_f32 v[86:87], v[130:131], v[68:69], v[86:87] op_sel:[0,1,0] op_sel_hi:[1,1,1]
	v_pk_fma_f32 v[88:89], v[132:133], v[68:69], v[88:89] op_sel:[0,1,0] op_sel_hi:[1,1,1]
	v_pk_fma_f32 v[90:91], v[134:135], v[68:69], v[90:91] op_sel:[0,1,0] op_sel_hi:[1,1,1]
	v_pk_fma_f32 v[92:93], v[136:137], v[68:69], v[92:93] op_sel:[0,1,0] op_sel_hi:[1,1,1]
	v_pk_fma_f32 v[94:95], v[138:139], v[68:69], v[94:95] op_sel:[0,1,0] op_sel_hi:[1,1,1]
	v_pk_fma_f32 v[96:97], v[140:141], v[68:69], v[96:97] op_sel:[0,1,0] op_sel_hi:[1,1,1]
	v_pk_fma_f32 v[98:99], v[142:143], v[68:69], v[98:99] op_sel:[0,1,0] op_sel_hi:[1,1,1]
	v_pk_fma_f32 v[100:101], v[144:145], v[68:69], v[100:101] op_sel:[0,1,0] op_sel_hi:[1,1,1]
	v_pk_fma_f32 v[102:103], v[146:147], v[68:69], v[102:103] op_sel:[0,1,0] op_sel_hi:[1,1,1]
	v_pk_fma_f32 v[104:105], v[148:149], v[68:69], v[104:105] op_sel:[0,1,0] op_sel_hi:[1,1,1]
	v_pk_fma_f32 v[106:107], v[150:151], v[68:69], v[106:107] op_sel:[0,1,0] op_sel_hi:[1,1,1]
	v_pk_fma_f32 v[108:109], v[152:153], v[68:69], v[108:109] op_sel:[0,1,0] op_sel_hi:[1,1,1]
	v_pk_fma_f32 v[110:111], v[154:155], v[68:69], v[110:111] op_sel:[0,1,0] op_sel_hi:[1,1,1]
	v_pk_fma_f32 v[112:113], v[156:157], v[68:69], v[112:113] op_sel:[0,1,0] op_sel_hi:[1,1,1]
	v_pk_fma_f32 v[114:115], v[158:159], v[68:69], v[114:115] op_sel:[0,1,0] op_sel_hi:[1,1,1]
	v_lshl_add_u32 v7, v21, 7, v1
	v_lshl_add_u32 v8, v21, 6, v10
	global_load_dwordx4 v[190:193], v7, s[26:27] sc1
	global_load_dwordx2 v[194:195], v8, s[26:27] sc1
	s_waitcnt vmcnt(41)
	v_cvt_scalef32_pk32_f32_fp6 v[128:159], v[196:201], 1.0
	v_pk_fma_f32 v[84:85], v[128:129], v[70:71], v[84:85] op_sel_hi:[1,0,1]
	v_pk_fma_f32 v[86:87], v[130:131], v[70:71], v[86:87] op_sel_hi:[1,0,1]
	v_pk_fma_f32 v[88:89], v[132:133], v[70:71], v[88:89] op_sel_hi:[1,0,1]
	v_pk_fma_f32 v[90:91], v[134:135], v[70:71], v[90:91] op_sel_hi:[1,0,1]
	v_pk_fma_f32 v[92:93], v[136:137], v[70:71], v[92:93] op_sel_hi:[1,0,1]
	v_pk_fma_f32 v[94:95], v[138:139], v[70:71], v[94:95] op_sel_hi:[1,0,1]
	v_pk_fma_f32 v[96:97], v[140:141], v[70:71], v[96:97] op_sel_hi:[1,0,1]
	v_pk_fma_f32 v[98:99], v[142:143], v[70:71], v[98:99] op_sel_hi:[1,0,1]
	v_pk_fma_f32 v[100:101], v[144:145], v[70:71], v[100:101] op_sel_hi:[1,0,1]
	v_pk_fma_f32 v[102:103], v[146:147], v[70:71], v[102:103] op_sel_hi:[1,0,1]
	v_pk_fma_f32 v[104:105], v[148:149], v[70:71], v[104:105] op_sel_hi:[1,0,1]
	v_pk_fma_f32 v[106:107], v[150:151], v[70:71], v[106:107] op_sel_hi:[1,0,1]
	v_pk_fma_f32 v[108:109], v[152:153], v[70:71], v[108:109] op_sel_hi:[1,0,1]
	v_pk_fma_f32 v[110:111], v[154:155], v[70:71], v[110:111] op_sel_hi:[1,0,1]
	v_pk_fma_f32 v[112:113], v[156:157], v[70:71], v[112:113] op_sel_hi:[1,0,1]
	v_pk_fma_f32 v[114:115], v[158:159], v[70:71], v[114:115] op_sel_hi:[1,0,1]
	v_lshl_add_u32 v7, v22, 7, v1
	v_lshl_add_u32 v8, v22, 6, v10
	global_load_dwordx4 v[196:199], v7, s[26:27] sc1
	global_load_dwordx2 v[200:201], v8, s[26:27] sc1
	s_waitcnt vmcnt(41)
	v_cvt_scalef32_pk32_f32_fp6 v[128:159], v[202:207], 1.0
	v_pk_fma_f32 v[84:85], v[128:129], v[70:71], v[84:85] op_sel:[0,1,0] op_sel_hi:[1,1,1]
	v_pk_fma_f32 v[86:87], v[130:131], v[70:71], v[86:87] op_sel:[0,1,0] op_sel_hi:[1,1,1]
	v_pk_fma_f32 v[88:89], v[132:133], v[70:71], v[88:89] op_sel:[0,1,0] op_sel_hi:[1,1,1]
	v_pk_fma_f32 v[90:91], v[134:135], v[70:71], v[90:91] op_sel:[0,1,0] op_sel_hi:[1,1,1]
	v_pk_fma_f32 v[92:93], v[136:137], v[70:71], v[92:93] op_sel:[0,1,0] op_sel_hi:[1,1,1]
	v_pk_fma_f32 v[94:95], v[138:139], v[70:71], v[94:95] op_sel:[0,1,0] op_sel_hi:[1,1,1]
	v_pk_fma_f32 v[96:97], v[140:141], v[70:71], v[96:97] op_sel:[0,1,0] op_sel_hi:[1,1,1]
	v_pk_fma_f32 v[98:99], v[142:143], v[70:71], v[98:99] op_sel:[0,1,0] op_sel_hi:[1,1,1]
	v_pk_fma_f32 v[100:101], v[144:145], v[70:71], v[100:101] op_sel:[0,1,0] op_sel_hi:[1,1,1]
	v_pk_fma_f32 v[102:103], v[146:147], v[70:71], v[102:103] op_sel:[0,1,0] op_sel_hi:[1,1,1]
	v_pk_fma_f32 v[104:105], v[148:149], v[70:71], v[104:105] op_sel:[0,1,0] op_sel_hi:[1,1,1]
	v_pk_fma_f32 v[106:107], v[150:151], v[70:71], v[106:107] op_sel:[0,1,0] op_sel_hi:[1,1,1]
	v_pk_fma_f32 v[108:109], v[152:153], v[70:71], v[108:109] op_sel:[0,1,0] op_sel_hi:[1,1,1]
	v_pk_fma_f32 v[110:111], v[154:155], v[70:71], v[110:111] op_sel:[0,1,0] op_sel_hi:[1,1,1]
	v_pk_fma_f32 v[112:113], v[156:157], v[70:71], v[112:113] op_sel:[0,1,0] op_sel_hi:[1,1,1]
	v_pk_fma_f32 v[114:115], v[158:159], v[70:71], v[114:115] op_sel:[0,1,0] op_sel_hi:[1,1,1]
	v_lshl_add_u32 v7, v23, 7, v1
	v_lshl_add_u32 v8, v23, 6, v10
	global_load_dwordx4 v[202:205], v7, s[26:27] sc1
	global_load_dwordx2 v[206:207], v8, s[26:27] sc1
	s_waitcnt vmcnt(41)
	v_cvt_scalef32_pk32_f32_fp6 v[128:159], v[208:213], 1.0
	v_pk_fma_f32 v[84:85], v[128:129], v[72:73], v[84:85] op_sel_hi:[1,0,1]
	v_pk_fma_f32 v[86:87], v[130:131], v[72:73], v[86:87] op_sel_hi:[1,0,1]
	v_pk_fma_f32 v[88:89], v[132:133], v[72:73], v[88:89] op_sel_hi:[1,0,1]
	v_pk_fma_f32 v[90:91], v[134:135], v[72:73], v[90:91] op_sel_hi:[1,0,1]
	v_pk_fma_f32 v[92:93], v[136:137], v[72:73], v[92:93] op_sel_hi:[1,0,1]
	v_pk_fma_f32 v[94:95], v[138:139], v[72:73], v[94:95] op_sel_hi:[1,0,1]
	v_pk_fma_f32 v[96:97], v[140:141], v[72:73], v[96:97] op_sel_hi:[1,0,1]
	v_pk_fma_f32 v[98:99], v[142:143], v[72:73], v[98:99] op_sel_hi:[1,0,1]
	v_pk_fma_f32 v[100:101], v[144:145], v[72:73], v[100:101] op_sel_hi:[1,0,1]
	v_pk_fma_f32 v[102:103], v[146:147], v[72:73], v[102:103] op_sel_hi:[1,0,1]
	v_pk_fma_f32 v[104:105], v[148:149], v[72:73], v[104:105] op_sel_hi:[1,0,1]
	v_pk_fma_f32 v[106:107], v[150:151], v[72:73], v[106:107] op_sel_hi:[1,0,1]
	v_pk_fma_f32 v[108:109], v[152:153], v[72:73], v[108:109] op_sel_hi:[1,0,1]
	v_pk_fma_f32 v[110:111], v[154:155], v[72:73], v[110:111] op_sel_hi:[1,0,1]
	v_pk_fma_f32 v[112:113], v[156:157], v[72:73], v[112:113] op_sel_hi:[1,0,1]
	v_pk_fma_f32 v[114:115], v[158:159], v[72:73], v[114:115] op_sel_hi:[1,0,1]
	v_lshl_add_u32 v7, v24, 7, v1
	v_lshl_add_u32 v8, v24, 6, v10
	global_load_dwordx4 v[208:211], v7, s[26:27] sc1
	global_load_dwordx2 v[212:213], v8, s[26:27] sc1
	s_waitcnt vmcnt(41)
	v_cvt_scalef32_pk32_f32_fp6 v[128:159], v[214:219], 1.0
	v_pk_fma_f32 v[84:85], v[128:129], v[72:73], v[84:85] op_sel:[0,1,0] op_sel_hi:[1,1,1]
	v_pk_fma_f32 v[86:87], v[130:131], v[72:73], v[86:87] op_sel:[0,1,0] op_sel_hi:[1,1,1]
	v_pk_fma_f32 v[88:89], v[132:133], v[72:73], v[88:89] op_sel:[0,1,0] op_sel_hi:[1,1,1]
	v_pk_fma_f32 v[90:91], v[134:135], v[72:73], v[90:91] op_sel:[0,1,0] op_sel_hi:[1,1,1]
	v_pk_fma_f32 v[92:93], v[136:137], v[72:73], v[92:93] op_sel:[0,1,0] op_sel_hi:[1,1,1]
	v_pk_fma_f32 v[94:95], v[138:139], v[72:73], v[94:95] op_sel:[0,1,0] op_sel_hi:[1,1,1]
	v_pk_fma_f32 v[96:97], v[140:141], v[72:73], v[96:97] op_sel:[0,1,0] op_sel_hi:[1,1,1]
	v_pk_fma_f32 v[98:99], v[142:143], v[72:73], v[98:99] op_sel:[0,1,0] op_sel_hi:[1,1,1]
	v_pk_fma_f32 v[100:101], v[144:145], v[72:73], v[100:101] op_sel:[0,1,0] op_sel_hi:[1,1,1]
	v_pk_fma_f32 v[102:103], v[146:147], v[72:73], v[102:103] op_sel:[0,1,0] op_sel_hi:[1,1,1]
	v_pk_fma_f32 v[104:105], v[148:149], v[72:73], v[104:105] op_sel:[0,1,0] op_sel_hi:[1,1,1]
	v_pk_fma_f32 v[106:107], v[150:151], v[72:73], v[106:107] op_sel:[0,1,0] op_sel_hi:[1,1,1]
	v_pk_fma_f32 v[108:109], v[152:153], v[72:73], v[108:109] op_sel:[0,1,0] op_sel_hi:[1,1,1]
	v_pk_fma_f32 v[110:111], v[154:155], v[72:73], v[110:111] op_sel:[0,1,0] op_sel_hi:[1,1,1]
	v_pk_fma_f32 v[112:113], v[156:157], v[72:73], v[112:113] op_sel:[0,1,0] op_sel_hi:[1,1,1]
	v_pk_fma_f32 v[114:115], v[158:159], v[72:73], v[114:115] op_sel:[0,1,0] op_sel_hi:[1,1,1]
	v_lshl_add_u32 v7, v25, 7, v1
	v_lshl_add_u32 v8, v25, 6, v10
	global_load_dwordx4 v[214:217], v7, s[26:27] sc1
	global_load_dwordx2 v[218:219], v8, s[26:27] sc1
	s_waitcnt vmcnt(41)
	v_cvt_scalef32_pk32_f32_fp6 v[128:159], v[220:225], 1.0
	v_pk_fma_f32 v[84:85], v[128:129], v[74:75], v[84:85] op_sel_hi:[1,0,1]
	v_pk_fma_f32 v[86:87], v[130:131], v[74:75], v[86:87] op_sel_hi:[1,0,1]
	v_pk_fma_f32 v[88:89], v[132:133], v[74:75], v[88:89] op_sel_hi:[1,0,1]
	v_pk_fma_f32 v[90:91], v[134:135], v[74:75], v[90:91] op_sel_hi:[1,0,1]
	v_pk_fma_f32 v[92:93], v[136:137], v[74:75], v[92:93] op_sel_hi:[1,0,1]
	v_pk_fma_f32 v[94:95], v[138:139], v[74:75], v[94:95] op_sel_hi:[1,0,1]
	v_pk_fma_f32 v[96:97], v[140:141], v[74:75], v[96:97] op_sel_hi:[1,0,1]
	v_pk_fma_f32 v[98:99], v[142:143], v[74:75], v[98:99] op_sel_hi:[1,0,1]
	v_pk_fma_f32 v[100:101], v[144:145], v[74:75], v[100:101] op_sel_hi:[1,0,1]
	v_pk_fma_f32 v[102:103], v[146:147], v[74:75], v[102:103] op_sel_hi:[1,0,1]
	v_pk_fma_f32 v[104:105], v[148:149], v[74:75], v[104:105] op_sel_hi:[1,0,1]
	v_pk_fma_f32 v[106:107], v[150:151], v[74:75], v[106:107] op_sel_hi:[1,0,1]
	v_pk_fma_f32 v[108:109], v[152:153], v[74:75], v[108:109] op_sel_hi:[1,0,1]
	v_pk_fma_f32 v[110:111], v[154:155], v[74:75], v[110:111] op_sel_hi:[1,0,1]
	v_pk_fma_f32 v[112:113], v[156:157], v[74:75], v[112:113] op_sel_hi:[1,0,1]
	v_pk_fma_f32 v[114:115], v[158:159], v[74:75], v[114:115] op_sel_hi:[1,0,1]
	v_lshl_add_u32 v7, v26, 7, v1
	v_lshl_add_u32 v8, v26, 6, v10
	global_load_dwordx4 v[220:223], v7, s[26:27] sc1
	global_load_dwordx2 v[224:225], v8, s[26:27] sc1
	s_waitcnt vmcnt(41)
	v_cvt_scalef32_pk32_f32_fp6 v[128:159], v[226:231], 1.0
	v_pk_fma_f32 v[84:85], v[128:129], v[74:75], v[84:85] op_sel:[0,1,0] op_sel_hi:[1,1,1]
	v_pk_fma_f32 v[86:87], v[130:131], v[74:75], v[86:87] op_sel:[0,1,0] op_sel_hi:[1,1,1]
	v_pk_fma_f32 v[88:89], v[132:133], v[74:75], v[88:89] op_sel:[0,1,0] op_sel_hi:[1,1,1]
	v_pk_fma_f32 v[90:91], v[134:135], v[74:75], v[90:91] op_sel:[0,1,0] op_sel_hi:[1,1,1]
	v_pk_fma_f32 v[92:93], v[136:137], v[74:75], v[92:93] op_sel:[0,1,0] op_sel_hi:[1,1,1]
	v_pk_fma_f32 v[94:95], v[138:139], v[74:75], v[94:95] op_sel:[0,1,0] op_sel_hi:[1,1,1]
	v_pk_fma_f32 v[96:97], v[140:141], v[74:75], v[96:97] op_sel:[0,1,0] op_sel_hi:[1,1,1]
	v_pk_fma_f32 v[98:99], v[142:143], v[74:75], v[98:99] op_sel:[0,1,0] op_sel_hi:[1,1,1]
	v_pk_fma_f32 v[100:101], v[144:145], v[74:75], v[100:101] op_sel:[0,1,0] op_sel_hi:[1,1,1]
	v_pk_fma_f32 v[102:103], v[146:147], v[74:75], v[102:103] op_sel:[0,1,0] op_sel_hi:[1,1,1]
	v_pk_fma_f32 v[104:105], v[148:149], v[74:75], v[104:105] op_sel:[0,1,0] op_sel_hi:[1,1,1]
	v_pk_fma_f32 v[106:107], v[150:151], v[74:75], v[106:107] op_sel:[0,1,0] op_sel_hi:[1,1,1]
	v_pk_fma_f32 v[108:109], v[152:153], v[74:75], v[108:109] op_sel:[0,1,0] op_sel_hi:[1,1,1]
	v_pk_fma_f32 v[110:111], v[154:155], v[74:75], v[110:111] op_sel:[0,1,0] op_sel_hi:[1,1,1]
	v_pk_fma_f32 v[112:113], v[156:157], v[74:75], v[112:113] op_sel:[0,1,0] op_sel_hi:[1,1,1]
	v_pk_fma_f32 v[114:115], v[158:159], v[74:75], v[114:115] op_sel:[0,1,0] op_sel_hi:[1,1,1]
	v_lshl_add_u32 v7, v27, 7, v1
	v_lshl_add_u32 v8, v27, 6, v10
	global_load_dwordx4 v[226:229], v7, s[26:27] sc1
	global_load_dwordx2 v[230:231], v8, s[26:27] sc1
	s_waitcnt vmcnt(41)
	v_cvt_scalef32_pk32_f32_fp6 v[128:159], v[232:237], 1.0
	v_pk_fma_f32 v[84:85], v[128:129], v[76:77], v[84:85] op_sel_hi:[1,0,1]
	v_pk_fma_f32 v[86:87], v[130:131], v[76:77], v[86:87] op_sel_hi:[1,0,1]
	v_pk_fma_f32 v[88:89], v[132:133], v[76:77], v[88:89] op_sel_hi:[1,0,1]
	v_pk_fma_f32 v[90:91], v[134:135], v[76:77], v[90:91] op_sel_hi:[1,0,1]
	v_pk_fma_f32 v[92:93], v[136:137], v[76:77], v[92:93] op_sel_hi:[1,0,1]
	v_pk_fma_f32 v[94:95], v[138:139], v[76:77], v[94:95] op_sel_hi:[1,0,1]
	v_pk_fma_f32 v[96:97], v[140:141], v[76:77], v[96:97] op_sel_hi:[1,0,1]
	v_pk_fma_f32 v[98:99], v[142:143], v[76:77], v[98:99] op_sel_hi:[1,0,1]
	v_pk_fma_f32 v[100:101], v[144:145], v[76:77], v[100:101] op_sel_hi:[1,0,1]
	v_pk_fma_f32 v[102:103], v[146:147], v[76:77], v[102:103] op_sel_hi:[1,0,1]
	v_pk_fma_f32 v[104:105], v[148:149], v[76:77], v[104:105] op_sel_hi:[1,0,1]
	v_pk_fma_f32 v[106:107], v[150:151], v[76:77], v[106:107] op_sel_hi:[1,0,1]
	v_pk_fma_f32 v[108:109], v[152:153], v[76:77], v[108:109] op_sel_hi:[1,0,1]
	v_pk_fma_f32 v[110:111], v[154:155], v[76:77], v[110:111] op_sel_hi:[1,0,1]
	v_pk_fma_f32 v[112:113], v[156:157], v[76:77], v[112:113] op_sel_hi:[1,0,1]
	v_pk_fma_f32 v[114:115], v[158:159], v[76:77], v[114:115] op_sel_hi:[1,0,1]
	v_lshl_add_u32 v7, v28, 7, v1
	v_lshl_add_u32 v8, v28, 6, v10
	global_load_dwordx4 v[232:235], v7, s[26:27] sc1
	global_load_dwordx2 v[236:237], v8, s[26:27] sc1
	s_waitcnt vmcnt(41)
	v_cvt_scalef32_pk32_f32_fp6 v[128:159], v[238:243], 1.0
	v_pk_fma_f32 v[84:85], v[128:129], v[76:77], v[84:85] op_sel:[0,1,0] op_sel_hi:[1,1,1]
	v_pk_fma_f32 v[86:87], v[130:131], v[76:77], v[86:87] op_sel:[0,1,0] op_sel_hi:[1,1,1]
	v_pk_fma_f32 v[88:89], v[132:133], v[76:77], v[88:89] op_sel:[0,1,0] op_sel_hi:[1,1,1]
	v_pk_fma_f32 v[90:91], v[134:135], v[76:77], v[90:91] op_sel:[0,1,0] op_sel_hi:[1,1,1]
	v_pk_fma_f32 v[92:93], v[136:137], v[76:77], v[92:93] op_sel:[0,1,0] op_sel_hi:[1,1,1]
	v_pk_fma_f32 v[94:95], v[138:139], v[76:77], v[94:95] op_sel:[0,1,0] op_sel_hi:[1,1,1]
	v_pk_fma_f32 v[96:97], v[140:141], v[76:77], v[96:97] op_sel:[0,1,0] op_sel_hi:[1,1,1]
	v_pk_fma_f32 v[98:99], v[142:143], v[76:77], v[98:99] op_sel:[0,1,0] op_sel_hi:[1,1,1]
	v_pk_fma_f32 v[100:101], v[144:145], v[76:77], v[100:101] op_sel:[0,1,0] op_sel_hi:[1,1,1]
	v_pk_fma_f32 v[102:103], v[146:147], v[76:77], v[102:103] op_sel:[0,1,0] op_sel_hi:[1,1,1]
	v_pk_fma_f32 v[104:105], v[148:149], v[76:77], v[104:105] op_sel:[0,1,0] op_sel_hi:[1,1,1]
	v_pk_fma_f32 v[106:107], v[150:151], v[76:77], v[106:107] op_sel:[0,1,0] op_sel_hi:[1,1,1]
	v_pk_fma_f32 v[108:109], v[152:153], v[76:77], v[108:109] op_sel:[0,1,0] op_sel_hi:[1,1,1]
	v_pk_fma_f32 v[110:111], v[154:155], v[76:77], v[110:111] op_sel:[0,1,0] op_sel_hi:[1,1,1]
	v_pk_fma_f32 v[112:113], v[156:157], v[76:77], v[112:113] op_sel:[0,1,0] op_sel_hi:[1,1,1]
	v_pk_fma_f32 v[114:115], v[158:159], v[76:77], v[114:115] op_sel:[0,1,0] op_sel_hi:[1,1,1]
	v_lshl_add_u32 v7, v29, 7, v1
	v_lshl_add_u32 v8, v29, 6, v10
	global_load_dwordx4 v[238:241], v7, s[26:27] sc1
	global_load_dwordx2 v[242:243], v8, s[26:27] sc1
	s_waitcnt vmcnt(41)
	v_cvt_scalef32_pk32_f32_fp6 v[128:159], v[244:249], 1.0
	v_pk_fma_f32 v[84:85], v[128:129], v[78:79], v[84:85] op_sel_hi:[1,0,1]
	v_pk_fma_f32 v[86:87], v[130:131], v[78:79], v[86:87] op_sel_hi:[1,0,1]
	v_pk_fma_f32 v[88:89], v[132:133], v[78:79], v[88:89] op_sel_hi:[1,0,1]
	v_pk_fma_f32 v[90:91], v[134:135], v[78:79], v[90:91] op_sel_hi:[1,0,1]
	v_pk_fma_f32 v[92:93], v[136:137], v[78:79], v[92:93] op_sel_hi:[1,0,1]
	v_pk_fma_f32 v[94:95], v[138:139], v[78:79], v[94:95] op_sel_hi:[1,0,1]
	v_pk_fma_f32 v[96:97], v[140:141], v[78:79], v[96:97] op_sel_hi:[1,0,1]
	v_pk_fma_f32 v[98:99], v[142:143], v[78:79], v[98:99] op_sel_hi:[1,0,1]
	v_pk_fma_f32 v[100:101], v[144:145], v[78:79], v[100:101] op_sel_hi:[1,0,1]
	v_pk_fma_f32 v[102:103], v[146:147], v[78:79], v[102:103] op_sel_hi:[1,0,1]
	v_pk_fma_f32 v[104:105], v[148:149], v[78:79], v[104:105] op_sel_hi:[1,0,1]
	v_pk_fma_f32 v[106:107], v[150:151], v[78:79], v[106:107] op_sel_hi:[1,0,1]
	v_pk_fma_f32 v[108:109], v[152:153], v[78:79], v[108:109] op_sel_hi:[1,0,1]
	v_pk_fma_f32 v[110:111], v[154:155], v[78:79], v[110:111] op_sel_hi:[1,0,1]
	v_pk_fma_f32 v[112:113], v[156:157], v[78:79], v[112:113] op_sel_hi:[1,0,1]
	v_pk_fma_f32 v[114:115], v[158:159], v[78:79], v[114:115] op_sel_hi:[1,0,1]
	v_lshl_add_u32 v7, v30, 7, v1
	v_lshl_add_u32 v8, v30, 6, v10
	global_load_dwordx4 v[244:247], v7, s[26:27] sc1
	global_load_dwordx2 v[248:249], v8, s[26:27] sc1
	s_waitcnt vmcnt(41)
	v_cvt_scalef32_pk32_f32_fp6 v[128:159], v[250:255], 1.0
	v_pk_fma_f32 v[84:85], v[128:129], v[78:79], v[84:85] op_sel:[0,1,0] op_sel_hi:[1,1,1]
	v_pk_fma_f32 v[86:87], v[130:131], v[78:79], v[86:87] op_sel:[0,1,0] op_sel_hi:[1,1,1]
	v_pk_fma_f32 v[88:89], v[132:133], v[78:79], v[88:89] op_sel:[0,1,0] op_sel_hi:[1,1,1]
	v_pk_fma_f32 v[90:91], v[134:135], v[78:79], v[90:91] op_sel:[0,1,0] op_sel_hi:[1,1,1]
	v_pk_fma_f32 v[92:93], v[136:137], v[78:79], v[92:93] op_sel:[0,1,0] op_sel_hi:[1,1,1]
	v_pk_fma_f32 v[94:95], v[138:139], v[78:79], v[94:95] op_sel:[0,1,0] op_sel_hi:[1,1,1]
	v_pk_fma_f32 v[96:97], v[140:141], v[78:79], v[96:97] op_sel:[0,1,0] op_sel_hi:[1,1,1]
	v_pk_fma_f32 v[98:99], v[142:143], v[78:79], v[98:99] op_sel:[0,1,0] op_sel_hi:[1,1,1]
	v_pk_fma_f32 v[100:101], v[144:145], v[78:79], v[100:101] op_sel:[0,1,0] op_sel_hi:[1,1,1]
	v_pk_fma_f32 v[102:103], v[146:147], v[78:79], v[102:103] op_sel:[0,1,0] op_sel_hi:[1,1,1]
	v_pk_fma_f32 v[104:105], v[148:149], v[78:79], v[104:105] op_sel:[0,1,0] op_sel_hi:[1,1,1]
	v_pk_fma_f32 v[106:107], v[150:151], v[78:79], v[106:107] op_sel:[0,1,0] op_sel_hi:[1,1,1]
	v_pk_fma_f32 v[108:109], v[152:153], v[78:79], v[108:109] op_sel:[0,1,0] op_sel_hi:[1,1,1]
	v_pk_fma_f32 v[110:111], v[154:155], v[78:79], v[110:111] op_sel:[0,1,0] op_sel_hi:[1,1,1]
	v_pk_fma_f32 v[112:113], v[156:157], v[78:79], v[112:113] op_sel:[0,1,0] op_sel_hi:[1,1,1]
	v_pk_fma_f32 v[114:115], v[158:159], v[78:79], v[114:115] op_sel:[0,1,0] op_sel_hi:[1,1,1]
	v_lshl_add_u32 v7, v31, 7, v1
	v_lshl_add_u32 v8, v31, 6, v10
	global_load_dwordx4 v[250:253], v7, s[26:27] sc1
	global_load_dwordx2 v[254:255], v8, s[26:27] sc1
	ds_write_b128 v4, v[84:87] offset:0
	ds_write_b128 v4, v[88:91] offset:16
	ds_write_b128 v4, v[92:95] offset:32
	ds_write_b128 v4, v[96:99] offset:48
	ds_write_b128 v4, v[100:103] offset:64
	ds_write_b128 v4, v[104:107] offset:80
	ds_write_b128 v4, v[108:111] offset:96
	ds_write_b128 v4, v[112:115] offset:112
	ds_read_b128 v[128:131], v5 offset:0
	ds_read_b128 v[132:135], v5 offset:1152
	ds_read_b128 v[136:139], v5 offset:2304
	ds_read_b128 v[140:143], v5 offset:3456
	ds_read_b128 v[144:147], v5 offset:4608
	ds_read_b128 v[148:151], v5 offset:5760
	ds_read_b128 v[152:155], v5 offset:6912
	ds_read_b128 v[156:159], v5 offset:8064
	s_waitcnt lgkmcnt(0)
	v_add_f32_e32 v128, v128, v132
	v_add_f32_e32 v136, v136, v140
	v_add_f32_e32 v144, v144, v148
	v_add_f32_e32 v152, v152, v156
	v_add_f32_e32 v129, v129, v133
	v_add_f32_e32 v137, v137, v141
	v_add_f32_e32 v145, v145, v149
	v_add_f32_e32 v153, v153, v157
	v_add_f32_e32 v130, v130, v134
	v_add_f32_e32 v138, v138, v142
	v_add_f32_e32 v146, v146, v150
	v_add_f32_e32 v154, v154, v158
	v_add_f32_e32 v131, v131, v135
	v_add_f32_e32 v139, v139, v143
	v_add_f32_e32 v147, v147, v151
	v_add_f32_e32 v155, v155, v159
	v_add_f32_e32 v128, v128, v136
	v_add_f32_e32 v144, v144, v152
	v_add_f32_e32 v129, v129, v137
	v_add_f32_e32 v145, v145, v153
	v_add_f32_e32 v130, v130, v138
	v_add_f32_e32 v146, v146, v154
	v_add_f32_e32 v131, v131, v139
	v_add_f32_e32 v147, v147, v155
	v_add_f32_e32 v128, v128, v144
	v_add_f32_e32 v129, v129, v145
	v_add_f32_e32 v130, v130, v146
	v_add_f32_e32 v131, v131, v147
	s_waitcnt vmcnt(40)
	v_add_f32_e32 v116, v80, v128
	v_add_f32_e32 v117, v81, v129
	v_add_f32_e32 v118, v82, v130
	v_add_f32_e32 v119, v83, v131
	global_store_dwordx4 v6, v[116:119], s[34:35]
	v_mul_f32_e32 v9, v116, v116
	v_fmac_f32_e32 v9, v117, v117
	v_fmac_f32_e32 v9, v118, v118
	v_fmac_f32_e32 v9, v119, v119
	s_nop 1
	v_add_f32_dpp v9, v9, v9 quad_perm:[1,0,3,2] row_mask:0xf bank_mask:0xf
	s_nop 1
	v_add_f32_dpp v9, v9, v9 quad_perm:[2,3,0,1] row_mask:0xf bank_mask:0xf
	s_nop 1
	v_add_f32_dpp v9, v9, v9 row_half_mirror row_mask:0xf bank_mask:0xf
	s_nop 1
	v_add_f32_dpp v9, v9, v9 row_mirror row_mask:0xf bank_mask:0xf
	s_nop 1
	v_add_f32_dpp v9, v9, v9 row_bcast:15 row_mask:0xa bank_mask:0xf
	s_nop 1
	v_add_f32_dpp v9, v9, v9 row_bcast:31 row_mask:0xc bank_mask:0xf
	s_nop 1
	s_mov_b64 exec, s[36:37]
	s_nop 1
	global_store_dword v3, v9, s[38:39]
	s_mov_b64 exec, -1
	s_add_u32 s28, s28, 1
	s_cmp_lt_u32 s28, 128
	s_cbranch_scc1 .Lpb_tokloop
	s_waitcnt vmcnt(0)
	s_waitcnt vmcnt(0) lgkmcnt(0)
	s_barrier
	s_cmp_lg_u32 s21, 0
	s_cbranch_scc1 .Lpb_skip_b
	s_mov_b64 exec, 1
	v_mov_b32_e32 v10, 0x12000
	ds_read_b32 v12, v10
	ds_read_b32 v13, v10 offset:4
	s_getreg_b32 s44, hwreg(HW_REG_XCC_ID, 0, 4)
	s_and_b32 s44, s44, 15
	s_lshl_b32 s44, s44, 2
	s_waitcnt lgkmcnt(0)
	v_readfirstlane_b32 s45, v12
	v_readfirstlane_b32 s46, v13
	v_mov_b32_e32 v10, s44
	v_mov_b32_e32 v11, 1
	global_atomic_add v12, v10, v11, s[14:15] offset:256 sc0
	s_waitcnt vmcnt(0)
	v_readfirstlane_b32 s47, v12
	s_nop 3
	s_add_u32 s47, s47, 1
	s_cmp_lg_u32 s47, s45
	v_mov_b32_e32 v10, 0
	s_cbranch_scc1 .Lpb_notlast_b
	buffer_wbl2 sc1
	s_waitcnt vmcnt(0)
	global_atomic_add v10, v11, s[14:15] offset:320
	s_waitcnt vmcnt(0)
